# s_setprio flips removed from all GEMM K-loops (SP2 structure: raising the MFMA wave starves the loading partner, which is the interval pole)
# speedup vs baseline: 1.0193x; 1.0033x over previous
.Lpeel_108:
	s_add_u32 s0, s40, 0xfffc0080
	s_addc_u32 s1, s41, -1
	s_add_i32 s68, 0, 0x10000
	s_cmp_eq_u32 s47, 12
	s_cselect_b32 s5, s6, s1
	s_cselect_b32 s4, s7, s0
	s_cselect_b32 s1, s37, s46
	s_cselect_b32 s0, s42, s43
	s_add_i32 s70, 0, 0x14000
	v_add_u32_e32 v60, s68, v250
	v_add_u32_e32 v124, s70, v250
	ds_read_b128 v[40:43], v60
	ds_read_b128 v[44:47], v60 offset:1024
	ds_read_b128 v[56:59], v60 offset:2048
	ds_read_b128 v[60:63], v60 offset:3072
	ds_read_b128 v[104:107], v124
	ds_read_b128 v[112:115], v124 offset:1024
	ds_read_b128 v[120:123], v124 offset:2048
	ds_read_b128 v[124:127], v124 offset:3072
	s_add_i32 m0, s20, 0xc000
	ds_read_b128 v[152:155], v251
	ds_read_b128 v[156:159], v251 offset:1024
	ds_read_b128 v[168:171], v251 offset:2048
	ds_read_b128 v[172:175], v251 offset:3072
	ds_read_b128 v[200:203], v251 offset:4096
	ds_read_b128 v[204:207], v251 offset:5120
	ds_read_b128 v[208:211], v251 offset:6144
	ds_read_b128 v[212:215], v251 offset:7168
	global_load_lds_dwordx4 v196, s[40:41]
	s_add_i32 m0, s20, 0xe000
	s_nop 0
	global_load_lds_dwordx4 v198, s[40:41]
	s_waitcnt vmcnt(8)
	s_waitcnt lgkmcnt(0)
	s_barrier
	s_waitcnt lgkmcnt(0)
	v_mfma_f32_16x16x32_bf16 v[164:167], v[40:43], v[152:155], 0
	v_mfma_f32_16x16x32_bf16 v[160:163], v[56:59], v[152:155], 0
	v_mfma_f32_16x16x32_bf16 v[116:119], v[40:43], v[168:171], 0
	v_mfma_f32_16x16x32_bf16 v[108:111], v[56:59], v[168:171], 0
	v_mfma_f32_16x16x32_bf16 v[140:143], v[40:43], v[200:203], 0
	v_mfma_f32_16x16x32_bf16 v[136:139], v[56:59], v[200:203], 0
	v_mfma_f32_16x16x32_bf16 v[92:95], v[40:43], v[208:211], 0
	v_mfma_f32_16x16x32_bf16 v[88:91], v[56:59], v[208:211], 0
	v_mfma_f32_16x16x32_bf16 v[164:167], v[44:47], v[156:159], v[164:167]
	v_mfma_f32_16x16x32_bf16 v[160:163], v[60:63], v[156:159], v[160:163]
	v_mfma_f32_16x16x32_bf16 v[116:119], v[44:47], v[172:175], v[116:119]
	v_mfma_f32_16x16x32_bf16 v[108:111], v[60:63], v[172:175], v[108:111]
	v_mfma_f32_16x16x32_bf16 v[140:143], v[44:47], v[204:207], v[140:143]
	v_mfma_f32_16x16x32_bf16 v[136:139], v[60:63], v[204:207], v[136:139]
	v_mfma_f32_16x16x32_bf16 v[92:95], v[44:47], v[212:215], v[92:95]
	v_mfma_f32_16x16x32_bf16 v[88:91], v[60:63], v[212:215], v[88:91]
	v_mfma_f32_16x16x32_bf16 v[148:151], v[104:107], v[152:155], 0
	v_mfma_f32_16x16x32_bf16 v[144:147], v[120:123], v[152:155], 0
	v_mfma_f32_16x16x32_bf16 v[100:103], v[104:107], v[168:171], 0
	v_mfma_f32_16x16x32_bf16 v[96:99], v[120:123], v[168:171], 0
	v_mfma_f32_16x16x32_bf16 v[132:135], v[104:107], v[200:203], 0
	v_mfma_f32_16x16x32_bf16 v[128:131], v[120:123], v[200:203], 0
	v_mfma_f32_16x16x32_bf16 v[84:87], v[104:107], v[208:211], 0
	v_mfma_f32_16x16x32_bf16 v[80:83], v[120:123], v[208:211], 0
	v_mfma_f32_16x16x32_bf16 v[148:151], v[112:115], v[156:159], v[148:151]
	v_mfma_f32_16x16x32_bf16 v[144:147], v[124:127], v[156:159], v[144:147]
	v_mfma_f32_16x16x32_bf16 v[100:103], v[112:115], v[172:175], v[100:103]
	v_mfma_f32_16x16x32_bf16 v[96:99], v[124:127], v[172:175], v[96:99]
	v_mfma_f32_16x16x32_bf16 v[132:135], v[112:115], v[204:207], v[132:135]
	v_mfma_f32_16x16x32_bf16 v[128:131], v[124:127], v[204:207], v[128:131]
	v_mfma_f32_16x16x32_bf16 v[84:87], v[112:115], v[212:215], v[84:87]
	v_mfma_f32_16x16x32_bf16 v[80:83], v[124:127], v[212:215], v[80:83]
	s_barrier
	s_add_i32 s68, s68, s27
	v_lshl_add_u64 v[178:179], s[0:1], 0, v[176:177]
	s_mov_b32 m0, s68
	ds_read_b128 v[152:155], v251 offset:16384
	ds_read_b128 v[156:159], v251 offset:17408
	ds_read_b128 v[168:171], v251 offset:18432
	ds_read_b128 v[172:175], v251 offset:19456
	ds_read_b128 v[200:203], v251 offset:20480
	ds_read_b128 v[204:207], v251 offset:21504
	ds_read_b128 v[208:211], v251 offset:22528
	ds_read_b128 v[212:215], v251 offset:23552
	global_load_lds_dwordx4 v176, s[0:1]
	s_add_i32 m0, s68, 0x2000
	s_add_u32 s68, s0, 0x40000
	v_lshl_add_u64 v[180:181], s[0:1], 0, v[190:191]
	s_addc_u32 s69, s1, 0
	s_add_i32 s70, s70, s27
	global_load_lds_dwordx4 v190, s[0:1]
	s_mov_b32 m0, s70
	v_lshl_add_u64 v[188:189], s[4:5], 0, v[192:193]
	global_load_lds_dwordx4 v176, s[68:69]
	s_add_i32 m0, s70, 0x2000
	s_nop 0
	global_load_lds_dwordx4 v190, s[68:69]
	v_lshl_add_u64 v[186:187], s[4:5], 0, v[194:195]
	s_mov_b32 m0, s20
	s_nop 0
	global_load_lds_dwordx4 v194, s[4:5]
	s_mov_b32 m0, s12
	s_nop 0
	global_load_lds_dwordx4 v192, s[4:5]
	s_waitcnt vmcnt(8)
	s_waitcnt lgkmcnt(0)
	s_barrier
	s_waitcnt lgkmcnt(0)
	v_mfma_f32_16x16x32_bf16 v[76:79], v[40:43], v[152:155], 0
	v_mfma_f32_16x16x32_bf16 v[72:75], v[56:59], v[152:155], 0
	v_mfma_f32_16x16x32_bf16 v[52:55], v[40:43], v[168:171], 0
	v_mfma_f32_16x16x32_bf16 v[48:51], v[56:59], v[168:171], 0
	v_mfma_f32_16x16x32_bf16 v[28:31], v[40:43], v[200:203], 0
	v_mfma_f32_16x16x32_bf16 v[24:27], v[56:59], v[200:203], 0
	v_mfma_f32_16x16x32_bf16 v[12:15], v[40:43], v[208:211], 0
	v_mfma_f32_16x16x32_bf16 v[8:11], v[56:59], v[208:211], 0
	v_mfma_f32_16x16x32_bf16 v[76:79], v[44:47], v[156:159], v[76:79]
	v_mfma_f32_16x16x32_bf16 v[72:75], v[60:63], v[156:159], v[72:75]
	v_mfma_f32_16x16x32_bf16 v[52:55], v[44:47], v[172:175], v[52:55]
	v_mfma_f32_16x16x32_bf16 v[48:51], v[60:63], v[172:175], v[48:51]
	v_mfma_f32_16x16x32_bf16 v[28:31], v[44:47], v[204:207], v[28:31]
	v_mfma_f32_16x16x32_bf16 v[24:27], v[60:63], v[204:207], v[24:27]
	v_mfma_f32_16x16x32_bf16 v[12:15], v[44:47], v[212:215], v[12:15]
	v_mfma_f32_16x16x32_bf16 v[8:11], v[60:63], v[212:215], v[8:11]
	v_mfma_f32_16x16x32_bf16 v[36:39], v[104:107], v[168:171], 0
	v_mfma_f32_16x16x32_bf16 v[32:35], v[120:123], v[168:171], 0
	v_mfma_f32_16x16x32_bf16 v[20:23], v[104:107], v[200:203], 0
	v_mfma_f32_16x16x32_bf16 v[16:19], v[120:123], v[200:203], 0
	v_mfma_f32_16x16x32_bf16 v[4:7], v[104:107], v[208:211], 0
	v_mfma_f32_16x16x32_bf16 v[0:3], v[120:123], v[208:211], 0
	v_mfma_f32_16x16x32_bf16 v[40:43], v[104:107], v[152:155], 0
	v_mfma_f32_16x16x32_bf16 v[44:47], v[120:123], v[152:155], 0
	v_mfma_f32_16x16x32_bf16 v[36:39], v[112:115], v[172:175], v[36:39]
	v_mfma_f32_16x16x32_bf16 v[32:35], v[124:127], v[172:175], v[32:35]
	v_mfma_f32_16x16x32_bf16 v[20:23], v[112:115], v[204:207], v[20:23]
	v_mfma_f32_16x16x32_bf16 v[16:19], v[124:127], v[204:207], v[16:19]
	v_mfma_f32_16x16x32_bf16 v[4:7], v[112:115], v[212:215], v[4:7]
	v_mfma_f32_16x16x32_bf16 v[0:3], v[124:127], v[212:215], v[0:3]
	v_mfma_f32_16x16x32_bf16 v[40:43], v[112:115], v[156:159], v[40:43]
	v_mfma_f32_16x16x32_bf16 v[44:47], v[124:127], v[156:159], v[44:47]
	s_barrier
	s_add_i32 s68, 0, 0x18000
	s_add_i32 s69, 0, 0x1c000
	v_add_u32_e32 v68, s68, v250
	v_add_u32_e32 v124, s69, v250
	ds_read_b128 v[56:59], v68
	ds_read_b128 v[60:63], v68 offset:1024
	ds_read_b128 v[64:67], v68 offset:2048
	ds_read_b128 v[68:71], v68 offset:3072
	ds_read_b128 v[104:107], v124
	ds_read_b128 v[112:115], v124 offset:1024
	ds_read_b128 v[120:123], v124 offset:2048
	ds_read_b128 v[124:127], v124 offset:3072
	s_add_u32 s4, s4, 0x40000
	s_addc_u32 s5, s5, 0
	s_mov_b32 m0, s60
	ds_read_b128 v[152:155], v251 offset:32768
	ds_read_b128 v[156:159], v251 offset:33792
	ds_read_b128 v[168:171], v251 offset:34816
	ds_read_b128 v[172:175], v251 offset:35840
	ds_read_b128 v[200:203], v251 offset:36864
	ds_read_b128 v[204:207], v251 offset:37888
	ds_read_b128 v[208:211], v251 offset:38912
	ds_read_b128 v[212:215], v251 offset:39936
	global_load_lds_dwordx4 v194, s[4:5]
	s_mov_b32 m0, s61
	s_nop 0
	global_load_lds_dwordx4 v192, s[4:5]
	s_waitcnt vmcnt(8)
	s_waitcnt lgkmcnt(0)
	s_barrier
	s_waitcnt lgkmcnt(0)
	v_mfma_f32_16x16x32_bf16 v[164:167], v[56:59], v[152:155], v[164:167]
	v_mfma_f32_16x16x32_bf16 v[160:163], v[64:67], v[152:155], v[160:163]
	v_mfma_f32_16x16x32_bf16 v[116:119], v[56:59], v[168:171], v[116:119]
	v_mfma_f32_16x16x32_bf16 v[108:111], v[64:67], v[168:171], v[108:111]
	v_mfma_f32_16x16x32_bf16 v[140:143], v[56:59], v[200:203], v[140:143]
	v_mfma_f32_16x16x32_bf16 v[136:139], v[64:67], v[200:203], v[136:139]
	v_mfma_f32_16x16x32_bf16 v[92:95], v[56:59], v[208:211], v[92:95]
	v_mfma_f32_16x16x32_bf16 v[88:91], v[64:67], v[208:211], v[88:91]
	v_mfma_f32_16x16x32_bf16 v[164:167], v[60:63], v[156:159], v[164:167]
	v_mfma_f32_16x16x32_bf16 v[160:163], v[68:71], v[156:159], v[160:163]
	v_mfma_f32_16x16x32_bf16 v[116:119], v[60:63], v[172:175], v[116:119]
	v_mfma_f32_16x16x32_bf16 v[108:111], v[68:71], v[172:175], v[108:111]
	v_mfma_f32_16x16x32_bf16 v[140:143], v[60:63], v[204:207], v[140:143]
	v_mfma_f32_16x16x32_bf16 v[136:139], v[68:71], v[204:207], v[136:139]
	v_mfma_f32_16x16x32_bf16 v[92:95], v[60:63], v[212:215], v[92:95]
	v_mfma_f32_16x16x32_bf16 v[88:91], v[68:71], v[212:215], v[88:91]
	v_mfma_f32_16x16x32_bf16 v[148:151], v[104:107], v[152:155], v[148:151]
	v_mfma_f32_16x16x32_bf16 v[144:147], v[120:123], v[152:155], v[144:147]
	v_mfma_f32_16x16x32_bf16 v[100:103], v[104:107], v[168:171], v[100:103]
	v_mfma_f32_16x16x32_bf16 v[96:99], v[120:123], v[168:171], v[96:99]
	v_mfma_f32_16x16x32_bf16 v[132:135], v[104:107], v[200:203], v[132:135]
	v_mfma_f32_16x16x32_bf16 v[128:131], v[120:123], v[200:203], v[128:131]
	v_mfma_f32_16x16x32_bf16 v[84:87], v[104:107], v[208:211], v[84:87]
	v_mfma_f32_16x16x32_bf16 v[80:83], v[120:123], v[208:211], v[80:83]
	v_mfma_f32_16x16x32_bf16 v[148:151], v[112:115], v[156:159], v[148:151]
	v_mfma_f32_16x16x32_bf16 v[144:147], v[124:127], v[156:159], v[144:147]
	v_mfma_f32_16x16x32_bf16 v[100:103], v[112:115], v[172:175], v[100:103]
	v_mfma_f32_16x16x32_bf16 v[96:99], v[124:127], v[172:175], v[96:99]
	v_mfma_f32_16x16x32_bf16 v[132:135], v[112:115], v[204:207], v[132:135]
	v_mfma_f32_16x16x32_bf16 v[128:131], v[124:127], v[204:207], v[128:131]
	v_mfma_f32_16x16x32_bf16 v[84:87], v[112:115], v[212:215], v[84:87]
	v_mfma_f32_16x16x32_bf16 v[80:83], v[124:127], v[212:215], v[80:83]
	s_barrier
	s_add_i32 s4, s68, s27
	v_lshl_add_u64 v[178:179], v[178:179], 0, s[82:83]
	s_mov_b32 m0, s4
	ds_read_b128 v[152:155], v251 offset:49152
	ds_read_b128 v[156:159], v251 offset:50176
	ds_read_b128 v[168:171], v251 offset:51200
	ds_read_b128 v[172:175], v251 offset:52224
	ds_read_b128 v[200:203], v251 offset:53248
	ds_read_b128 v[204:207], v251 offset:54272
	ds_read_b128 v[208:211], v251 offset:55296
	ds_read_b128 v[212:215], v251 offset:56320
	global_load_lds_dwordx4 v[178:179], off
	s_add_i32 m0, s4, 0x2000
	s_add_u32 s0, s0, 0x40080
	v_lshl_add_u64 v[178:179], v[180:181], 0, s[82:83]
	s_addc_u32 s1, s1, 0
	s_add_i32 s4, s69, s27
	global_load_lds_dwordx4 v[178:179], off
	s_mov_b32 m0, s4
	s_nop 0
	global_load_lds_dwordx4 v176, s[0:1]
	s_add_i32 m0, s4, 0x2000
	s_nop 0
	global_load_lds_dwordx4 v190, s[0:1]
	v_lshl_add_u64 v[178:179], v[186:187], 0, s[82:83]
	s_mov_b32 m0, s64
	s_nop 0
	global_load_lds_dwordx4 v[178:179], off
	v_lshl_add_u64 v[178:179], v[188:189], 0, s[82:83]
	s_mov_b32 m0, s65
	s_nop 0
	global_load_lds_dwordx4 v[178:179], off
	s_waitcnt vmcnt(8)
	s_waitcnt lgkmcnt(0)
	s_barrier
	s_waitcnt lgkmcnt(0)
	v_mfma_f32_16x16x32_bf16 v[76:79], v[56:59], v[152:155], v[76:79]
	v_mfma_f32_16x16x32_bf16 v[72:75], v[64:67], v[152:155], v[72:75]
	v_mfma_f32_16x16x32_bf16 v[52:55], v[56:59], v[168:171], v[52:55]
	v_mfma_f32_16x16x32_bf16 v[48:51], v[64:67], v[168:171], v[48:51]
	v_mfma_f32_16x16x32_bf16 v[28:31], v[56:59], v[200:203], v[28:31]
	v_mfma_f32_16x16x32_bf16 v[24:27], v[64:67], v[200:203], v[24:27]
	v_mfma_f32_16x16x32_bf16 v[12:15], v[56:59], v[208:211], v[12:15]
	v_mfma_f32_16x16x32_bf16 v[8:11], v[64:67], v[208:211], v[8:11]
	v_mfma_f32_16x16x32_bf16 v[76:79], v[60:63], v[156:159], v[76:79]
	v_mfma_f32_16x16x32_bf16 v[72:75], v[68:71], v[156:159], v[72:75]
	v_mfma_f32_16x16x32_bf16 v[52:55], v[60:63], v[172:175], v[52:55]
	v_mfma_f32_16x16x32_bf16 v[48:51], v[68:71], v[172:175], v[48:51]
	v_mfma_f32_16x16x32_bf16 v[28:31], v[60:63], v[204:207], v[28:31]
	v_mfma_f32_16x16x32_bf16 v[24:27], v[68:71], v[204:207], v[24:27]
	v_mfma_f32_16x16x32_bf16 v[12:15], v[60:63], v[212:215], v[12:15]
	v_mfma_f32_16x16x32_bf16 v[8:11], v[68:71], v[212:215], v[8:11]
	v_mfma_f32_16x16x32_bf16 v[40:43], v[104:107], v[152:155], v[40:43]
	v_mfma_f32_16x16x32_bf16 v[68:71], v[112:115], v[156:159], v[40:43]
	v_mfma_f32_16x16x32_bf16 v[40:43], v[120:123], v[152:155], v[44:47]
	v_mfma_f32_16x16x32_bf16 v[36:39], v[104:107], v[168:171], v[36:39]
	v_mfma_f32_16x16x32_bf16 v[32:35], v[120:123], v[168:171], v[32:35]
	v_mfma_f32_16x16x32_bf16 v[20:23], v[104:107], v[200:203], v[20:23]
	v_mfma_f32_16x16x32_bf16 v[16:19], v[120:123], v[200:203], v[16:19]
	v_mfma_f32_16x16x32_bf16 v[4:7], v[104:107], v[208:211], v[4:7]
	v_mfma_f32_16x16x32_bf16 v[0:3], v[120:123], v[208:211], v[0:3]
	v_mfma_f32_16x16x32_bf16 v[64:67], v[124:127], v[156:159], v[40:43]
	v_mfma_f32_16x16x32_bf16 v[36:39], v[112:115], v[172:175], v[36:39]
	v_mfma_f32_16x16x32_bf16 v[32:35], v[124:127], v[172:175], v[32:35]
	v_mfma_f32_16x16x32_bf16 v[20:23], v[112:115], v[204:207], v[20:23]
	v_mfma_f32_16x16x32_bf16 v[16:19], v[124:127], v[204:207], v[16:19]
	v_mfma_f32_16x16x32_bf16 v[4:7], v[112:115], v[212:215], v[4:7]
	v_mfma_f32_16x16x32_bf16 v[0:3], v[124:127], v[212:215], v[0:3]
	s_barrier
	s_add_i32 s47, s47, 2
	s_add_u32 s40, s40, 0x100
	s_addc_u32 s41, s41, 0
	s_add_u32 s43, s43, 0x100
	s_addc_u32 s46, s46, 0
	s_cmp_gt_u32 s47, 13
.LBB0_108:
	s_add_u32 s0, s40, 0xfffc0080
	s_addc_u32 s1, s41, -1
	s_add_i32 s68, 0, 0x10000
	s_cmp_eq_u32 s47, 12
	s_cselect_b32 s5, s6, s1
	s_cselect_b32 s4, s7, s0
	s_cselect_b32 s1, s37, s46
	s_cselect_b32 s0, s42, s43
	s_add_i32 s70, 0, 0x14000
	v_add_u32_e32 v60, s68, v250
	v_add_u32_e32 v124, s70, v250
	ds_read_b128 v[40:43], v60
	ds_read_b128 v[44:47], v60 offset:1024
	ds_read_b128 v[56:59], v60 offset:2048
	ds_read_b128 v[60:63], v60 offset:3072
	ds_read_b128 v[104:107], v124
	ds_read_b128 v[112:115], v124 offset:1024
	ds_read_b128 v[120:123], v124 offset:2048
	ds_read_b128 v[124:127], v124 offset:3072
	s_add_i32 m0, s20, 0xc000
	ds_read_b128 v[152:155], v251
	ds_read_b128 v[156:159], v251 offset:1024
	ds_read_b128 v[168:171], v251 offset:2048
	ds_read_b128 v[172:175], v251 offset:3072
	ds_read_b128 v[200:203], v251 offset:4096
	ds_read_b128 v[204:207], v251 offset:5120
	ds_read_b128 v[208:211], v251 offset:6144
	ds_read_b128 v[212:215], v251 offset:7168
	global_load_lds_dwordx4 v196, s[40:41]
	s_add_i32 m0, s20, 0xe000
	s_nop 0
	global_load_lds_dwordx4 v198, s[40:41]
	s_waitcnt vmcnt(8)
	s_waitcnt lgkmcnt(0)
	s_barrier
	s_waitcnt lgkmcnt(0)
	v_mfma_f32_16x16x32_bf16 v[164:167], v[40:43], v[152:155], v[164:167]
	v_mfma_f32_16x16x32_bf16 v[160:163], v[56:59], v[152:155], v[160:163]
	v_mfma_f32_16x16x32_bf16 v[116:119], v[40:43], v[168:171], v[116:119]
	v_mfma_f32_16x16x32_bf16 v[108:111], v[56:59], v[168:171], v[108:111]
	v_mfma_f32_16x16x32_bf16 v[140:143], v[40:43], v[200:203], v[140:143]
	v_mfma_f32_16x16x32_bf16 v[136:139], v[56:59], v[200:203], v[136:139]
	v_mfma_f32_16x16x32_bf16 v[92:95], v[40:43], v[208:211], v[92:95]
	v_mfma_f32_16x16x32_bf16 v[88:91], v[56:59], v[208:211], v[88:91]
	v_mfma_f32_16x16x32_bf16 v[164:167], v[44:47], v[156:159], v[164:167]
	v_mfma_f32_16x16x32_bf16 v[160:163], v[60:63], v[156:159], v[160:163]
	v_mfma_f32_16x16x32_bf16 v[116:119], v[44:47], v[172:175], v[116:119]
	v_mfma_f32_16x16x32_bf16 v[108:111], v[60:63], v[172:175], v[108:111]
	v_mfma_f32_16x16x32_bf16 v[140:143], v[44:47], v[204:207], v[140:143]
	v_mfma_f32_16x16x32_bf16 v[136:139], v[60:63], v[204:207], v[136:139]
	v_mfma_f32_16x16x32_bf16 v[92:95], v[44:47], v[212:215], v[92:95]
	v_mfma_f32_16x16x32_bf16 v[88:91], v[60:63], v[212:215], v[88:91]
	v_mfma_f32_16x16x32_bf16 v[148:151], v[104:107], v[152:155], v[148:151]
	v_mfma_f32_16x16x32_bf16 v[144:147], v[120:123], v[152:155], v[144:147]
	v_mfma_f32_16x16x32_bf16 v[100:103], v[104:107], v[168:171], v[100:103]
	v_mfma_f32_16x16x32_bf16 v[96:99], v[120:123], v[168:171], v[96:99]
	v_mfma_f32_16x16x32_bf16 v[132:135], v[104:107], v[200:203], v[132:135]
	v_mfma_f32_16x16x32_bf16 v[128:131], v[120:123], v[200:203], v[128:131]
	v_mfma_f32_16x16x32_bf16 v[84:87], v[104:107], v[208:211], v[84:87]
	v_mfma_f32_16x16x32_bf16 v[80:83], v[120:123], v[208:211], v[80:83]
	v_mfma_f32_16x16x32_bf16 v[148:151], v[112:115], v[156:159], v[148:151]
	v_mfma_f32_16x16x32_bf16 v[144:147], v[124:127], v[156:159], v[144:147]
	v_mfma_f32_16x16x32_bf16 v[100:103], v[112:115], v[172:175], v[100:103]
	v_mfma_f32_16x16x32_bf16 v[96:99], v[124:127], v[172:175], v[96:99]
	v_mfma_f32_16x16x32_bf16 v[132:135], v[112:115], v[204:207], v[132:135]
	v_mfma_f32_16x16x32_bf16 v[128:131], v[124:127], v[204:207], v[128:131]
	v_mfma_f32_16x16x32_bf16 v[84:87], v[112:115], v[212:215], v[84:87]
	v_mfma_f32_16x16x32_bf16 v[80:83], v[124:127], v[212:215], v[80:83]
	s_barrier
	s_add_i32 s68, s68, s27
	v_lshl_add_u64 v[178:179], s[0:1], 0, v[176:177]
	s_mov_b32 m0, s68
	ds_read_b128 v[152:155], v251 offset:16384
	ds_read_b128 v[156:159], v251 offset:17408
	ds_read_b128 v[168:171], v251 offset:18432
	ds_read_b128 v[172:175], v251 offset:19456
	ds_read_b128 v[200:203], v251 offset:20480
	ds_read_b128 v[204:207], v251 offset:21504
	ds_read_b128 v[208:211], v251 offset:22528
	ds_read_b128 v[212:215], v251 offset:23552
	global_load_lds_dwordx4 v176, s[0:1]
	s_add_i32 m0, s68, 0x2000
	s_add_u32 s68, s0, 0x40000
	v_lshl_add_u64 v[180:181], s[0:1], 0, v[190:191]
	s_addc_u32 s69, s1, 0
	s_add_i32 s70, s70, s27
	global_load_lds_dwordx4 v190, s[0:1]
	s_mov_b32 m0, s70
	v_lshl_add_u64 v[188:189], s[4:5], 0, v[192:193]
	global_load_lds_dwordx4 v176, s[68:69]
	s_add_i32 m0, s70, 0x2000
	s_nop 0
	global_load_lds_dwordx4 v190, s[68:69]
	v_lshl_add_u64 v[186:187], s[4:5], 0, v[194:195]
	s_mov_b32 m0, s20
	s_nop 0
	global_load_lds_dwordx4 v194, s[4:5]
	s_mov_b32 m0, s12
	s_nop 0
	global_load_lds_dwordx4 v192, s[4:5]
	s_waitcnt vmcnt(8)
	s_waitcnt lgkmcnt(0)
	s_barrier
	s_waitcnt lgkmcnt(0)
	v_mfma_f32_16x16x32_bf16 v[76:79], v[40:43], v[152:155], v[76:79]
	v_mfma_f32_16x16x32_bf16 v[72:75], v[56:59], v[152:155], v[72:75]
	v_mfma_f32_16x16x32_bf16 v[52:55], v[40:43], v[168:171], v[52:55]
	v_mfma_f32_16x16x32_bf16 v[48:51], v[56:59], v[168:171], v[48:51]
	v_mfma_f32_16x16x32_bf16 v[28:31], v[40:43], v[200:203], v[28:31]
	v_mfma_f32_16x16x32_bf16 v[24:27], v[56:59], v[200:203], v[24:27]
	v_mfma_f32_16x16x32_bf16 v[12:15], v[40:43], v[208:211], v[12:15]
	v_mfma_f32_16x16x32_bf16 v[8:11], v[56:59], v[208:211], v[8:11]
	v_mfma_f32_16x16x32_bf16 v[76:79], v[44:47], v[156:159], v[76:79]
	v_mfma_f32_16x16x32_bf16 v[72:75], v[60:63], v[156:159], v[72:75]
	v_mfma_f32_16x16x32_bf16 v[52:55], v[44:47], v[172:175], v[52:55]
	v_mfma_f32_16x16x32_bf16 v[48:51], v[60:63], v[172:175], v[48:51]
	v_mfma_f32_16x16x32_bf16 v[28:31], v[44:47], v[204:207], v[28:31]
	v_mfma_f32_16x16x32_bf16 v[24:27], v[60:63], v[204:207], v[24:27]
	v_mfma_f32_16x16x32_bf16 v[12:15], v[44:47], v[212:215], v[12:15]
	v_mfma_f32_16x16x32_bf16 v[8:11], v[60:63], v[212:215], v[8:11]
	v_mfma_f32_16x16x32_bf16 v[36:39], v[104:107], v[168:171], v[36:39]
	v_mfma_f32_16x16x32_bf16 v[32:35], v[120:123], v[168:171], v[32:35]
	v_mfma_f32_16x16x32_bf16 v[20:23], v[104:107], v[200:203], v[20:23]
	v_mfma_f32_16x16x32_bf16 v[16:19], v[120:123], v[200:203], v[16:19]
	v_mfma_f32_16x16x32_bf16 v[4:7], v[104:107], v[208:211], v[4:7]
	v_mfma_f32_16x16x32_bf16 v[0:3], v[120:123], v[208:211], v[0:3]
	v_mfma_f32_16x16x32_bf16 v[40:43], v[104:107], v[152:155], v[68:71]
	v_mfma_f32_16x16x32_bf16 v[44:47], v[120:123], v[152:155], v[64:67]
	v_mfma_f32_16x16x32_bf16 v[36:39], v[112:115], v[172:175], v[36:39]
	v_mfma_f32_16x16x32_bf16 v[32:35], v[124:127], v[172:175], v[32:35]
	v_mfma_f32_16x16x32_bf16 v[20:23], v[112:115], v[204:207], v[20:23]
	v_mfma_f32_16x16x32_bf16 v[16:19], v[124:127], v[204:207], v[16:19]
	v_mfma_f32_16x16x32_bf16 v[4:7], v[112:115], v[212:215], v[4:7]
	v_mfma_f32_16x16x32_bf16 v[0:3], v[124:127], v[212:215], v[0:3]
	v_mfma_f32_16x16x32_bf16 v[40:43], v[112:115], v[156:159], v[40:43]
	v_mfma_f32_16x16x32_bf16 v[44:47], v[124:127], v[156:159], v[44:47]
	s_barrier
	s_add_i32 s68, 0, 0x18000
	s_add_i32 s69, 0, 0x1c000
	v_add_u32_e32 v68, s68, v250
	v_add_u32_e32 v124, s69, v250
	ds_read_b128 v[56:59], v68
	ds_read_b128 v[60:63], v68 offset:1024
	ds_read_b128 v[64:67], v68 offset:2048
	ds_read_b128 v[68:71], v68 offset:3072
	ds_read_b128 v[104:107], v124
	ds_read_b128 v[112:115], v124 offset:1024
	ds_read_b128 v[120:123], v124 offset:2048
	ds_read_b128 v[124:127], v124 offset:3072
	s_add_u32 s4, s4, 0x40000
	s_addc_u32 s5, s5, 0
	s_mov_b32 m0, s60
	ds_read_b128 v[152:155], v251 offset:32768
	ds_read_b128 v[156:159], v251 offset:33792
	ds_read_b128 v[168:171], v251 offset:34816
	ds_read_b128 v[172:175], v251 offset:35840
	ds_read_b128 v[200:203], v251 offset:36864
	ds_read_b128 v[204:207], v251 offset:37888
	ds_read_b128 v[208:211], v251 offset:38912
	ds_read_b128 v[212:215], v251 offset:39936
	global_load_lds_dwordx4 v194, s[4:5]
	s_mov_b32 m0, s61
	s_nop 0
	global_load_lds_dwordx4 v192, s[4:5]
	s_waitcnt vmcnt(8)
	s_waitcnt lgkmcnt(0)
	s_barrier
	s_waitcnt lgkmcnt(0)
	v_mfma_f32_16x16x32_bf16 v[164:167], v[56:59], v[152:155], v[164:167]
	v_mfma_f32_16x16x32_bf16 v[160:163], v[64:67], v[152:155], v[160:163]
	v_mfma_f32_16x16x32_bf16 v[116:119], v[56:59], v[168:171], v[116:119]
	v_mfma_f32_16x16x32_bf16 v[108:111], v[64:67], v[168:171], v[108:111]
	v_mfma_f32_16x16x32_bf16 v[140:143], v[56:59], v[200:203], v[140:143]
	v_mfma_f32_16x16x32_bf16 v[136:139], v[64:67], v[200:203], v[136:139]
	v_mfma_f32_16x16x32_bf16 v[92:95], v[56:59], v[208:211], v[92:95]
	v_mfma_f32_16x16x32_bf16 v[88:91], v[64:67], v[208:211], v[88:91]
	v_mfma_f32_16x16x32_bf16 v[164:167], v[60:63], v[156:159], v[164:167]
	v_mfma_f32_16x16x32_bf16 v[160:163], v[68:71], v[156:159], v[160:163]
	v_mfma_f32_16x16x32_bf16 v[116:119], v[60:63], v[172:175], v[116:119]
	v_mfma_f32_16x16x32_bf16 v[108:111], v[68:71], v[172:175], v[108:111]
	v_mfma_f32_16x16x32_bf16 v[140:143], v[60:63], v[204:207], v[140:143]
	v_mfma_f32_16x16x32_bf16 v[136:139], v[68:71], v[204:207], v[136:139]
	v_mfma_f32_16x16x32_bf16 v[92:95], v[60:63], v[212:215], v[92:95]
	v_mfma_f32_16x16x32_bf16 v[88:91], v[68:71], v[212:215], v[88:91]
	v_mfma_f32_16x16x32_bf16 v[148:151], v[104:107], v[152:155], v[148:151]
	v_mfma_f32_16x16x32_bf16 v[144:147], v[120:123], v[152:155], v[144:147]
	v_mfma_f32_16x16x32_bf16 v[100:103], v[104:107], v[168:171], v[100:103]
	v_mfma_f32_16x16x32_bf16 v[96:99], v[120:123], v[168:171], v[96:99]
	v_mfma_f32_16x16x32_bf16 v[132:135], v[104:107], v[200:203], v[132:135]
	v_mfma_f32_16x16x32_bf16 v[128:131], v[120:123], v[200:203], v[128:131]
	v_mfma_f32_16x16x32_bf16 v[84:87], v[104:107], v[208:211], v[84:87]
	v_mfma_f32_16x16x32_bf16 v[80:83], v[120:123], v[208:211], v[80:83]
	v_mfma_f32_16x16x32_bf16 v[148:151], v[112:115], v[156:159], v[148:151]
	v_mfma_f32_16x16x32_bf16 v[144:147], v[124:127], v[156:159], v[144:147]
	v_mfma_f32_16x16x32_bf16 v[100:103], v[112:115], v[172:175], v[100:103]
	v_mfma_f32_16x16x32_bf16 v[96:99], v[124:127], v[172:175], v[96:99]
	v_mfma_f32_16x16x32_bf16 v[132:135], v[112:115], v[204:207], v[132:135]
	v_mfma_f32_16x16x32_bf16 v[128:131], v[124:127], v[204:207], v[128:131]
	v_mfma_f32_16x16x32_bf16 v[84:87], v[112:115], v[212:215], v[84:87]
	v_mfma_f32_16x16x32_bf16 v[80:83], v[124:127], v[212:215], v[80:83]
	s_barrier
	s_add_i32 s4, s68, s27
	v_lshl_add_u64 v[178:179], v[178:179], 0, s[82:83]
	s_mov_b32 m0, s4
	ds_read_b128 v[152:155], v251 offset:49152
	ds_read_b128 v[156:159], v251 offset:50176
	ds_read_b128 v[168:171], v251 offset:51200
	ds_read_b128 v[172:175], v251 offset:52224
	ds_read_b128 v[200:203], v251 offset:53248
	ds_read_b128 v[204:207], v251 offset:54272
	ds_read_b128 v[208:211], v251 offset:55296
	ds_read_b128 v[212:215], v251 offset:56320
	global_load_lds_dwordx4 v[178:179], off
	s_add_i32 m0, s4, 0x2000
	s_add_u32 s0, s0, 0x40080
	v_lshl_add_u64 v[178:179], v[180:181], 0, s[82:83]
	s_addc_u32 s1, s1, 0
	s_add_i32 s4, s69, s27
	global_load_lds_dwordx4 v[178:179], off
	s_mov_b32 m0, s4
	s_nop 0
	global_load_lds_dwordx4 v176, s[0:1]
	s_add_i32 m0, s4, 0x2000
	s_nop 0
	global_load_lds_dwordx4 v190, s[0:1]
	v_lshl_add_u64 v[178:179], v[186:187], 0, s[82:83]
	s_mov_b32 m0, s64
	s_nop 0
	global_load_lds_dwordx4 v[178:179], off
	v_lshl_add_u64 v[178:179], v[188:189], 0, s[82:83]
	s_mov_b32 m0, s65
	s_nop 0
	global_load_lds_dwordx4 v[178:179], off
	s_waitcnt vmcnt(8)
	s_waitcnt lgkmcnt(0)
	s_barrier
	s_waitcnt lgkmcnt(0)
	v_mfma_f32_16x16x32_bf16 v[76:79], v[56:59], v[152:155], v[76:79]
	v_mfma_f32_16x16x32_bf16 v[72:75], v[64:67], v[152:155], v[72:75]
	v_mfma_f32_16x16x32_bf16 v[52:55], v[56:59], v[168:171], v[52:55]
	v_mfma_f32_16x16x32_bf16 v[48:51], v[64:67], v[168:171], v[48:51]
	v_mfma_f32_16x16x32_bf16 v[28:31], v[56:59], v[200:203], v[28:31]
	v_mfma_f32_16x16x32_bf16 v[24:27], v[64:67], v[200:203], v[24:27]
	v_mfma_f32_16x16x32_bf16 v[12:15], v[56:59], v[208:211], v[12:15]
	v_mfma_f32_16x16x32_bf16 v[8:11], v[64:67], v[208:211], v[8:11]
	v_mfma_f32_16x16x32_bf16 v[76:79], v[60:63], v[156:159], v[76:79]
	v_mfma_f32_16x16x32_bf16 v[72:75], v[68:71], v[156:159], v[72:75]
	v_mfma_f32_16x16x32_bf16 v[52:55], v[60:63], v[172:175], v[52:55]
	v_mfma_f32_16x16x32_bf16 v[48:51], v[68:71], v[172:175], v[48:51]
	v_mfma_f32_16x16x32_bf16 v[28:31], v[60:63], v[204:207], v[28:31]
	v_mfma_f32_16x16x32_bf16 v[24:27], v[68:71], v[204:207], v[24:27]
	v_mfma_f32_16x16x32_bf16 v[12:15], v[60:63], v[212:215], v[12:15]
	v_mfma_f32_16x16x32_bf16 v[8:11], v[68:71], v[212:215], v[8:11]
	v_mfma_f32_16x16x32_bf16 v[40:43], v[104:107], v[152:155], v[40:43]
	v_mfma_f32_16x16x32_bf16 v[68:71], v[112:115], v[156:159], v[40:43]
	v_mfma_f32_16x16x32_bf16 v[40:43], v[120:123], v[152:155], v[44:47]
	v_mfma_f32_16x16x32_bf16 v[36:39], v[104:107], v[168:171], v[36:39]
	v_mfma_f32_16x16x32_bf16 v[32:35], v[120:123], v[168:171], v[32:35]
	v_mfma_f32_16x16x32_bf16 v[20:23], v[104:107], v[200:203], v[20:23]
	v_mfma_f32_16x16x32_bf16 v[16:19], v[120:123], v[200:203], v[16:19]
	v_mfma_f32_16x16x32_bf16 v[4:7], v[104:107], v[208:211], v[4:7]
	v_mfma_f32_16x16x32_bf16 v[0:3], v[120:123], v[208:211], v[0:3]
	v_mfma_f32_16x16x32_bf16 v[64:67], v[124:127], v[156:159], v[40:43]
	v_mfma_f32_16x16x32_bf16 v[36:39], v[112:115], v[172:175], v[36:39]
	v_mfma_f32_16x16x32_bf16 v[32:35], v[124:127], v[172:175], v[32:35]
	v_mfma_f32_16x16x32_bf16 v[20:23], v[112:115], v[204:207], v[20:23]
	v_mfma_f32_16x16x32_bf16 v[16:19], v[124:127], v[204:207], v[16:19]
	v_mfma_f32_16x16x32_bf16 v[4:7], v[112:115], v[212:215], v[4:7]
	v_mfma_f32_16x16x32_bf16 v[0:3], v[124:127], v[212:215], v[0:3]
	s_barrier
	s_add_i32 s47, s47, 2
	s_add_u32 s40, s40, 0x100
	s_addc_u32 s41, s41, 0
	s_add_u32 s43, s43, 0x100
	s_addc_u32 s46, s46, 0
	s_cmp_gt_u32 s47, 13
	s_cbranch_scc0 .LBB0_108
	s_and_b64 vcc, exec, s[30:31]
	s_cbranch_vccz .LBB0_111
	s_barrier

.LBB0_571:
	s_ashr_i32 s49, s48, 31
	s_lshl_b64 s[6:7], s[48:49], 17
	s_add_u32 s50, s12, s6
	s_addc_u32 s51, s20, s7
	s_and_b64 s[6:7], s[40:41], exec
	s_cselect_b32 s57, s51, s5
	s_cselect_b32 s56, s50, s4
	s_ashr_i32 s47, s46, 31
	s_lshl_b64 s[6:7], s[46:47], 17
	s_add_u32 s52, s27, s6
	s_addc_u32 s53, s60, s7
	s_and_b64 s[6:7], s[40:41], exec
	s_cselect_b32 s55, s53, s1
	s_cselect_b32 s54, s52, s0
	s_add_i32 s72, 0, 0x10000
	s_add_i32 s47, 0, 0x14000
	v_add_u32_e32 v182, s72, v174
	v_add_u32_e32 v183, s47, v174
	ds_read_b128 v[0:3], v182
	ds_read_b128 v[4:7], v182 offset:1024
	ds_read_b128 v[8:11], v182 offset:2048
	ds_read_b128 v[12:15], v182 offset:3072
	s_waitcnt vmcnt(0)
	ds_read_b128 v[16:19], v183
	ds_read_b128 v[20:23], v183 offset:1024
	ds_read_b128 v[24:27], v183 offset:2048
	ds_read_b128 v[28:31], v183 offset:3072
	v_mov_b64_e32 v[184:185], 0x100
	s_add_u32 s6, s4, 0x10080
	s_addc_u32 s7, s5, 0
	s_add_i32 s74, s62, 0xc000
	s_mov_b32 m0, s74
	ds_read_b128 v[32:35], v175
	ds_read_b128 v[36:39], v175 offset:1024
	ds_read_b128 v[40:43], v175 offset:2048
	ds_read_b128 v[44:47], v175 offset:3072
	ds_read_b128 v[48:51], v175 offset:4096
	ds_read_b128 v[52:55], v175 offset:5120
	ds_read_b128 v[56:59], v175 offset:6144
	ds_read_b128 v[60:63], v175 offset:7168
	global_load_lds_dwordx4 v160, s[6:7]
	v_lshl_add_u64 v[64:65], s[6:7], 0, v[158:159]
	s_add_i32 s6, s62, 0xe000
	s_mov_b32 m0, s6
	s_nop 0
	global_load_lds_dwordx4 v[64:65], off
	s_waitcnt vmcnt(8)
	s_waitcnt lgkmcnt(0)
	s_barrier
	s_waitcnt lgkmcnt(0)
	v_mfma_f32_16x16x32_bf16 v[64:67], v[0:3], v[32:35], 0
	v_mfma_f32_16x16x32_bf16 v[68:71], v[8:11], v[32:35], 0
	v_mfma_f32_16x16x32_bf16 v[72:75], v[0:3], v[40:43], 0
	v_mfma_f32_16x16x32_bf16 v[76:79], v[8:11], v[40:43], 0
	v_mfma_f32_16x16x32_bf16 v[80:83], v[0:3], v[48:51], 0
	v_mfma_f32_16x16x32_bf16 v[84:87], v[8:11], v[48:51], 0
	v_mfma_f32_16x16x32_bf16 v[88:91], v[0:3], v[56:59], 0
	v_mfma_f32_16x16x32_bf16 v[92:95], v[8:11], v[56:59], 0
	v_mfma_f32_16x16x32_bf16 v[64:67], v[4:7], v[36:39], v[64:67]
	v_mfma_f32_16x16x32_bf16 v[68:71], v[12:15], v[36:39], v[68:71]
	v_mfma_f32_16x16x32_bf16 v[72:75], v[4:7], v[44:47], v[72:75]
	v_mfma_f32_16x16x32_bf16 v[76:79], v[12:15], v[44:47], v[76:79]
	v_mfma_f32_16x16x32_bf16 v[80:83], v[4:7], v[52:55], v[80:83]
	v_mfma_f32_16x16x32_bf16 v[84:87], v[12:15], v[52:55], v[84:87]
	v_mfma_f32_16x16x32_bf16 v[88:91], v[4:7], v[60:63], v[88:91]
	v_mfma_f32_16x16x32_bf16 v[92:95], v[12:15], v[60:63], v[92:95]
	v_mfma_f32_16x16x32_bf16 v[96:99], v[16:19], v[32:35], 0
	v_mfma_f32_16x16x32_bf16 v[32:35], v[24:27], v[32:35], 0
	v_mfma_f32_16x16x32_bf16 v[96:99], v[20:23], v[36:39], v[96:99]
	v_mfma_f32_16x16x32_bf16 v[32:35], v[28:31], v[36:39], v[32:35]
	v_mfma_f32_16x16x32_bf16 v[36:39], v[16:19], v[40:43], 0
	v_mfma_f32_16x16x32_bf16 v[40:43], v[24:27], v[40:43], 0
	v_mfma_f32_16x16x32_bf16 v[36:39], v[20:23], v[44:47], v[36:39]
	v_mfma_f32_16x16x32_bf16 v[40:43], v[28:31], v[44:47], v[40:43]
	v_mfma_f32_16x16x32_bf16 v[44:47], v[16:19], v[48:51], 0
	v_mfma_f32_16x16x32_bf16 v[48:51], v[24:27], v[48:51], 0
	v_mfma_f32_16x16x32_bf16 v[44:47], v[20:23], v[52:55], v[44:47]
	v_mfma_f32_16x16x32_bf16 v[48:51], v[28:31], v[52:55], v[48:51]
	v_mfma_f32_16x16x32_bf16 v[52:55], v[16:19], v[56:59], 0
	v_mfma_f32_16x16x32_bf16 v[56:59], v[24:27], v[56:59], 0
	v_mfma_f32_16x16x32_bf16 v[52:55], v[20:23], v[60:63], v[52:55]
	v_mfma_f32_16x16x32_bf16 v[56:59], v[28:31], v[60:63], v[56:59]
	s_barrier
	s_add_i32 s72, s72, s61
	v_lshl_add_u64 v[178:179], s[0:1], 0, v[176:177]
	s_add_i32 s7, s72, 0x2000
	v_lshl_add_u64 v[128:129], v[178:179], 0, s[58:59]
	s_mov_b32 m0, s72
	v_lshl_add_u64 v[180:181], s[0:1], 0, v[156:157]
	s_add_u32 s86, s0, 0x10100
	ds_read_b128 v[60:63], v175 offset:16384
	ds_read_b128 v[100:103], v175 offset:17408
	ds_read_b128 v[104:107], v175 offset:18432
	ds_read_b128 v[108:111], v175 offset:19456
	ds_read_b128 v[112:115], v175 offset:20480
	ds_read_b128 v[116:119], v175 offset:21504
	ds_read_b128 v[120:123], v175 offset:22528
	ds_read_b128 v[124:127], v175 offset:23552
	global_load_lds_dwordx4 v[128:129], off
	v_lshl_add_u64 v[128:129], v[180:181], 0, s[58:59]
	s_mov_b32 m0, s7
	s_addc_u32 s87, s1, 0
	s_add_i32 s47, s47, s61
	global_load_lds_dwordx4 v[128:129], off
	s_mov_b32 m0, s47
	s_add_i32 s49, s47, 0x2000
	global_load_lds_dwordx4 v176, s[86:87]
	s_mov_b32 m0, s49
	v_lshl_add_u64 v[186:187], s[4:5], 0, v[160:161]
	global_load_lds_dwordx4 v156, s[86:87]
	v_lshl_add_u64 v[128:129], v[186:187], 0, s[58:59]
	s_mov_b32 m0, s62
	v_lshl_add_u64 v[188:189], s[4:5], 0, v[158:159]
	global_load_lds_dwordx4 v[128:129], off
	v_lshl_add_u64 v[128:129], v[188:189], 0, s[58:59]
	s_mov_b32 m0, s63
	s_nop 0
	global_load_lds_dwordx4 v[128:129], off
	s_waitcnt vmcnt(8)
	s_waitcnt lgkmcnt(0)
	s_barrier
	s_waitcnt lgkmcnt(0)
	v_mfma_f32_16x16x32_bf16 v[128:131], v[0:3], v[60:63], 0
	v_mfma_f32_16x16x32_bf16 v[136:139], v[0:3], v[104:107], 0
	v_mfma_f32_16x16x32_bf16 v[144:147], v[0:3], v[112:115], 0
	v_mfma_f32_16x16x32_bf16 v[0:3], v[0:3], v[120:123], 0
	v_mfma_f32_16x16x32_bf16 v[128:131], v[4:7], v[100:103], v[128:131]
	v_mfma_f32_16x16x32_bf16 v[136:139], v[4:7], v[108:111], v[136:139]
	v_mfma_f32_16x16x32_bf16 v[144:147], v[4:7], v[116:119], v[144:147]
	v_mfma_f32_16x16x32_bf16 v[148:151], v[8:11], v[112:115], 0
	v_mfma_f32_16x16x32_bf16 v[0:3], v[4:7], v[124:127], v[0:3]
	v_mfma_f32_16x16x32_bf16 v[4:7], v[8:11], v[120:123], 0
	v_mfma_f32_16x16x32_bf16 v[132:135], v[8:11], v[60:63], 0
	v_mfma_f32_16x16x32_bf16 v[140:143], v[8:11], v[104:107], 0
	v_mfma_f32_16x16x32_bf16 v[148:151], v[12:15], v[116:119], v[148:151]
	v_mfma_f32_16x16x32_bf16 v[4:7], v[12:15], v[124:127], v[4:7]
	v_mfma_f32_16x16x32_bf16 v[132:135], v[12:15], v[100:103], v[132:135]
	v_mfma_f32_16x16x32_bf16 v[140:143], v[12:15], v[108:111], v[140:143]
	v_mfma_f32_16x16x32_bf16 v[8:11], v[16:19], v[60:63], 0
	v_mfma_f32_16x16x32_bf16 v[12:15], v[24:27], v[60:63], 0
	v_mfma_f32_16x16x32_bf16 v[8:11], v[20:23], v[100:103], v[8:11]
	v_mfma_f32_16x16x32_bf16 v[12:15], v[28:31], v[100:103], v[12:15]
	v_mfma_f32_16x16x32_bf16 v[60:63], v[16:19], v[104:107], 0
	v_mfma_f32_16x16x32_bf16 v[100:103], v[24:27], v[104:107], 0
	v_mfma_f32_16x16x32_bf16 v[104:107], v[16:19], v[112:115], 0
	v_mfma_f32_16x16x32_bf16 v[16:19], v[16:19], v[120:123], 0
	v_mfma_f32_16x16x32_bf16 v[60:63], v[20:23], v[108:111], v[60:63]
	v_mfma_f32_16x16x32_bf16 v[100:103], v[28:31], v[108:111], v[100:103]
	v_mfma_f32_16x16x32_bf16 v[104:107], v[20:23], v[116:119], v[104:107]
	v_mfma_f32_16x16x32_bf16 v[108:111], v[24:27], v[112:115], 0
	v_mfma_f32_16x16x32_bf16 v[16:19], v[20:23], v[124:127], v[16:19]
	v_mfma_f32_16x16x32_bf16 v[20:23], v[24:27], v[120:123], 0
	v_mfma_f32_16x16x32_bf16 v[108:111], v[28:31], v[116:119], v[108:111]
	v_mfma_f32_16x16x32_bf16 v[20:23], v[28:31], v[124:127], v[20:23]
	s_barrier
	s_add_i32 s75, 0, 0x18000
	s_add_i32 s88, 0, 0x1c000
	v_add_u32_e32 v226, s75, v174
	v_add_u32_e32 v227, s88, v174
	ds_read_b128 v[24:27], v226
	ds_read_b128 v[28:31], v226 offset:1024
	ds_read_b128 v[112:115], v226 offset:2048
	ds_read_b128 v[116:119], v226 offset:3072
	ds_read_b128 v[120:123], v227
	ds_read_b128 v[124:127], v227 offset:1024
	ds_read_b128 v[152:155], v227 offset:2048
	ds_read_b128 v[162:165], v227 offset:3072
	s_add_u32 s86, s4, 0x10100
	s_addc_u32 s87, s5, 0
	s_mov_b32 m0, s64
	ds_read_b128 v[166:169], v175 offset:32768
	ds_read_b128 v[170:173], v175 offset:33792
	ds_read_b128 v[190:193], v175 offset:34816
	ds_read_b128 v[194:197], v175 offset:35840
	ds_read_b128 v[198:201], v175 offset:36864
	ds_read_b128 v[202:205], v175 offset:37888
	ds_read_b128 v[206:209], v175 offset:38912
	ds_read_b128 v[210:213], v175 offset:39936
	global_load_lds_dwordx4 v160, s[86:87]
	v_lshl_add_u64 v[214:215], s[86:87], 0, v[158:159]
	s_mov_b32 m0, s65
	s_nop 0
	global_load_lds_dwordx4 v158, s[86:87]
	s_waitcnt vmcnt(8)
	s_waitcnt lgkmcnt(0)
	s_barrier
	s_waitcnt lgkmcnt(0)
	v_mfma_f32_16x16x32_bf16 v[64:67], v[24:27], v[166:169], v[64:67]
	v_mfma_f32_16x16x32_bf16 v[68:71], v[112:115], v[166:169], v[68:71]
	v_mfma_f32_16x16x32_bf16 v[72:75], v[24:27], v[190:193], v[72:75]
	v_mfma_f32_16x16x32_bf16 v[76:79], v[112:115], v[190:193], v[76:79]
	v_mfma_f32_16x16x32_bf16 v[80:83], v[24:27], v[198:201], v[80:83]
	v_mfma_f32_16x16x32_bf16 v[84:87], v[112:115], v[198:201], v[84:87]
	v_mfma_f32_16x16x32_bf16 v[88:91], v[24:27], v[206:209], v[88:91]
	v_mfma_f32_16x16x32_bf16 v[92:95], v[112:115], v[206:209], v[92:95]
	v_mfma_f32_16x16x32_bf16 v[64:67], v[28:31], v[170:173], v[64:67]
	v_mfma_f32_16x16x32_bf16 v[68:71], v[116:119], v[170:173], v[68:71]
	v_mfma_f32_16x16x32_bf16 v[72:75], v[28:31], v[194:197], v[72:75]
	v_mfma_f32_16x16x32_bf16 v[76:79], v[116:119], v[194:197], v[76:79]
	v_mfma_f32_16x16x32_bf16 v[80:83], v[28:31], v[202:205], v[80:83]
	v_mfma_f32_16x16x32_bf16 v[84:87], v[116:119], v[202:205], v[84:87]
	v_mfma_f32_16x16x32_bf16 v[88:91], v[28:31], v[210:213], v[88:91]
	v_mfma_f32_16x16x32_bf16 v[92:95], v[116:119], v[210:213], v[92:95]
	v_mfma_f32_16x16x32_bf16 v[96:99], v[120:123], v[166:169], v[96:99]
	v_mfma_f32_16x16x32_bf16 v[32:35], v[152:155], v[166:169], v[32:35]
	v_mfma_f32_16x16x32_bf16 v[36:39], v[120:123], v[190:193], v[36:39]
	v_mfma_f32_16x16x32_bf16 v[40:43], v[152:155], v[190:193], v[40:43]
	v_mfma_f32_16x16x32_bf16 v[44:47], v[120:123], v[198:201], v[44:47]
	v_mfma_f32_16x16x32_bf16 v[48:51], v[152:155], v[198:201], v[48:51]
	v_mfma_f32_16x16x32_bf16 v[52:55], v[120:123], v[206:209], v[52:55]
	v_mfma_f32_16x16x32_bf16 v[56:59], v[152:155], v[206:209], v[56:59]
	v_mfma_f32_16x16x32_bf16 v[96:99], v[124:127], v[170:173], v[96:99]
	v_mfma_f32_16x16x32_bf16 v[32:35], v[162:165], v[170:173], v[32:35]
	v_mfma_f32_16x16x32_bf16 v[36:39], v[124:127], v[194:197], v[36:39]
	v_mfma_f32_16x16x32_bf16 v[40:43], v[162:165], v[194:197], v[40:43]
	v_mfma_f32_16x16x32_bf16 v[44:47], v[124:127], v[202:205], v[44:47]
	v_mfma_f32_16x16x32_bf16 v[48:51], v[162:165], v[202:205], v[48:51]
	v_mfma_f32_16x16x32_bf16 v[52:55], v[124:127], v[210:213], v[52:55]
	v_mfma_f32_16x16x32_bf16 v[56:59], v[162:165], v[210:213], v[56:59]
	s_barrier
	s_add_i32 s75, s75, s61
	s_add_i32 s73, s75, 0x2000
	v_lshl_add_u64 v[178:179], v[178:179], 0, s[44:45]
	s_mov_b32 m0, s75
	s_add_u32 s86, s0, 0x10180
	ds_read_b128 v[166:169], v175 offset:49152
	ds_read_b128 v[170:173], v175 offset:50176
	ds_read_b128 v[190:193], v175 offset:51200
	ds_read_b128 v[194:197], v175 offset:52224
	ds_read_b128 v[198:201], v175 offset:53248
	ds_read_b128 v[202:205], v175 offset:54272
	ds_read_b128 v[206:209], v175 offset:55296
	ds_read_b128 v[210:213], v175 offset:56320
	global_load_lds_dwordx4 v[178:179], off
	v_lshl_add_u64 v[178:179], v[180:181], 0, s[44:45]
	s_mov_b32 m0, s73
	s_addc_u32 s87, s1, 0
	s_add_i32 s0, s88, s61
	global_load_lds_dwordx4 v[178:179], off
	s_mov_b32 m0, s0
	s_add_i32 s1, s0, 0x2000
	global_load_lds_dwordx4 v176, s[86:87]
	s_mov_b32 m0, s1
	s_nop 0
	global_load_lds_dwordx4 v156, s[86:87]
	v_lshl_add_u64 v[178:179], v[186:187], 0, s[44:45]
	s_mov_b32 m0, s68
	s_nop 0
	global_load_lds_dwordx4 v[178:179], off
	v_lshl_add_u64 v[178:179], v[188:189], 0, s[44:45]
	s_mov_b32 m0, s69
	s_nop 0
	global_load_lds_dwordx4 v[178:179], off
	s_waitcnt vmcnt(8)
	s_waitcnt lgkmcnt(0)
	s_barrier
	s_waitcnt lgkmcnt(0)
	v_mfma_f32_16x16x32_bf16 v[148:151], v[112:115], v[198:201], v[148:151]
	v_mfma_f32_16x16x32_bf16 v[0:3], v[24:27], v[206:209], v[0:3]
	v_mfma_f32_16x16x32_bf16 v[4:7], v[112:115], v[206:209], v[4:7]
	v_mfma_f32_16x16x32_bf16 v[128:131], v[24:27], v[166:169], v[128:131]
	v_mfma_f32_16x16x32_bf16 v[132:135], v[112:115], v[166:169], v[132:135]
	v_mfma_f32_16x16x32_bf16 v[136:139], v[24:27], v[190:193], v[136:139]
	v_mfma_f32_16x16x32_bf16 v[140:143], v[112:115], v[190:193], v[140:143]
	v_mfma_f32_16x16x32_bf16 v[144:147], v[24:27], v[198:201], v[144:147]
	v_mfma_f32_16x16x32_bf16 v[148:151], v[116:119], v[202:205], v[148:151]
	v_mfma_f32_16x16x32_bf16 v[0:3], v[28:31], v[210:213], v[0:3]
	v_mfma_f32_16x16x32_bf16 v[4:7], v[116:119], v[210:213], v[4:7]
	v_mfma_f32_16x16x32_bf16 v[128:131], v[28:31], v[170:173], v[128:131]
	v_mfma_f32_16x16x32_bf16 v[132:135], v[116:119], v[170:173], v[132:135]
	v_mfma_f32_16x16x32_bf16 v[136:139], v[28:31], v[194:197], v[136:139]
	v_mfma_f32_16x16x32_bf16 v[140:143], v[116:119], v[194:197], v[140:143]
	v_mfma_f32_16x16x32_bf16 v[144:147], v[28:31], v[202:205], v[144:147]
	v_mfma_f32_16x16x32_bf16 v[8:11], v[120:123], v[166:169], v[8:11]
	v_mfma_f32_16x16x32_bf16 v[12:15], v[152:155], v[166:169], v[12:15]
	v_mfma_f32_16x16x32_bf16 v[24:27], v[120:123], v[190:193], v[60:63]
	v_mfma_f32_16x16x32_bf16 v[28:31], v[152:155], v[190:193], v[100:103]
	v_mfma_f32_16x16x32_bf16 v[60:63], v[120:123], v[198:201], v[104:107]
	v_mfma_f32_16x16x32_bf16 v[100:103], v[152:155], v[198:201], v[108:111]
	v_mfma_f32_16x16x32_bf16 v[16:19], v[120:123], v[206:209], v[16:19]
	v_mfma_f32_16x16x32_bf16 v[20:23], v[152:155], v[206:209], v[20:23]
	v_mfma_f32_16x16x32_bf16 v[8:11], v[124:127], v[170:173], v[8:11]
	v_mfma_f32_16x16x32_bf16 v[12:15], v[162:165], v[170:173], v[12:15]
	v_mfma_f32_16x16x32_bf16 v[24:27], v[124:127], v[194:197], v[24:27]
	v_mfma_f32_16x16x32_bf16 v[28:31], v[162:165], v[194:197], v[28:31]
	v_mfma_f32_16x16x32_bf16 v[60:63], v[124:127], v[202:205], v[60:63]
	v_mfma_f32_16x16x32_bf16 v[100:103], v[162:165], v[202:205], v[100:103]
	v_mfma_f32_16x16x32_bf16 v[16:19], v[124:127], v[210:213], v[16:19]
	v_mfma_f32_16x16x32_bf16 v[20:23], v[162:165], v[210:213], v[20:23]
	s_barrier
	ds_read_b128 v[104:107], v182
	ds_read_b128 v[108:111], v182 offset:1024
	ds_read_b128 v[112:115], v182 offset:2048
	ds_read_b128 v[116:119], v182 offset:3072
	ds_read_b128 v[120:123], v183
	ds_read_b128 v[124:127], v183 offset:1024
	ds_read_b128 v[152:155], v183 offset:2048
	ds_read_b128 v[162:165], v183 offset:3072
	s_add_u32 s4, s4, 0x10180
	s_addc_u32 s5, s5, 0
	s_mov_b32 m0, s74
	ds_read_b128 v[166:169], v175
	ds_read_b128 v[170:173], v175 offset:1024
	ds_read_b128 v[190:193], v175 offset:2048
	ds_read_b128 v[194:197], v175 offset:3072
	ds_read_b128 v[198:201], v175 offset:4096
	ds_read_b128 v[202:205], v175 offset:5120
	ds_read_b128 v[206:209], v175 offset:6144
	ds_read_b128 v[210:213], v175 offset:7168
	global_load_lds_dwordx4 v160, s[4:5]
	s_mov_b32 m0, s6
	s_nop 0
	global_load_lds_dwordx4 v158, s[4:5]
	s_waitcnt vmcnt(8)
	s_waitcnt lgkmcnt(0)
	s_barrier
	s_waitcnt lgkmcnt(0)
	v_mfma_f32_16x16x32_bf16 v[64:67], v[104:107], v[166:169], v[64:67]
	v_mfma_f32_16x16x32_bf16 v[68:71], v[112:115], v[166:169], v[68:71]
	v_mfma_f32_16x16x32_bf16 v[72:75], v[104:107], v[190:193], v[72:75]
	v_mfma_f32_16x16x32_bf16 v[76:79], v[112:115], v[190:193], v[76:79]
	v_mfma_f32_16x16x32_bf16 v[80:83], v[104:107], v[198:201], v[80:83]
	v_mfma_f32_16x16x32_bf16 v[84:87], v[112:115], v[198:201], v[84:87]
	v_mfma_f32_16x16x32_bf16 v[88:91], v[104:107], v[206:209], v[88:91]
	v_mfma_f32_16x16x32_bf16 v[64:67], v[108:111], v[170:173], v[64:67]
	v_mfma_f32_16x16x32_bf16 v[68:71], v[116:119], v[170:173], v[68:71]
	v_mfma_f32_16x16x32_bf16 v[72:75], v[108:111], v[194:197], v[72:75]
	v_mfma_f32_16x16x32_bf16 v[76:79], v[116:119], v[194:197], v[76:79]
	v_mfma_f32_16x16x32_bf16 v[80:83], v[108:111], v[202:205], v[80:83]
	v_mfma_f32_16x16x32_bf16 v[84:87], v[116:119], v[202:205], v[84:87]
	v_mfma_f32_16x16x32_bf16 v[214:217], v[108:111], v[210:213], v[88:91]
	v_mfma_f32_16x16x32_bf16 v[88:91], v[112:115], v[206:209], v[92:95]
	v_mfma_f32_16x16x32_bf16 v[218:221], v[116:119], v[210:213], v[88:91]
	v_mfma_f32_16x16x32_bf16 v[88:91], v[120:123], v[166:169], v[96:99]
	v_mfma_f32_16x16x32_bf16 v[32:35], v[152:155], v[166:169], v[32:35]
	v_mfma_f32_16x16x32_bf16 v[36:39], v[120:123], v[190:193], v[36:39]
	v_mfma_f32_16x16x32_bf16 v[40:43], v[152:155], v[190:193], v[40:43]
	v_mfma_f32_16x16x32_bf16 v[44:47], v[120:123], v[198:201], v[44:47]
	v_mfma_f32_16x16x32_bf16 v[48:51], v[152:155], v[198:201], v[48:51]
	v_mfma_f32_16x16x32_bf16 v[52:55], v[120:123], v[206:209], v[52:55]
	v_mfma_f32_16x16x32_bf16 v[56:59], v[152:155], v[206:209], v[56:59]
	v_mfma_f32_16x16x32_bf16 v[96:99], v[124:127], v[170:173], v[88:91]
	v_mfma_f32_16x16x32_bf16 v[32:35], v[162:165], v[170:173], v[32:35]
	v_mfma_f32_16x16x32_bf16 v[36:39], v[124:127], v[194:197], v[36:39]
	v_mfma_f32_16x16x32_bf16 v[40:43], v[162:165], v[194:197], v[40:43]
	v_mfma_f32_16x16x32_bf16 v[44:47], v[124:127], v[202:205], v[44:47]
	v_mfma_f32_16x16x32_bf16 v[48:51], v[162:165], v[202:205], v[48:51]
	v_mfma_f32_16x16x32_bf16 v[52:55], v[124:127], v[210:213], v[52:55]
	v_mfma_f32_16x16x32_bf16 v[56:59], v[162:165], v[210:213], v[56:59]
	s_barrier
	s_mov_b32 m0, s72
	v_lshl_add_u64 v[248:249], s[54:55], 0, v[176:177]
	s_add_u32 s4, s54, 0x10000
	ds_read_b128 v[88:91], v175 offset:16384
	ds_read_b128 v[92:95], v175 offset:17408
	ds_read_b128 v[166:169], v175 offset:18432
	ds_read_b128 v[170:173], v175 offset:19456
	ds_read_b128 v[190:193], v175 offset:20480
	ds_read_b128 v[194:197], v175 offset:21504
	ds_read_b128 v[198:201], v175 offset:22528
	ds_read_b128 v[202:205], v175 offset:23552
	global_load_lds_dwordx4 v176, s[54:55]
	v_lshl_add_u64 v[250:251], s[54:55], 0, v[156:157]
	s_mov_b32 m0, s7
	s_addc_u32 s5, s55, 0
	global_load_lds_dwordx4 v156, s[54:55]
	s_mov_b32 m0, s47
	v_lshl_add_u64 v[242:243], s[56:57], 0, v[160:161]
	global_load_lds_dwordx4 v176, s[4:5]
	s_mov_b32 m0, s49
	v_lshl_add_u64 v[182:183], s[56:57], 0, v[158:159]
	global_load_lds_dwordx4 v156, s[4:5]
	s_mov_b32 m0, s62
	s_nop 0
	global_load_lds_dwordx4 v160, s[56:57]
	s_mov_b32 m0, s63
	s_nop 0
	global_load_lds_dwordx4 v158, s[56:57]
	s_waitcnt vmcnt(8)
	s_waitcnt lgkmcnt(0)
	s_barrier
	s_waitcnt lgkmcnt(0)
	v_mfma_f32_16x16x32_bf16 v[0:3], v[104:107], v[198:201], v[0:3]
	v_mfma_f32_16x16x32_bf16 v[4:7], v[112:115], v[198:201], v[4:7]
	v_mfma_f32_16x16x32_bf16 v[128:131], v[104:107], v[88:91], v[128:131]
	v_mfma_f32_16x16x32_bf16 v[132:135], v[112:115], v[88:91], v[132:135]
	v_mfma_f32_16x16x32_bf16 v[136:139], v[104:107], v[166:169], v[136:139]
	v_mfma_f32_16x16x32_bf16 v[140:143], v[112:115], v[166:169], v[140:143]
	v_mfma_f32_16x16x32_bf16 v[144:147], v[104:107], v[190:193], v[144:147]
	v_mfma_f32_16x16x32_bf16 v[148:151], v[112:115], v[190:193], v[148:151]
	v_mfma_f32_16x16x32_bf16 v[0:3], v[108:111], v[202:205], v[0:3]
	v_mfma_f32_16x16x32_bf16 v[4:7], v[116:119], v[202:205], v[4:7]
	v_mfma_f32_16x16x32_bf16 v[128:131], v[108:111], v[92:95], v[128:131]
	v_mfma_f32_16x16x32_bf16 v[132:135], v[116:119], v[92:95], v[132:135]
	v_mfma_f32_16x16x32_bf16 v[136:139], v[108:111], v[170:173], v[136:139]
	v_mfma_f32_16x16x32_bf16 v[140:143], v[116:119], v[170:173], v[140:143]
	v_mfma_f32_16x16x32_bf16 v[144:147], v[108:111], v[194:197], v[144:147]
	v_mfma_f32_16x16x32_bf16 v[206:209], v[116:119], v[194:197], v[148:151]
	v_mfma_f32_16x16x32_bf16 v[8:11], v[120:123], v[88:91], v[8:11]
	v_mfma_f32_16x16x32_bf16 v[116:119], v[124:127], v[92:95], v[8:11]
	v_mfma_f32_16x16x32_bf16 v[8:11], v[152:155], v[88:91], v[12:15]
	v_mfma_f32_16x16x32_bf16 v[210:213], v[162:165], v[92:95], v[8:11]
	v_mfma_f32_16x16x32_bf16 v[8:11], v[120:123], v[166:169], v[24:27]
	v_mfma_f32_16x16x32_bf16 v[222:225], v[124:127], v[170:173], v[8:11]
	v_mfma_f32_16x16x32_bf16 v[8:11], v[152:155], v[166:169], v[28:31]
	v_mfma_f32_16x16x32_bf16 v[166:169], v[162:165], v[170:173], v[8:11]
	v_mfma_f32_16x16x32_bf16 v[8:11], v[120:123], v[190:193], v[60:63]
	v_mfma_f32_16x16x32_bf16 v[170:173], v[124:127], v[194:197], v[8:11]
	v_mfma_f32_16x16x32_bf16 v[8:11], v[152:155], v[190:193], v[100:103]
	v_mfma_f32_16x16x32_bf16 v[190:193], v[162:165], v[194:197], v[8:11]
	v_mfma_f32_16x16x32_bf16 v[8:11], v[120:123], v[198:201], v[16:19]
	v_mfma_f32_16x16x32_bf16 v[120:123], v[124:127], v[202:205], v[8:11]
	v_mfma_f32_16x16x32_bf16 v[8:11], v[152:155], v[198:201], v[20:23]
	v_mfma_f32_16x16x32_bf16 v[162:165], v[162:165], v[202:205], v[8:11]
	s_barrier
	s_nop 4
	ds_read_b128 v[8:11], v226
	ds_read_b128 v[12:15], v226 offset:1024
	ds_read_b128 v[16:19], v226 offset:2048
	ds_read_b128 v[20:23], v226 offset:3072
	ds_read_b128 v[194:197], v227
	ds_read_b128 v[198:201], v227 offset:1024
	ds_read_b128 v[202:205], v227 offset:2048
	ds_read_b128 v[226:229], v227 offset:3072
	s_add_u32 s4, s56, 0x10000
	s_addc_u32 s5, s57, 0
	s_mov_b32 m0, s64
	ds_read_b128 v[24:27], v175 offset:32768
	ds_read_b128 v[28:31], v175 offset:33792
	ds_read_b128 v[60:63], v175 offset:34816
	ds_read_b128 v[230:233], v175 offset:35840
	ds_read_b128 v[234:237], v175 offset:36864
	ds_read_b128 v[238:241], v175 offset:37888
	ds_read_b128 v[178:181], v175 offset:38912
	ds_read_b128 v[186:189], v175 offset:39936
	global_load_lds_dwordx4 v160, s[4:5]
	v_lshl_add_u64 v[88:89], s[4:5], 0, v[158:159]
	s_mov_b32 m0, s65
	s_nop 0
	global_load_lds_dwordx4 v158, s[4:5]
	s_waitcnt vmcnt(8)
	s_waitcnt lgkmcnt(0)
	s_barrier
	s_waitcnt lgkmcnt(0)
	v_mfma_f32_16x16x32_bf16 v[64:67], v[8:11], v[24:27], v[64:67]
	v_mfma_f32_16x16x32_bf16 v[152:155], v[12:15], v[28:31], v[64:67]
	v_mfma_f32_16x16x32_bf16 v[64:67], v[16:19], v[24:27], v[68:71]
	v_mfma_f32_16x16x32_bf16 v[148:151], v[20:23], v[28:31], v[64:67]
	v_mfma_f32_16x16x32_bf16 v[64:67], v[8:11], v[60:63], v[72:75]
	v_mfma_f32_16x16x32_bf16 v[108:111], v[12:15], v[230:233], v[64:67]
	v_mfma_f32_16x16x32_bf16 v[64:67], v[16:19], v[60:63], v[76:79]
	v_mfma_f32_16x16x32_bf16 v[104:107], v[20:23], v[230:233], v[64:67]
	v_mfma_f32_16x16x32_bf16 v[64:67], v[8:11], v[234:237], v[80:83]
	v_mfma_f32_16x16x32_bf16 v[92:95], v[12:15], v[238:241], v[64:67]
	v_mfma_f32_16x16x32_bf16 v[64:67], v[16:19], v[234:237], v[84:87]
	v_mfma_f32_16x16x32_bf16 v[88:91], v[20:23], v[238:241], v[64:67]
	v_mfma_f32_16x16x32_bf16 v[64:67], v[8:11], v[178:181], v[214:217]
	v_mfma_f32_16x16x32_bf16 v[76:79], v[12:15], v[186:189], v[64:67]
	v_mfma_f32_16x16x32_bf16 v[64:67], v[16:19], v[178:181], v[218:221]
	v_mfma_f32_16x16x32_bf16 v[72:75], v[20:23], v[186:189], v[64:67]
	v_mfma_f32_16x16x32_bf16 v[64:67], v[194:197], v[24:27], v[96:99]
	v_mfma_f32_16x16x32_bf16 v[24:27], v[202:205], v[24:27], v[32:35]
	v_mfma_f32_16x16x32_bf16 v[112:115], v[226:229], v[28:31], v[24:27]
	v_mfma_f32_16x16x32_bf16 v[24:27], v[194:197], v[60:63], v[36:39]
	v_mfma_f32_16x16x32_bf16 v[100:103], v[198:201], v[230:233], v[24:27]
	v_mfma_f32_16x16x32_bf16 v[24:27], v[202:205], v[60:63], v[40:43]
	v_mfma_f32_16x16x32_bf16 v[96:99], v[226:229], v[230:233], v[24:27]
	v_mfma_f32_16x16x32_bf16 v[24:27], v[194:197], v[234:237], v[44:47]
	v_mfma_f32_16x16x32_bf16 v[84:87], v[198:201], v[238:241], v[24:27]
	v_mfma_f32_16x16x32_bf16 v[24:27], v[202:205], v[234:237], v[48:51]
	v_mfma_f32_16x16x32_bf16 v[80:83], v[226:229], v[238:241], v[24:27]
	v_mfma_f32_16x16x32_bf16 v[24:27], v[194:197], v[178:181], v[52:55]
	v_mfma_f32_16x16x32_bf16 v[68:71], v[198:201], v[186:189], v[24:27]
	v_mfma_f32_16x16x32_bf16 v[24:27], v[202:205], v[178:181], v[56:59]
	v_mfma_f32_16x16x32_bf16 v[124:127], v[198:201], v[28:31], v[64:67]
	v_mfma_f32_16x16x32_bf16 v[64:67], v[226:229], v[186:189], v[24:27]
	s_barrier
	s_mov_b32 m0, s75
	s_nop 2
	v_lshl_add_u64 v[24:25], v[248:249], 0, s[82:83]
	s_add_u32 s4, s54, 0x10080
	ds_read_b128 v[32:35], v175 offset:49152
	ds_read_b128 v[36:39], v175 offset:50176
	ds_read_b128 v[178:181], v175 offset:51200
	ds_read_b128 v[186:189], v175 offset:52224
	ds_read_b128 v[214:217], v175 offset:53248
	ds_read_b128 v[218:221], v175 offset:54272
	ds_read_b128 v[230:233], v175 offset:55296
	ds_read_b128 v[234:237], v175 offset:56320
	global_load_lds_dwordx4 v[24:25], off
	v_lshl_add_u64 v[24:25], v[250:251], 0, s[82:83]
	s_mov_b32 m0, s73
	s_addc_u32 s5, s55, 0
	global_load_lds_dwordx4 v[24:25], off
	s_mov_b32 m0, s0
	s_nop 0
	global_load_lds_dwordx4 v176, s[4:5]
	s_mov_b32 m0, s1
	s_nop 0
	global_load_lds_dwordx4 v156, s[4:5]
	v_lshl_add_u64 v[24:25], v[242:243], 0, s[82:83]
	s_mov_b32 m0, s68
	s_nop 0
	global_load_lds_dwordx4 v[24:25], off
	v_lshl_add_u64 v[24:25], v[182:183], 0, s[82:83]
	s_mov_b32 m0, s69
	s_nop 0
	global_load_lds_dwordx4 v[24:25], off
	s_waitcnt vmcnt(8)
	s_waitcnt lgkmcnt(0)
	s_barrier
	s_waitcnt lgkmcnt(0)
	v_mfma_f32_16x16x32_bf16 v[24:27], v[8:11], v[32:35], v[128:131]
	v_mfma_f32_16x16x32_bf16 v[60:63], v[12:15], v[36:39], v[24:27]
	v_mfma_f32_16x16x32_bf16 v[24:27], v[16:19], v[32:35], v[132:135]
	v_mfma_f32_16x16x32_bf16 v[56:59], v[20:23], v[36:39], v[24:27]
	v_mfma_f32_16x16x32_bf16 v[24:27], v[8:11], v[178:181], v[136:139]
	v_mfma_f32_16x16x32_bf16 v[44:47], v[12:15], v[186:189], v[24:27]
	v_mfma_f32_16x16x32_bf16 v[24:27], v[16:19], v[178:181], v[140:143]
	v_mfma_f32_16x16x32_bf16 v[40:43], v[20:23], v[186:189], v[24:27]
	v_mfma_f32_16x16x32_bf16 v[24:27], v[8:11], v[214:217], v[144:147]
	v_mfma_f32_16x16x32_bf16 v[0:3], v[8:11], v[230:233], v[0:3]
	v_mfma_f32_16x16x32_bf16 v[28:31], v[12:15], v[218:221], v[24:27]
	v_mfma_f32_16x16x32_bf16 v[24:27], v[16:19], v[214:217], v[206:209]
	v_mfma_f32_16x16x32_bf16 v[12:15], v[12:15], v[234:237], v[0:3]
	v_mfma_f32_16x16x32_bf16 v[0:3], v[16:19], v[230:233], v[4:7]
	v_mfma_f32_16x16x32_bf16 v[24:27], v[20:23], v[218:221], v[24:27]
	v_mfma_f32_16x16x32_bf16 v[8:11], v[20:23], v[234:237], v[0:3]
	v_mfma_f32_16x16x32_bf16 v[0:3], v[194:197], v[32:35], v[116:119]
	v_mfma_f32_16x16x32_bf16 v[52:55], v[198:201], v[36:39], v[0:3]
	v_mfma_f32_16x16x32_bf16 v[0:3], v[202:205], v[32:35], v[210:213]
	v_mfma_f32_16x16x32_bf16 v[48:51], v[226:229], v[36:39], v[0:3]
	v_mfma_f32_16x16x32_bf16 v[0:3], v[194:197], v[178:181], v[222:225]
	v_mfma_f32_16x16x32_bf16 v[36:39], v[198:201], v[186:189], v[0:3]
	v_mfma_f32_16x16x32_bf16 v[0:3], v[202:205], v[178:181], v[166:169]
	v_mfma_f32_16x16x32_bf16 v[32:35], v[226:229], v[186:189], v[0:3]
	v_mfma_f32_16x16x32_bf16 v[0:3], v[194:197], v[214:217], v[170:173]
	v_mfma_f32_16x16x32_bf16 v[20:23], v[198:201], v[218:221], v[0:3]
	v_mfma_f32_16x16x32_bf16 v[0:3], v[202:205], v[214:217], v[190:193]
	v_mfma_f32_16x16x32_bf16 v[16:19], v[226:229], v[218:221], v[0:3]
	v_mfma_f32_16x16x32_bf16 v[0:3], v[194:197], v[230:233], v[120:123]
	v_mfma_f32_16x16x32_bf16 v[4:7], v[198:201], v[234:237], v[0:3]
	v_mfma_f32_16x16x32_bf16 v[0:3], v[202:205], v[230:233], v[162:165]
	v_mfma_f32_16x16x32_bf16 v[0:3], v[226:229], v[234:237], v[0:3]
	s_barrier
	s_andn2_b64 vcc, exec, s[38:39]
	s_cbranch_vccnz .LBB0_573
	s_barrier

.LBB0_589:
	s_ashr_i32 s49, s48, 31
	s_lshl_b64 s[6:7], s[48:49], 17
	s_add_u32 s50, s12, s6
	s_addc_u32 s51, s20, s7
	s_and_b64 s[6:7], s[42:43], exec
	s_cselect_b32 s57, s51, s5
	s_cselect_b32 s56, s50, s4
	s_ashr_i32 s47, s46, 31
	s_lshl_b64 s[6:7], s[46:47], 17
	s_add_u32 s52, s27, s6
	s_addc_u32 s53, s60, s7
	s_and_b64 s[6:7], s[42:43], exec
	s_cselect_b32 s55, s53, s1
	s_cselect_b32 s54, s52, s0
	s_add_i32 s72, 0, 0x10000
	s_add_i32 s47, 0, 0x14000
	v_add_u32_e32 v214, s72, v192
	v_add_u32_e32 v215, s47, v192
	ds_read_b128 v[0:3], v214
	ds_read_b128 v[4:7], v214 offset:1024
	ds_read_b128 v[8:11], v214 offset:2048
	ds_read_b128 v[12:15], v214 offset:3072
	s_waitcnt vmcnt(0)
	ds_read_b128 v[16:19], v215
	ds_read_b128 v[20:23], v215 offset:1024
	ds_read_b128 v[24:27], v215 offset:2048
	ds_read_b128 v[28:31], v215 offset:3072
	v_mov_b64_e32 v[184:185], 0x100
	s_add_u32 s6, s4, 0x10080
	s_addc_u32 s7, s5, 0
	s_add_i32 s74, s62, 0xc000
	s_mov_b32 m0, s74
	ds_read_b128 v[32:35], v193
	ds_read_b128 v[36:39], v193 offset:1024
	ds_read_b128 v[40:43], v193 offset:2048
	ds_read_b128 v[44:47], v193 offset:3072
	ds_read_b128 v[48:51], v193 offset:4096
	ds_read_b128 v[52:55], v193 offset:5120
	ds_read_b128 v[56:59], v193 offset:6144
	ds_read_b128 v[60:63], v193 offset:7168
	global_load_lds_dwordx4 v164, s[6:7]
	v_lshl_add_u64 v[64:65], s[6:7], 0, v[162:163]
	s_add_i32 s6, s62, 0xe000
	s_mov_b32 m0, s6
	s_nop 0
	global_load_lds_dwordx4 v[64:65], off
	s_waitcnt vmcnt(8)
	s_waitcnt lgkmcnt(0)
	s_barrier
	s_waitcnt lgkmcnt(0)
	v_mfma_f32_16x16x32_bf16 v[64:67], v[0:3], v[32:35], 0
	v_mfma_f32_16x16x32_bf16 v[68:71], v[8:11], v[32:35], 0
	v_mfma_f32_16x16x32_bf16 v[72:75], v[0:3], v[40:43], 0
	v_mfma_f32_16x16x32_bf16 v[76:79], v[8:11], v[40:43], 0
	v_mfma_f32_16x16x32_bf16 v[80:83], v[0:3], v[48:51], 0
	v_mfma_f32_16x16x32_bf16 v[84:87], v[8:11], v[48:51], 0
	v_mfma_f32_16x16x32_bf16 v[88:91], v[0:3], v[56:59], 0
	v_mfma_f32_16x16x32_bf16 v[92:95], v[8:11], v[56:59], 0
	v_mfma_f32_16x16x32_bf16 v[64:67], v[4:7], v[36:39], v[64:67]
	v_mfma_f32_16x16x32_bf16 v[68:71], v[12:15], v[36:39], v[68:71]
	v_mfma_f32_16x16x32_bf16 v[72:75], v[4:7], v[44:47], v[72:75]
	v_mfma_f32_16x16x32_bf16 v[76:79], v[12:15], v[44:47], v[76:79]
	v_mfma_f32_16x16x32_bf16 v[80:83], v[4:7], v[52:55], v[80:83]
	v_mfma_f32_16x16x32_bf16 v[84:87], v[12:15], v[52:55], v[84:87]
	v_mfma_f32_16x16x32_bf16 v[88:91], v[4:7], v[60:63], v[88:91]
	v_mfma_f32_16x16x32_bf16 v[92:95], v[12:15], v[60:63], v[92:95]
	v_mfma_f32_16x16x32_bf16 v[96:99], v[16:19], v[32:35], 0
	v_mfma_f32_16x16x32_bf16 v[32:35], v[24:27], v[32:35], 0
	v_mfma_f32_16x16x32_bf16 v[96:99], v[20:23], v[36:39], v[96:99]
	v_mfma_f32_16x16x32_bf16 v[32:35], v[28:31], v[36:39], v[32:35]
	v_mfma_f32_16x16x32_bf16 v[36:39], v[16:19], v[40:43], 0
	v_mfma_f32_16x16x32_bf16 v[40:43], v[24:27], v[40:43], 0
	v_mfma_f32_16x16x32_bf16 v[36:39], v[20:23], v[44:47], v[36:39]
	v_mfma_f32_16x16x32_bf16 v[40:43], v[28:31], v[44:47], v[40:43]
	v_mfma_f32_16x16x32_bf16 v[44:47], v[16:19], v[48:51], 0
	v_mfma_f32_16x16x32_bf16 v[48:51], v[24:27], v[48:51], 0
	v_mfma_f32_16x16x32_bf16 v[44:47], v[20:23], v[52:55], v[44:47]
	v_mfma_f32_16x16x32_bf16 v[48:51], v[28:31], v[52:55], v[48:51]
	v_mfma_f32_16x16x32_bf16 v[52:55], v[16:19], v[56:59], 0
	v_mfma_f32_16x16x32_bf16 v[56:59], v[24:27], v[56:59], 0
	v_mfma_f32_16x16x32_bf16 v[52:55], v[20:23], v[60:63], v[52:55]
	v_mfma_f32_16x16x32_bf16 v[56:59], v[28:31], v[60:63], v[56:59]
	s_barrier
	s_add_i32 s72, s72, s61
	v_lshl_add_u64 v[174:175], s[0:1], 0, v[176:177]
	s_add_i32 s7, s72, 0x2000
	v_lshl_add_u64 v[128:129], v[174:175], 0, s[58:59]
	s_mov_b32 m0, s72
	v_lshl_add_u64 v[182:183], s[0:1], 0, v[160:161]
	s_add_u32 s86, s0, 0x10100
	ds_read_b128 v[60:63], v193 offset:16384
	ds_read_b128 v[100:103], v193 offset:17408
	ds_read_b128 v[104:107], v193 offset:18432
	ds_read_b128 v[108:111], v193 offset:19456
	ds_read_b128 v[112:115], v193 offset:20480
	ds_read_b128 v[116:119], v193 offset:21504
	ds_read_b128 v[120:123], v193 offset:22528
	ds_read_b128 v[124:127], v193 offset:23552
	global_load_lds_dwordx4 v[128:129], off
	v_lshl_add_u64 v[128:129], v[182:183], 0, s[58:59]
	s_mov_b32 m0, s7
	s_addc_u32 s87, s1, 0
	s_add_i32 s47, s47, s61
	global_load_lds_dwordx4 v[128:129], off
	s_mov_b32 m0, s47
	s_add_i32 s49, s47, 0x2000
	global_load_lds_dwordx4 v176, s[86:87]
	s_mov_b32 m0, s49
	v_lshl_add_u64 v[190:191], s[4:5], 0, v[164:165]
	global_load_lds_dwordx4 v160, s[86:87]
	v_lshl_add_u64 v[128:129], v[190:191], 0, s[58:59]
	s_mov_b32 m0, s62
	v_lshl_add_u64 v[210:211], s[4:5], 0, v[162:163]
	global_load_lds_dwordx4 v[128:129], off
	v_lshl_add_u64 v[128:129], v[210:211], 0, s[58:59]
	s_mov_b32 m0, s63
	s_nop 0
	global_load_lds_dwordx4 v[128:129], off
	s_waitcnt vmcnt(8)
	s_waitcnt lgkmcnt(0)
	s_barrier
	s_waitcnt lgkmcnt(0)
	v_mfma_f32_16x16x32_bf16 v[128:131], v[0:3], v[60:63], 0
	v_mfma_f32_16x16x32_bf16 v[136:139], v[0:3], v[104:107], 0
	v_mfma_f32_16x16x32_bf16 v[144:147], v[0:3], v[112:115], 0
	v_mfma_f32_16x16x32_bf16 v[0:3], v[0:3], v[120:123], 0
	v_mfma_f32_16x16x32_bf16 v[128:131], v[4:7], v[100:103], v[128:131]
	v_mfma_f32_16x16x32_bf16 v[132:135], v[8:11], v[60:63], 0
	v_mfma_f32_16x16x32_bf16 v[136:139], v[4:7], v[108:111], v[136:139]
	v_mfma_f32_16x16x32_bf16 v[140:143], v[8:11], v[104:107], 0
	v_mfma_f32_16x16x32_bf16 v[144:147], v[4:7], v[116:119], v[144:147]
	v_mfma_f32_16x16x32_bf16 v[148:151], v[8:11], v[112:115], 0
	v_mfma_f32_16x16x32_bf16 v[0:3], v[4:7], v[124:127], v[0:3]
	v_mfma_f32_16x16x32_bf16 v[4:7], v[8:11], v[120:123], 0
	v_mfma_f32_16x16x32_bf16 v[132:135], v[12:15], v[100:103], v[132:135]
	v_mfma_f32_16x16x32_bf16 v[140:143], v[12:15], v[108:111], v[140:143]
	v_mfma_f32_16x16x32_bf16 v[148:151], v[12:15], v[116:119], v[148:151]
	v_mfma_f32_16x16x32_bf16 v[4:7], v[12:15], v[124:127], v[4:7]
	v_mfma_f32_16x16x32_bf16 v[8:11], v[16:19], v[60:63], 0
	v_mfma_f32_16x16x32_bf16 v[12:15], v[24:27], v[60:63], 0
	v_mfma_f32_16x16x32_bf16 v[8:11], v[20:23], v[100:103], v[8:11]
	v_mfma_f32_16x16x32_bf16 v[12:15], v[28:31], v[100:103], v[12:15]
	v_mfma_f32_16x16x32_bf16 v[60:63], v[16:19], v[104:107], 0
	v_mfma_f32_16x16x32_bf16 v[100:103], v[24:27], v[104:107], 0
	v_mfma_f32_16x16x32_bf16 v[104:107], v[16:19], v[112:115], 0
	v_mfma_f32_16x16x32_bf16 v[16:19], v[16:19], v[120:123], 0
	v_mfma_f32_16x16x32_bf16 v[60:63], v[20:23], v[108:111], v[60:63]
	v_mfma_f32_16x16x32_bf16 v[104:107], v[20:23], v[116:119], v[104:107]
	v_mfma_f32_16x16x32_bf16 v[16:19], v[20:23], v[124:127], v[16:19]
	v_mfma_f32_16x16x32_bf16 v[20:23], v[24:27], v[120:123], 0
	v_mfma_f32_16x16x32_bf16 v[100:103], v[28:31], v[108:111], v[100:103]
	v_mfma_f32_16x16x32_bf16 v[108:111], v[24:27], v[112:115], 0
	v_mfma_f32_16x16x32_bf16 v[20:23], v[28:31], v[124:127], v[20:23]
	v_mfma_f32_16x16x32_bf16 v[108:111], v[28:31], v[116:119], v[108:111]
	s_barrier
	s_add_i32 s75, 0, 0x18000
	s_add_i32 s88, 0, 0x1c000
	v_add_u32_e32 v234, s75, v192
	v_add_u32_e32 v235, s88, v192
	ds_read_b128 v[24:27], v234
	ds_read_b128 v[28:31], v234 offset:1024
	ds_read_b128 v[112:115], v234 offset:2048
	ds_read_b128 v[116:119], v234 offset:3072
	ds_read_b128 v[120:123], v235
	ds_read_b128 v[124:127], v235 offset:1024
	ds_read_b128 v[152:155], v235 offset:2048
	ds_read_b128 v[156:159], v235 offset:3072
	s_add_u32 s86, s4, 0x10100
	s_addc_u32 s87, s5, 0
	s_mov_b32 m0, s64
	ds_read_b128 v[166:169], v193 offset:32768
	ds_read_b128 v[170:173], v193 offset:33792
	ds_read_b128 v[178:181], v193 offset:34816
	ds_read_b128 v[186:189], v193 offset:35840
	ds_read_b128 v[194:197], v193 offset:36864
	ds_read_b128 v[198:201], v193 offset:37888
	ds_read_b128 v[202:205], v193 offset:38912
	ds_read_b128 v[206:209], v193 offset:39936
	global_load_lds_dwordx4 v164, s[86:87]
	v_lshl_add_u64 v[212:213], s[86:87], 0, v[162:163]
	s_mov_b32 m0, s65
	s_nop 0
	global_load_lds_dwordx4 v162, s[86:87]
	s_waitcnt vmcnt(8)
	s_waitcnt lgkmcnt(0)
	s_barrier
	s_waitcnt lgkmcnt(0)
	v_mfma_f32_16x16x32_bf16 v[64:67], v[24:27], v[166:169], v[64:67]
	v_mfma_f32_16x16x32_bf16 v[68:71], v[112:115], v[166:169], v[68:71]
	v_mfma_f32_16x16x32_bf16 v[72:75], v[24:27], v[178:181], v[72:75]
	v_mfma_f32_16x16x32_bf16 v[76:79], v[112:115], v[178:181], v[76:79]
	v_mfma_f32_16x16x32_bf16 v[80:83], v[24:27], v[194:197], v[80:83]
	v_mfma_f32_16x16x32_bf16 v[84:87], v[112:115], v[194:197], v[84:87]
	v_mfma_f32_16x16x32_bf16 v[88:91], v[24:27], v[202:205], v[88:91]
	v_mfma_f32_16x16x32_bf16 v[92:95], v[112:115], v[202:205], v[92:95]
	v_mfma_f32_16x16x32_bf16 v[64:67], v[28:31], v[170:173], v[64:67]
	v_mfma_f32_16x16x32_bf16 v[68:71], v[116:119], v[170:173], v[68:71]
	v_mfma_f32_16x16x32_bf16 v[72:75], v[28:31], v[186:189], v[72:75]
	v_mfma_f32_16x16x32_bf16 v[76:79], v[116:119], v[186:189], v[76:79]
	v_mfma_f32_16x16x32_bf16 v[80:83], v[28:31], v[198:201], v[80:83]
	v_mfma_f32_16x16x32_bf16 v[84:87], v[116:119], v[198:201], v[84:87]
	v_mfma_f32_16x16x32_bf16 v[88:91], v[28:31], v[206:209], v[88:91]
	v_mfma_f32_16x16x32_bf16 v[92:95], v[116:119], v[206:209], v[92:95]
	v_mfma_f32_16x16x32_bf16 v[32:35], v[152:155], v[166:169], v[32:35]
	v_mfma_f32_16x16x32_bf16 v[36:39], v[120:123], v[178:181], v[36:39]
	v_mfma_f32_16x16x32_bf16 v[40:43], v[152:155], v[178:181], v[40:43]
	v_mfma_f32_16x16x32_bf16 v[44:47], v[120:123], v[194:197], v[44:47]
	v_mfma_f32_16x16x32_bf16 v[48:51], v[152:155], v[194:197], v[48:51]
	v_mfma_f32_16x16x32_bf16 v[52:55], v[120:123], v[202:205], v[52:55]
	v_mfma_f32_16x16x32_bf16 v[56:59], v[152:155], v[202:205], v[56:59]
	v_mfma_f32_16x16x32_bf16 v[96:99], v[120:123], v[166:169], v[96:99]
	v_mfma_f32_16x16x32_bf16 v[32:35], v[156:159], v[170:173], v[32:35]
	v_mfma_f32_16x16x32_bf16 v[36:39], v[124:127], v[186:189], v[36:39]
	v_mfma_f32_16x16x32_bf16 v[40:43], v[156:159], v[186:189], v[40:43]
	v_mfma_f32_16x16x32_bf16 v[44:47], v[124:127], v[198:201], v[44:47]
	v_mfma_f32_16x16x32_bf16 v[48:51], v[156:159], v[198:201], v[48:51]
	v_mfma_f32_16x16x32_bf16 v[52:55], v[124:127], v[206:209], v[52:55]
	v_mfma_f32_16x16x32_bf16 v[56:59], v[156:159], v[206:209], v[56:59]
	v_mfma_f32_16x16x32_bf16 v[96:99], v[124:127], v[170:173], v[96:99]
	s_barrier
	s_add_i32 s75, s75, s61
	s_add_i32 s73, s75, 0x2000
	v_lshl_add_u64 v[174:175], v[174:175], 0, s[44:45]
	s_mov_b32 m0, s75
	s_add_u32 s86, s0, 0x10180
	ds_read_b128 v[166:169], v193 offset:49152
	ds_read_b128 v[170:173], v193 offset:50176
	ds_read_b128 v[178:181], v193 offset:51200
	ds_read_b128 v[186:189], v193 offset:52224
	ds_read_b128 v[194:197], v193 offset:53248
	ds_read_b128 v[198:201], v193 offset:54272
	ds_read_b128 v[202:205], v193 offset:55296
	ds_read_b128 v[206:209], v193 offset:56320
	global_load_lds_dwordx4 v[174:175], off
	v_lshl_add_u64 v[174:175], v[182:183], 0, s[44:45]
	s_mov_b32 m0, s73
	s_addc_u32 s87, s1, 0
	s_add_i32 s0, s88, s61
	global_load_lds_dwordx4 v[174:175], off
	s_mov_b32 m0, s0
	s_add_i32 s1, s0, 0x2000
	global_load_lds_dwordx4 v176, s[86:87]
	s_mov_b32 m0, s1
	s_nop 0
	global_load_lds_dwordx4 v160, s[86:87]
	v_lshl_add_u64 v[174:175], v[190:191], 0, s[44:45]
	s_mov_b32 m0, s68
	s_nop 0
	global_load_lds_dwordx4 v[174:175], off
	v_lshl_add_u64 v[174:175], v[210:211], 0, s[44:45]
	s_mov_b32 m0, s69
	s_nop 0
	global_load_lds_dwordx4 v[174:175], off
	s_waitcnt vmcnt(8)
	s_waitcnt lgkmcnt(0)
	s_barrier
	s_waitcnt lgkmcnt(0)
	v_mfma_f32_16x16x32_bf16 v[132:135], v[112:115], v[166:169], v[132:135]
	v_mfma_f32_16x16x32_bf16 v[140:143], v[112:115], v[178:181], v[140:143]
	v_mfma_f32_16x16x32_bf16 v[144:147], v[24:27], v[194:197], v[144:147]
	v_mfma_f32_16x16x32_bf16 v[148:151], v[112:115], v[194:197], v[148:151]
	v_mfma_f32_16x16x32_bf16 v[0:3], v[24:27], v[202:205], v[0:3]
	v_mfma_f32_16x16x32_bf16 v[4:7], v[112:115], v[202:205], v[4:7]
	v_mfma_f32_16x16x32_bf16 v[128:131], v[24:27], v[166:169], v[128:131]
	v_mfma_f32_16x16x32_bf16 v[132:135], v[116:119], v[170:173], v[132:135]
	v_mfma_f32_16x16x32_bf16 v[136:139], v[24:27], v[178:181], v[136:139]
	v_mfma_f32_16x16x32_bf16 v[140:143], v[116:119], v[186:189], v[140:143]
	v_mfma_f32_16x16x32_bf16 v[144:147], v[28:31], v[198:201], v[144:147]
	v_mfma_f32_16x16x32_bf16 v[148:151], v[116:119], v[198:201], v[148:151]
	v_mfma_f32_16x16x32_bf16 v[0:3], v[28:31], v[206:209], v[0:3]
	v_mfma_f32_16x16x32_bf16 v[4:7], v[116:119], v[206:209], v[4:7]
	v_mfma_f32_16x16x32_bf16 v[128:131], v[28:31], v[170:173], v[128:131]
	v_mfma_f32_16x16x32_bf16 v[136:139], v[28:31], v[186:189], v[136:139]
	v_mfma_f32_16x16x32_bf16 v[8:11], v[120:123], v[166:169], v[8:11]
	v_mfma_f32_16x16x32_bf16 v[12:15], v[152:155], v[166:169], v[12:15]
	v_mfma_f32_16x16x32_bf16 v[24:27], v[120:123], v[178:181], v[60:63]
	v_mfma_f32_16x16x32_bf16 v[28:31], v[152:155], v[178:181], v[100:103]
	v_mfma_f32_16x16x32_bf16 v[60:63], v[120:123], v[194:197], v[104:107]
	v_mfma_f32_16x16x32_bf16 v[100:103], v[152:155], v[194:197], v[108:111]
	v_mfma_f32_16x16x32_bf16 v[16:19], v[120:123], v[202:205], v[16:19]
	v_mfma_f32_16x16x32_bf16 v[20:23], v[152:155], v[202:205], v[20:23]
	v_mfma_f32_16x16x32_bf16 v[8:11], v[124:127], v[170:173], v[8:11]
	v_mfma_f32_16x16x32_bf16 v[12:15], v[156:159], v[170:173], v[12:15]
	v_mfma_f32_16x16x32_bf16 v[24:27], v[124:127], v[186:189], v[24:27]
	v_mfma_f32_16x16x32_bf16 v[28:31], v[156:159], v[186:189], v[28:31]
	v_mfma_f32_16x16x32_bf16 v[60:63], v[124:127], v[198:201], v[60:63]
	v_mfma_f32_16x16x32_bf16 v[100:103], v[156:159], v[198:201], v[100:103]
	v_mfma_f32_16x16x32_bf16 v[16:19], v[124:127], v[206:209], v[16:19]
	v_mfma_f32_16x16x32_bf16 v[20:23], v[156:159], v[206:209], v[20:23]
	s_barrier
	ds_read_b128 v[104:107], v214
	ds_read_b128 v[108:111], v214 offset:1024
	ds_read_b128 v[112:115], v214 offset:2048
	ds_read_b128 v[116:119], v214 offset:3072
	ds_read_b128 v[120:123], v215
	ds_read_b128 v[124:127], v215 offset:1024
	ds_read_b128 v[152:155], v215 offset:2048
	ds_read_b128 v[156:159], v215 offset:3072
	s_add_u32 s4, s4, 0x10180
	s_addc_u32 s5, s5, 0
	s_mov_b32 m0, s74
	ds_read_b128 v[166:169], v193
	ds_read_b128 v[170:173], v193 offset:1024
	ds_read_b128 v[178:181], v193 offset:2048
	ds_read_b128 v[186:189], v193 offset:3072
	ds_read_b128 v[194:197], v193 offset:4096
	ds_read_b128 v[198:201], v193 offset:5120
	ds_read_b128 v[202:205], v193 offset:6144
	ds_read_b128 v[206:209], v193 offset:7168
	global_load_lds_dwordx4 v164, s[4:5]
	s_mov_b32 m0, s6
	s_nop 0
	global_load_lds_dwordx4 v162, s[4:5]
	s_waitcnt vmcnt(8)
	s_waitcnt lgkmcnt(0)
	s_barrier
	s_waitcnt lgkmcnt(0)
	v_mfma_f32_16x16x32_bf16 v[64:67], v[104:107], v[166:169], v[64:67]
	v_mfma_f32_16x16x32_bf16 v[68:71], v[112:115], v[166:169], v[68:71]
	v_mfma_f32_16x16x32_bf16 v[72:75], v[104:107], v[178:181], v[72:75]
	v_mfma_f32_16x16x32_bf16 v[76:79], v[112:115], v[178:181], v[76:79]
	v_mfma_f32_16x16x32_bf16 v[80:83], v[104:107], v[194:197], v[80:83]
	v_mfma_f32_16x16x32_bf16 v[84:87], v[112:115], v[194:197], v[84:87]
	v_mfma_f32_16x16x32_bf16 v[88:91], v[104:107], v[202:205], v[88:91]
	v_mfma_f32_16x16x32_bf16 v[64:67], v[108:111], v[170:173], v[64:67]
	v_mfma_f32_16x16x32_bf16 v[68:71], v[116:119], v[170:173], v[68:71]
	v_mfma_f32_16x16x32_bf16 v[72:75], v[108:111], v[186:189], v[72:75]
	v_mfma_f32_16x16x32_bf16 v[76:79], v[116:119], v[186:189], v[76:79]
	v_mfma_f32_16x16x32_bf16 v[80:83], v[108:111], v[198:201], v[80:83]
	v_mfma_f32_16x16x32_bf16 v[84:87], v[116:119], v[198:201], v[84:87]
	v_mfma_f32_16x16x32_bf16 v[210:213], v[108:111], v[206:209], v[88:91]
	v_mfma_f32_16x16x32_bf16 v[88:91], v[112:115], v[202:205], v[92:95]
	v_mfma_f32_16x16x32_bf16 v[214:217], v[116:119], v[206:209], v[88:91]
	v_mfma_f32_16x16x32_bf16 v[32:35], v[152:155], v[166:169], v[32:35]
	v_mfma_f32_16x16x32_bf16 v[36:39], v[120:123], v[178:181], v[36:39]
	v_mfma_f32_16x16x32_bf16 v[40:43], v[152:155], v[178:181], v[40:43]
	v_mfma_f32_16x16x32_bf16 v[44:47], v[120:123], v[194:197], v[44:47]
	v_mfma_f32_16x16x32_bf16 v[48:51], v[152:155], v[194:197], v[48:51]
	v_mfma_f32_16x16x32_bf16 v[52:55], v[120:123], v[202:205], v[52:55]
	v_mfma_f32_16x16x32_bf16 v[56:59], v[152:155], v[202:205], v[56:59]
	v_mfma_f32_16x16x32_bf16 v[88:91], v[120:123], v[166:169], v[96:99]
	v_mfma_f32_16x16x32_bf16 v[32:35], v[156:159], v[170:173], v[32:35]
	v_mfma_f32_16x16x32_bf16 v[36:39], v[124:127], v[186:189], v[36:39]
	v_mfma_f32_16x16x32_bf16 v[40:43], v[156:159], v[186:189], v[40:43]
	v_mfma_f32_16x16x32_bf16 v[44:47], v[124:127], v[198:201], v[44:47]
	v_mfma_f32_16x16x32_bf16 v[48:51], v[156:159], v[198:201], v[48:51]
	v_mfma_f32_16x16x32_bf16 v[52:55], v[124:127], v[206:209], v[52:55]
	v_mfma_f32_16x16x32_bf16 v[56:59], v[156:159], v[206:209], v[56:59]
	v_mfma_f32_16x16x32_bf16 v[96:99], v[124:127], v[170:173], v[88:91]
	s_barrier
	s_mov_b32 m0, s72
	v_lshl_add_u64 v[174:175], s[54:55], 0, v[176:177]
	s_add_u32 s4, s54, 0x10000
	ds_read_b128 v[88:91], v193 offset:16384
	ds_read_b128 v[92:95], v193 offset:17408
	ds_read_b128 v[166:169], v193 offset:18432
	ds_read_b128 v[170:173], v193 offset:19456
	ds_read_b128 v[178:181], v193 offset:20480
	ds_read_b128 v[186:189], v193 offset:21504
	ds_read_b128 v[194:197], v193 offset:22528
	ds_read_b128 v[198:201], v193 offset:23552
	global_load_lds_dwordx4 v176, s[54:55]
	v_lshl_add_u64 v[182:183], s[54:55], 0, v[160:161]
	s_mov_b32 m0, s7
	s_addc_u32 s5, s55, 0
	global_load_lds_dwordx4 v160, s[54:55]
	s_mov_b32 m0, s47
	v_lshl_add_u64 v[242:243], s[56:57], 0, v[162:163]
	global_load_lds_dwordx4 v176, s[4:5]
	s_mov_b32 m0, s49
	s_nop 0
	global_load_lds_dwordx4 v160, s[4:5]
	v_lshl_add_u64 v[190:191], s[56:57], 0, v[164:165]
	s_mov_b32 m0, s62
	s_nop 0
	global_load_lds_dwordx4 v164, s[56:57]
	s_mov_b32 m0, s63
	s_nop 0
	global_load_lds_dwordx4 v162, s[56:57]
	s_waitcnt vmcnt(8)
	s_waitcnt lgkmcnt(0)
	s_barrier
	s_waitcnt lgkmcnt(0)
	v_mfma_f32_16x16x32_bf16 v[132:135], v[112:115], v[88:91], v[132:135]
	v_mfma_f32_16x16x32_bf16 v[202:205], v[116:119], v[92:95], v[132:135]
	v_mfma_f32_16x16x32_bf16 v[132:135], v[104:107], v[166:169], v[136:139]
	v_mfma_f32_16x16x32_bf16 v[136:139], v[108:111], v[170:173], v[132:135]
	v_mfma_f32_16x16x32_bf16 v[132:135], v[112:115], v[166:169], v[140:143]
	v_mfma_f32_16x16x32_bf16 v[206:209], v[116:119], v[170:173], v[132:135]
	v_mfma_f32_16x16x32_bf16 v[132:135], v[104:107], v[178:181], v[144:147]
	v_mfma_f32_16x16x32_bf16 v[0:3], v[104:107], v[194:197], v[0:3]
	v_mfma_f32_16x16x32_bf16 v[4:7], v[112:115], v[194:197], v[4:7]
	v_mfma_f32_16x16x32_bf16 v[128:131], v[104:107], v[88:91], v[128:131]
	v_mfma_f32_16x16x32_bf16 v[218:221], v[108:111], v[186:189], v[132:135]
	v_mfma_f32_16x16x32_bf16 v[132:135], v[112:115], v[178:181], v[148:151]
	v_mfma_f32_16x16x32_bf16 v[0:3], v[108:111], v[198:201], v[0:3]
	v_mfma_f32_16x16x32_bf16 v[4:7], v[116:119], v[198:201], v[4:7]
	v_mfma_f32_16x16x32_bf16 v[128:131], v[108:111], v[92:95], v[128:131]
	v_mfma_f32_16x16x32_bf16 v[222:225], v[116:119], v[186:189], v[132:135]
	v_mfma_f32_16x16x32_bf16 v[8:11], v[120:123], v[88:91], v[8:11]
	v_mfma_f32_16x16x32_bf16 v[108:111], v[124:127], v[92:95], v[8:11]
	v_mfma_f32_16x16x32_bf16 v[8:11], v[152:155], v[88:91], v[12:15]
	v_mfma_f32_16x16x32_bf16 v[226:229], v[156:159], v[92:95], v[8:11]
	v_mfma_f32_16x16x32_bf16 v[8:11], v[120:123], v[166:169], v[24:27]
	v_mfma_f32_16x16x32_bf16 v[230:233], v[124:127], v[170:173], v[8:11]
	v_mfma_f32_16x16x32_bf16 v[8:11], v[152:155], v[166:169], v[28:31]
	v_mfma_f32_16x16x32_bf16 v[166:169], v[156:159], v[170:173], v[8:11]
	v_mfma_f32_16x16x32_bf16 v[8:11], v[120:123], v[178:181], v[60:63]
	v_mfma_f32_16x16x32_bf16 v[170:173], v[124:127], v[186:189], v[8:11]
	v_mfma_f32_16x16x32_bf16 v[8:11], v[152:155], v[178:181], v[100:103]
	v_mfma_f32_16x16x32_bf16 v[178:181], v[156:159], v[186:189], v[8:11]
	v_mfma_f32_16x16x32_bf16 v[8:11], v[120:123], v[194:197], v[16:19]
	v_mfma_f32_16x16x32_bf16 v[120:123], v[124:127], v[198:201], v[8:11]
	v_mfma_f32_16x16x32_bf16 v[8:11], v[152:155], v[194:197], v[20:23]
	v_mfma_f32_16x16x32_bf16 v[124:127], v[156:159], v[198:201], v[8:11]
	s_barrier
	s_nop 4
	ds_read_b128 v[8:11], v234
	ds_read_b128 v[12:15], v234 offset:1024
	ds_read_b128 v[16:19], v234 offset:2048
	ds_read_b128 v[20:23], v234 offset:3072
	ds_read_b128 v[152:155], v235
	ds_read_b128 v[156:159], v235 offset:1024
	ds_read_b128 v[186:189], v235 offset:2048
	ds_read_b128 v[194:197], v235 offset:3072
	s_add_u32 s4, s56, 0x10000
	s_addc_u32 s5, s57, 0
	s_mov_b32 m0, s64
	ds_read_b128 v[24:27], v193 offset:32768
	ds_read_b128 v[28:31], v193 offset:33792
	ds_read_b128 v[60:63], v193 offset:34816
	ds_read_b128 v[100:103], v193 offset:35840
	ds_read_b128 v[198:201], v193 offset:36864
	ds_read_b128 v[234:237], v193 offset:37888
	ds_read_b128 v[238:241], v193 offset:38912
	ds_read_b128 v[248:251], v193 offset:39936
	global_load_lds_dwordx4 v164, s[4:5]
	v_lshl_add_u64 v[88:89], s[4:5], 0, v[162:163]
	s_mov_b32 m0, s65
	s_nop 0
	global_load_lds_dwordx4 v162, s[4:5]
	s_waitcnt vmcnt(8)
	s_waitcnt lgkmcnt(0)
	s_barrier
	s_waitcnt lgkmcnt(0)
	v_mfma_f32_16x16x32_bf16 v[64:67], v[8:11], v[24:27], v[64:67]
	v_mfma_f32_16x16x32_bf16 v[148:151], v[12:15], v[28:31], v[64:67]
	v_mfma_f32_16x16x32_bf16 v[64:67], v[16:19], v[24:27], v[68:71]
	v_mfma_f32_16x16x32_bf16 v[144:147], v[20:23], v[28:31], v[64:67]
	v_mfma_f32_16x16x32_bf16 v[64:67], v[8:11], v[60:63], v[72:75]
	v_mfma_f32_16x16x32_bf16 v[116:119], v[12:15], v[100:103], v[64:67]
	v_mfma_f32_16x16x32_bf16 v[64:67], v[16:19], v[60:63], v[76:79]
	v_mfma_f32_16x16x32_bf16 v[112:115], v[20:23], v[100:103], v[64:67]
	v_mfma_f32_16x16x32_bf16 v[64:67], v[8:11], v[198:201], v[80:83]
	v_mfma_f32_16x16x32_bf16 v[92:95], v[12:15], v[234:237], v[64:67]
	v_mfma_f32_16x16x32_bf16 v[64:67], v[16:19], v[198:201], v[84:87]
	v_mfma_f32_16x16x32_bf16 v[88:91], v[20:23], v[234:237], v[64:67]
	v_mfma_f32_16x16x32_bf16 v[64:67], v[8:11], v[238:241], v[210:213]
	v_mfma_f32_16x16x32_bf16 v[76:79], v[12:15], v[248:251], v[64:67]
	v_mfma_f32_16x16x32_bf16 v[64:67], v[16:19], v[238:241], v[214:217]
	v_mfma_f32_16x16x32_bf16 v[72:75], v[20:23], v[248:251], v[64:67]
	v_mfma_f32_16x16x32_bf16 v[64:67], v[152:155], v[24:27], v[96:99]
	v_mfma_f32_16x16x32_bf16 v[24:27], v[186:189], v[24:27], v[32:35]
	v_mfma_f32_16x16x32_bf16 v[132:135], v[194:197], v[28:31], v[24:27]
	v_mfma_f32_16x16x32_bf16 v[24:27], v[152:155], v[60:63], v[36:39]
	v_mfma_f32_16x16x32_bf16 v[104:107], v[156:159], v[100:103], v[24:27]
	v_mfma_f32_16x16x32_bf16 v[24:27], v[186:189], v[60:63], v[40:43]
	v_mfma_f32_16x16x32_bf16 v[100:103], v[194:197], v[100:103], v[24:27]
	v_mfma_f32_16x16x32_bf16 v[24:27], v[152:155], v[198:201], v[44:47]
	v_mfma_f32_16x16x32_bf16 v[84:87], v[156:159], v[234:237], v[24:27]
	v_mfma_f32_16x16x32_bf16 v[24:27], v[186:189], v[198:201], v[48:51]
	v_mfma_f32_16x16x32_bf16 v[80:83], v[194:197], v[234:237], v[24:27]
	v_mfma_f32_16x16x32_bf16 v[24:27], v[152:155], v[238:241], v[52:55]
	v_mfma_f32_16x16x32_bf16 v[68:71], v[156:159], v[248:251], v[24:27]
	v_mfma_f32_16x16x32_bf16 v[24:27], v[186:189], v[238:241], v[56:59]
	v_mfma_f32_16x16x32_bf16 v[140:143], v[156:159], v[28:31], v[64:67]
	v_mfma_f32_16x16x32_bf16 v[64:67], v[194:197], v[248:251], v[24:27]
	s_barrier
	s_mov_b32 m0, s75
	s_nop 2
	v_lshl_add_u64 v[24:25], v[174:175], 0, s[82:83]
	s_add_u32 s4, s54, 0x10080
	ds_read_b128 v[32:35], v193 offset:49152
	ds_read_b128 v[36:39], v193 offset:50176
	ds_read_b128 v[96:99], v193 offset:51200
	ds_read_b128 v[198:201], v193 offset:52224
	ds_read_b128 v[210:213], v193 offset:53248
	ds_read_b128 v[214:217], v193 offset:54272
	ds_read_b128 v[234:237], v193 offset:55296
	ds_read_b128 v[238:241], v193 offset:56320
	global_load_lds_dwordx4 v[24:25], off
	v_lshl_add_u64 v[24:25], v[182:183], 0, s[82:83]
	s_mov_b32 m0, s73
	s_addc_u32 s5, s55, 0
	global_load_lds_dwordx4 v[24:25], off
	s_mov_b32 m0, s0
	s_nop 0
	global_load_lds_dwordx4 v176, s[4:5]
	s_mov_b32 m0, s1
	s_nop 0
	global_load_lds_dwordx4 v160, s[4:5]
	v_lshl_add_u64 v[24:25], v[190:191], 0, s[82:83]
	s_mov_b32 m0, s68
	s_nop 0
	global_load_lds_dwordx4 v[24:25], off
	v_lshl_add_u64 v[24:25], v[242:243], 0, s[82:83]
	s_mov_b32 m0, s69
	s_nop 0
	global_load_lds_dwordx4 v[24:25], off
	s_waitcnt vmcnt(8)
	s_waitcnt lgkmcnt(0)
	s_barrier
	s_waitcnt lgkmcnt(0)
	v_mfma_f32_16x16x32_bf16 v[24:27], v[8:11], v[32:35], v[128:131]
	v_mfma_f32_16x16x32_bf16 v[60:63], v[12:15], v[36:39], v[24:27]
	v_mfma_f32_16x16x32_bf16 v[24:27], v[16:19], v[32:35], v[202:205]
	v_mfma_f32_16x16x32_bf16 v[56:59], v[20:23], v[36:39], v[24:27]
	v_mfma_f32_16x16x32_bf16 v[24:27], v[8:11], v[96:99], v[136:139]
	v_mfma_f32_16x16x32_bf16 v[44:47], v[12:15], v[198:201], v[24:27]
	v_mfma_f32_16x16x32_bf16 v[24:27], v[16:19], v[96:99], v[206:209]
	v_mfma_f32_16x16x32_bf16 v[40:43], v[20:23], v[198:201], v[24:27]
	v_mfma_f32_16x16x32_bf16 v[24:27], v[8:11], v[210:213], v[218:221]
	v_mfma_f32_16x16x32_bf16 v[0:3], v[8:11], v[234:237], v[0:3]
	v_mfma_f32_16x16x32_bf16 v[28:31], v[12:15], v[214:217], v[24:27]
	v_mfma_f32_16x16x32_bf16 v[24:27], v[16:19], v[210:213], v[222:225]
	v_mfma_f32_16x16x32_bf16 v[12:15], v[12:15], v[238:241], v[0:3]
	v_mfma_f32_16x16x32_bf16 v[0:3], v[16:19], v[234:237], v[4:7]
	v_mfma_f32_16x16x32_bf16 v[24:27], v[20:23], v[214:217], v[24:27]
	v_mfma_f32_16x16x32_bf16 v[8:11], v[20:23], v[238:241], v[0:3]
	v_mfma_f32_16x16x32_bf16 v[0:3], v[152:155], v[32:35], v[108:111]
	v_mfma_f32_16x16x32_bf16 v[52:55], v[156:159], v[36:39], v[0:3]
	v_mfma_f32_16x16x32_bf16 v[0:3], v[186:189], v[32:35], v[226:229]
	v_mfma_f32_16x16x32_bf16 v[48:51], v[194:197], v[36:39], v[0:3]
	v_mfma_f32_16x16x32_bf16 v[0:3], v[152:155], v[96:99], v[230:233]
	v_mfma_f32_16x16x32_bf16 v[36:39], v[156:159], v[198:201], v[0:3]
	v_mfma_f32_16x16x32_bf16 v[0:3], v[186:189], v[96:99], v[166:169]
	v_mfma_f32_16x16x32_bf16 v[32:35], v[194:197], v[198:201], v[0:3]
	v_mfma_f32_16x16x32_bf16 v[0:3], v[152:155], v[210:213], v[170:173]
	v_mfma_f32_16x16x32_bf16 v[20:23], v[156:159], v[214:217], v[0:3]
	v_mfma_f32_16x16x32_bf16 v[0:3], v[186:189], v[210:213], v[178:181]
	v_mfma_f32_16x16x32_bf16 v[16:19], v[194:197], v[214:217], v[0:3]
	v_mfma_f32_16x16x32_bf16 v[0:3], v[152:155], v[234:237], v[120:123]
	v_mfma_f32_16x16x32_bf16 v[4:7], v[156:159], v[238:241], v[0:3]
	v_mfma_f32_16x16x32_bf16 v[0:3], v[186:189], v[234:237], v[124:127]
	v_mfma_f32_16x16x32_bf16 v[0:3], v[194:197], v[238:241], v[0:3]
	s_barrier
	s_andn2_b64 vcc, exec, s[38:39]
	s_cbranch_vccnz .LBB0_591
	s_barrier

.LBB0_662:
	s_add_u32 s0, s44, 0xfffc0080
	s_addc_u32 s1, s45, -1
	s_add_i32 s87, 0, 0x10000
	s_cmp_eq_u32 s86, 12
	s_cselect_b32 s5, s6, s1
	s_cselect_b32 s4, s7, s0
	s_cselect_b32 s1, s41, s75
	s_cselect_b32 s0, s53, s74
	s_add_i32 s90, 0, 0x14000
	v_add_u32_e32 v140, s87, v162
	v_add_u32_e32 v168, s90, v162
	ds_read_b128 v[128:131], v140
	ds_read_b128 v[132:135], v140 offset:1024
	ds_read_b128 v[136:139], v140 offset:2048
	ds_read_b128 v[140:143], v140 offset:3072
	ds_read_b128 v[154:157], v168
	ds_read_b128 v[158:161], v168 offset:1024
	ds_read_b128 v[164:167], v168 offset:2048
	ds_read_b128 v[168:171], v168 offset:3072
	s_add_i32 m0, s62, 0xc000
	ds_read_b128 v[172:175], v163
	ds_read_b128 v[178:181], v163 offset:1024
	ds_read_b128 v[186:189], v163 offset:2048
	ds_read_b128 v[190:193], v163 offset:3072
	ds_read_b128 v[194:197], v163 offset:4096
	ds_read_b128 v[198:201], v163 offset:5120
	ds_read_b128 v[202:205], v163 offset:6144
	ds_read_b128 v[206:209], v163 offset:7168
	global_load_lds_dwordx4 v150, s[44:45]
	s_add_i32 m0, s62, 0xe000
	s_nop 0
	global_load_lds_dwordx4 v152, s[44:45]
	s_waitcnt vmcnt(8)
	s_waitcnt lgkmcnt(0)
	s_barrier
	s_waitcnt lgkmcnt(0)
	v_mfma_f32_16x16x32_bf16 v[124:127], v[128:131], v[172:175], v[124:127]
	v_mfma_f32_16x16x32_bf16 v[120:123], v[136:139], v[172:175], v[120:123]
	v_mfma_f32_16x16x32_bf16 v[108:111], v[128:131], v[186:189], v[108:111]
	v_mfma_f32_16x16x32_bf16 v[104:107], v[136:139], v[186:189], v[104:107]
	v_mfma_f32_16x16x32_bf16 v[92:95], v[128:131], v[194:197], v[92:95]
	v_mfma_f32_16x16x32_bf16 v[88:91], v[136:139], v[194:197], v[88:91]
	v_mfma_f32_16x16x32_bf16 v[76:79], v[128:131], v[202:205], v[76:79]
	v_mfma_f32_16x16x32_bf16 v[72:75], v[136:139], v[202:205], v[72:75]
	v_mfma_f32_16x16x32_bf16 v[124:127], v[132:135], v[178:181], v[124:127]
	v_mfma_f32_16x16x32_bf16 v[120:123], v[140:143], v[178:181], v[120:123]
	v_mfma_f32_16x16x32_bf16 v[108:111], v[132:135], v[190:193], v[108:111]
	v_mfma_f32_16x16x32_bf16 v[104:107], v[140:143], v[190:193], v[104:107]
	v_mfma_f32_16x16x32_bf16 v[92:95], v[132:135], v[198:201], v[92:95]
	v_mfma_f32_16x16x32_bf16 v[88:91], v[140:143], v[198:201], v[88:91]
	v_mfma_f32_16x16x32_bf16 v[76:79], v[132:135], v[206:209], v[76:79]
	v_mfma_f32_16x16x32_bf16 v[72:75], v[140:143], v[206:209], v[72:75]
	v_mfma_f32_16x16x32_bf16 v[116:119], v[154:157], v[172:175], v[116:119]
	v_mfma_f32_16x16x32_bf16 v[112:115], v[164:167], v[172:175], v[112:115]
	v_mfma_f32_16x16x32_bf16 v[100:103], v[154:157], v[186:189], v[100:103]
	v_mfma_f32_16x16x32_bf16 v[96:99], v[164:167], v[186:189], v[96:99]
	v_mfma_f32_16x16x32_bf16 v[84:87], v[154:157], v[194:197], v[84:87]
	v_mfma_f32_16x16x32_bf16 v[80:83], v[164:167], v[194:197], v[80:83]
	v_mfma_f32_16x16x32_bf16 v[68:71], v[154:157], v[202:205], v[68:71]
	v_mfma_f32_16x16x32_bf16 v[64:67], v[164:167], v[202:205], v[64:67]
	v_mfma_f32_16x16x32_bf16 v[116:119], v[158:161], v[178:181], v[116:119]
	v_mfma_f32_16x16x32_bf16 v[112:115], v[168:171], v[178:181], v[112:115]
	v_mfma_f32_16x16x32_bf16 v[100:103], v[158:161], v[190:193], v[100:103]
	v_mfma_f32_16x16x32_bf16 v[96:99], v[168:171], v[190:193], v[96:99]
	v_mfma_f32_16x16x32_bf16 v[84:87], v[158:161], v[198:201], v[84:87]
	v_mfma_f32_16x16x32_bf16 v[80:83], v[168:171], v[198:201], v[80:83]
	v_mfma_f32_16x16x32_bf16 v[68:71], v[158:161], v[206:209], v[68:71]
	v_mfma_f32_16x16x32_bf16 v[64:67], v[168:171], v[206:209], v[64:67]
	s_barrier
	s_add_i32 s87, s87, s61
	v_lshl_add_u64 v[182:183], s[0:1], 0, v[176:177]
	s_mov_b32 m0, s87
	ds_read_b128 v[172:175], v163 offset:16384
	ds_read_b128 v[178:181], v163 offset:17408
	ds_read_b128 v[186:189], v163 offset:18432
	ds_read_b128 v[190:193], v163 offset:19456
	ds_read_b128 v[194:197], v163 offset:20480
	ds_read_b128 v[198:201], v163 offset:21504
	ds_read_b128 v[202:205], v163 offset:22528
	ds_read_b128 v[206:209], v163 offset:23552
	global_load_lds_dwordx4 v176, s[0:1]
	s_add_i32 m0, s87, 0x2000
	s_add_u32 s88, s0, 0x40000
	v_lshl_add_u64 v[210:211], s[0:1], 0, v[144:145]
	s_addc_u32 s89, s1, 0
	s_add_i32 s87, s90, s61
	global_load_lds_dwordx4 v144, s[0:1]
	s_mov_b32 m0, s87
	v_lshl_add_u64 v[214:215], s[4:5], 0, v[146:147]
	global_load_lds_dwordx4 v176, s[88:89]
	s_add_i32 m0, s87, 0x2000
	s_nop 0
	global_load_lds_dwordx4 v144, s[88:89]
	v_lshl_add_u64 v[212:213], s[4:5], 0, v[148:149]
	s_mov_b32 m0, s62
	s_nop 0
	global_load_lds_dwordx4 v148, s[4:5]
	s_mov_b32 m0, s63
	s_nop 0
	global_load_lds_dwordx4 v146, s[4:5]
	s_waitcnt vmcnt(8)
	s_waitcnt lgkmcnt(0)
	s_barrier
	s_waitcnt lgkmcnt(0)
	v_mfma_f32_16x16x32_bf16 v[60:63], v[128:131], v[172:175], v[60:63]
	v_mfma_f32_16x16x32_bf16 v[56:59], v[136:139], v[172:175], v[56:59]
	v_mfma_f32_16x16x32_bf16 v[44:47], v[128:131], v[186:189], v[44:47]
	v_mfma_f32_16x16x32_bf16 v[40:43], v[136:139], v[186:189], v[40:43]
	v_mfma_f32_16x16x32_bf16 v[28:31], v[128:131], v[194:197], v[28:31]
	v_mfma_f32_16x16x32_bf16 v[24:27], v[136:139], v[194:197], v[24:27]
	v_mfma_f32_16x16x32_bf16 v[12:15], v[128:131], v[202:205], v[12:15]
	v_mfma_f32_16x16x32_bf16 v[8:11], v[136:139], v[202:205], v[8:11]
	v_mfma_f32_16x16x32_bf16 v[60:63], v[132:135], v[178:181], v[60:63]
	v_mfma_f32_16x16x32_bf16 v[56:59], v[140:143], v[178:181], v[56:59]
	v_mfma_f32_16x16x32_bf16 v[44:47], v[132:135], v[190:193], v[44:47]
	v_mfma_f32_16x16x32_bf16 v[40:43], v[140:143], v[190:193], v[40:43]
	v_mfma_f32_16x16x32_bf16 v[28:31], v[132:135], v[198:201], v[28:31]
	v_mfma_f32_16x16x32_bf16 v[24:27], v[140:143], v[198:201], v[24:27]
	v_mfma_f32_16x16x32_bf16 v[12:15], v[132:135], v[206:209], v[12:15]
	v_mfma_f32_16x16x32_bf16 v[8:11], v[140:143], v[206:209], v[8:11]
	v_mfma_f32_16x16x32_bf16 v[52:55], v[154:157], v[172:175], v[52:55]
	v_mfma_f32_16x16x32_bf16 v[48:51], v[164:167], v[172:175], v[48:51]
	v_mfma_f32_16x16x32_bf16 v[36:39], v[154:157], v[186:189], v[36:39]
	v_mfma_f32_16x16x32_bf16 v[32:35], v[164:167], v[186:189], v[32:35]
	v_mfma_f32_16x16x32_bf16 v[20:23], v[154:157], v[194:197], v[20:23]
	v_mfma_f32_16x16x32_bf16 v[16:19], v[164:167], v[194:197], v[16:19]
	v_mfma_f32_16x16x32_bf16 v[4:7], v[154:157], v[202:205], v[4:7]
	v_mfma_f32_16x16x32_bf16 v[0:3], v[164:167], v[202:205], v[0:3]
	v_mfma_f32_16x16x32_bf16 v[52:55], v[158:161], v[178:181], v[52:55]
	v_mfma_f32_16x16x32_bf16 v[48:51], v[168:171], v[178:181], v[48:51]
	v_mfma_f32_16x16x32_bf16 v[36:39], v[158:161], v[190:193], v[36:39]
	v_mfma_f32_16x16x32_bf16 v[32:35], v[168:171], v[190:193], v[32:35]
	v_mfma_f32_16x16x32_bf16 v[20:23], v[158:161], v[198:201], v[20:23]
	v_mfma_f32_16x16x32_bf16 v[16:19], v[168:171], v[198:201], v[16:19]
	v_mfma_f32_16x16x32_bf16 v[4:7], v[158:161], v[206:209], v[4:7]
	v_mfma_f32_16x16x32_bf16 v[0:3], v[168:171], v[206:209], v[0:3]
	s_barrier
	s_add_i32 s87, 0, 0x18000
	s_add_i32 s88, 0, 0x1c000
	v_add_u32_e32 v140, s87, v162
	v_add_u32_e32 v168, s88, v162
	ds_read_b128 v[128:131], v140
	ds_read_b128 v[132:135], v140 offset:1024
	ds_read_b128 v[136:139], v140 offset:2048
	ds_read_b128 v[140:143], v140 offset:3072
	ds_read_b128 v[154:157], v168
	ds_read_b128 v[158:161], v168 offset:1024
	ds_read_b128 v[164:167], v168 offset:2048
	ds_read_b128 v[168:171], v168 offset:3072
	s_add_u32 s4, s4, 0x40000
	s_addc_u32 s5, s5, 0
	s_mov_b32 m0, s64
	ds_read_b128 v[172:175], v163 offset:32768
	ds_read_b128 v[178:181], v163 offset:33792
	ds_read_b128 v[186:189], v163 offset:34816
	ds_read_b128 v[190:193], v163 offset:35840
	ds_read_b128 v[194:197], v163 offset:36864
	ds_read_b128 v[198:201], v163 offset:37888
	ds_read_b128 v[202:205], v163 offset:38912
	ds_read_b128 v[206:209], v163 offset:39936
	global_load_lds_dwordx4 v148, s[4:5]
	s_mov_b32 m0, s65
	s_nop 0
	global_load_lds_dwordx4 v146, s[4:5]
	s_waitcnt vmcnt(8)
	s_waitcnt lgkmcnt(0)
	s_barrier
	s_waitcnt lgkmcnt(0)
	v_mfma_f32_16x16x32_bf16 v[124:127], v[128:131], v[172:175], v[124:127]
	v_mfma_f32_16x16x32_bf16 v[120:123], v[136:139], v[172:175], v[120:123]
	v_mfma_f32_16x16x32_bf16 v[108:111], v[128:131], v[186:189], v[108:111]
	v_mfma_f32_16x16x32_bf16 v[104:107], v[136:139], v[186:189], v[104:107]
	v_mfma_f32_16x16x32_bf16 v[92:95], v[128:131], v[194:197], v[92:95]
	v_mfma_f32_16x16x32_bf16 v[88:91], v[136:139], v[194:197], v[88:91]
	v_mfma_f32_16x16x32_bf16 v[76:79], v[128:131], v[202:205], v[76:79]
	v_mfma_f32_16x16x32_bf16 v[72:75], v[136:139], v[202:205], v[72:75]
	v_mfma_f32_16x16x32_bf16 v[124:127], v[132:135], v[178:181], v[124:127]
	v_mfma_f32_16x16x32_bf16 v[120:123], v[140:143], v[178:181], v[120:123]
	v_mfma_f32_16x16x32_bf16 v[108:111], v[132:135], v[190:193], v[108:111]
	v_mfma_f32_16x16x32_bf16 v[104:107], v[140:143], v[190:193], v[104:107]
	v_mfma_f32_16x16x32_bf16 v[92:95], v[132:135], v[198:201], v[92:95]
	v_mfma_f32_16x16x32_bf16 v[88:91], v[140:143], v[198:201], v[88:91]
	v_mfma_f32_16x16x32_bf16 v[76:79], v[132:135], v[206:209], v[76:79]
	v_mfma_f32_16x16x32_bf16 v[72:75], v[140:143], v[206:209], v[72:75]
	v_mfma_f32_16x16x32_bf16 v[116:119], v[154:157], v[172:175], v[116:119]
	v_mfma_f32_16x16x32_bf16 v[112:115], v[164:167], v[172:175], v[112:115]
	v_mfma_f32_16x16x32_bf16 v[100:103], v[154:157], v[186:189], v[100:103]
	v_mfma_f32_16x16x32_bf16 v[96:99], v[164:167], v[186:189], v[96:99]
	v_mfma_f32_16x16x32_bf16 v[84:87], v[154:157], v[194:197], v[84:87]
	v_mfma_f32_16x16x32_bf16 v[80:83], v[164:167], v[194:197], v[80:83]
	v_mfma_f32_16x16x32_bf16 v[68:71], v[154:157], v[202:205], v[68:71]
	v_mfma_f32_16x16x32_bf16 v[64:67], v[164:167], v[202:205], v[64:67]
	v_mfma_f32_16x16x32_bf16 v[116:119], v[158:161], v[178:181], v[116:119]
	v_mfma_f32_16x16x32_bf16 v[112:115], v[168:171], v[178:181], v[112:115]
	v_mfma_f32_16x16x32_bf16 v[100:103], v[158:161], v[190:193], v[100:103]
	v_mfma_f32_16x16x32_bf16 v[96:99], v[168:171], v[190:193], v[96:99]
	v_mfma_f32_16x16x32_bf16 v[84:87], v[158:161], v[198:201], v[84:87]
	v_mfma_f32_16x16x32_bf16 v[80:83], v[168:171], v[198:201], v[80:83]
	v_mfma_f32_16x16x32_bf16 v[68:71], v[158:161], v[206:209], v[68:71]
	v_mfma_f32_16x16x32_bf16 v[64:67], v[168:171], v[206:209], v[64:67]
	s_barrier
	s_add_i32 s4, s87, s61
	v_lshl_add_u64 v[182:183], v[182:183], 0, s[82:83]
	s_mov_b32 m0, s4
	ds_read_b128 v[172:175], v163 offset:49152
	ds_read_b128 v[178:181], v163 offset:50176
	ds_read_b128 v[186:189], v163 offset:51200
	ds_read_b128 v[190:193], v163 offset:52224
	ds_read_b128 v[194:197], v163 offset:53248
	ds_read_b128 v[198:201], v163 offset:54272
	ds_read_b128 v[202:205], v163 offset:55296
	ds_read_b128 v[206:209], v163 offset:56320
	global_load_lds_dwordx4 v[182:183], off
	s_add_i32 m0, s4, 0x2000
	s_add_u32 s0, s0, 0x40080
	v_lshl_add_u64 v[182:183], v[210:211], 0, s[82:83]
	s_addc_u32 s1, s1, 0
	s_add_i32 s4, s88, s61
	global_load_lds_dwordx4 v[182:183], off
	s_mov_b32 m0, s4
	s_nop 0
	global_load_lds_dwordx4 v176, s[0:1]
	s_add_i32 m0, s4, 0x2000
	s_nop 0
	global_load_lds_dwordx4 v144, s[0:1]
	v_lshl_add_u64 v[182:183], v[212:213], 0, s[82:83]
	s_mov_b32 m0, s69
	s_nop 0
	global_load_lds_dwordx4 v[182:183], off
	v_lshl_add_u64 v[182:183], v[214:215], 0, s[82:83]
	s_mov_b32 m0, s70
	s_nop 0
	global_load_lds_dwordx4 v[182:183], off
	s_waitcnt vmcnt(8)
	s_waitcnt lgkmcnt(0)
	s_barrier
	s_waitcnt lgkmcnt(0)
	v_mfma_f32_16x16x32_bf16 v[60:63], v[128:131], v[172:175], v[60:63]
	v_mfma_f32_16x16x32_bf16 v[56:59], v[136:139], v[172:175], v[56:59]
	v_mfma_f32_16x16x32_bf16 v[44:47], v[128:131], v[186:189], v[44:47]
	v_mfma_f32_16x16x32_bf16 v[40:43], v[136:139], v[186:189], v[40:43]
	v_mfma_f32_16x16x32_bf16 v[28:31], v[128:131], v[194:197], v[28:31]
	v_mfma_f32_16x16x32_bf16 v[24:27], v[136:139], v[194:197], v[24:27]
	v_mfma_f32_16x16x32_bf16 v[12:15], v[128:131], v[202:205], v[12:15]
	v_mfma_f32_16x16x32_bf16 v[8:11], v[136:139], v[202:205], v[8:11]
	v_mfma_f32_16x16x32_bf16 v[60:63], v[132:135], v[178:181], v[60:63]
	v_mfma_f32_16x16x32_bf16 v[56:59], v[140:143], v[178:181], v[56:59]
	v_mfma_f32_16x16x32_bf16 v[44:47], v[132:135], v[190:193], v[44:47]
	v_mfma_f32_16x16x32_bf16 v[40:43], v[140:143], v[190:193], v[40:43]
	v_mfma_f32_16x16x32_bf16 v[28:31], v[132:135], v[198:201], v[28:31]
	v_mfma_f32_16x16x32_bf16 v[24:27], v[140:143], v[198:201], v[24:27]
	v_mfma_f32_16x16x32_bf16 v[12:15], v[132:135], v[206:209], v[12:15]
	v_mfma_f32_16x16x32_bf16 v[8:11], v[140:143], v[206:209], v[8:11]
	v_mfma_f32_16x16x32_bf16 v[52:55], v[154:157], v[172:175], v[52:55]
	v_mfma_f32_16x16x32_bf16 v[48:51], v[164:167], v[172:175], v[48:51]
	v_mfma_f32_16x16x32_bf16 v[36:39], v[154:157], v[186:189], v[36:39]
	v_mfma_f32_16x16x32_bf16 v[32:35], v[164:167], v[186:189], v[32:35]
	v_mfma_f32_16x16x32_bf16 v[20:23], v[154:157], v[194:197], v[20:23]
	v_mfma_f32_16x16x32_bf16 v[16:19], v[164:167], v[194:197], v[16:19]
	v_mfma_f32_16x16x32_bf16 v[4:7], v[154:157], v[202:205], v[4:7]
	v_mfma_f32_16x16x32_bf16 v[0:3], v[164:167], v[202:205], v[0:3]
	v_mfma_f32_16x16x32_bf16 v[52:55], v[158:161], v[178:181], v[52:55]
	v_mfma_f32_16x16x32_bf16 v[48:51], v[168:171], v[178:181], v[48:51]
	v_mfma_f32_16x16x32_bf16 v[36:39], v[158:161], v[190:193], v[36:39]
	v_mfma_f32_16x16x32_bf16 v[32:35], v[168:171], v[190:193], v[32:35]
	v_mfma_f32_16x16x32_bf16 v[20:23], v[158:161], v[198:201], v[20:23]
	v_mfma_f32_16x16x32_bf16 v[16:19], v[168:171], v[198:201], v[16:19]
	v_mfma_f32_16x16x32_bf16 v[4:7], v[158:161], v[206:209], v[4:7]
	v_mfma_f32_16x16x32_bf16 v[0:3], v[168:171], v[206:209], v[0:3]
	s_barrier
	s_add_i32 s86, s86, 2
	s_add_u32 s44, s44, 0x100
	s_addc_u32 s45, s45, 0
	s_add_u32 s74, s74, 0x100
	s_addc_u32 s75, s75, 0
	s_cmp_gt_u32 s86, 13
	s_cbranch_scc0 .LBB0_662
	s_and_b64 vcc, exec, s[38:39]
	s_cbranch_vccz .LBB0_665
	s_barrier

.Lpeel_748:
	s_add_u32 s0, s44, 0xfffc0080
	s_addc_u32 s1, s45, -1
	s_add_i32 s74, 0, 0x10000
	s_cmp_eq_u32 s73, 12
	s_cselect_b32 s5, s6, s1
	s_cselect_b32 s4, s7, s0
	s_cselect_b32 s1, s39, s72
	s_cselect_b32 s0, s41, s49
	s_add_i32 s92, 0, 0x14000
	v_add_u32_e32 v124, s74, v199
	v_add_u32_e32 v140, s92, v199
	ds_read_b128 v[112:115], v124
	ds_read_b128 v[116:119], v124 offset:1024
	ds_read_b128 v[120:123], v124 offset:2048
	ds_read_b128 v[124:127], v124 offset:3072
	ds_read_b128 v[128:131], v140
	ds_read_b128 v[132:135], v140 offset:1024
	ds_read_b128 v[136:139], v140 offset:2048
	ds_read_b128 v[140:143], v140 offset:3072
	s_add_i32 m0, s63, 0xc000
	ds_read_b128 v[172:175], v207
	ds_read_b128 v[178:181], v207 offset:1024
	ds_read_b128 v[186:189], v207 offset:2048
	ds_read_b128 v[190:193], v207 offset:3072
	ds_read_b128 v[194:197], v207 offset:4096
	ds_read_b128 v[200:203], v207 offset:5120
	ds_read_b128 v[208:211], v207 offset:6144
	ds_read_b128 v[212:215], v207 offset:7168
	global_load_lds_dwordx4 v168, s[44:45]
	s_add_i32 m0, s63, 0xe000
	s_nop 0
	global_load_lds_dwordx4 v170, s[44:45]
	s_waitcnt vmcnt(8)
	s_waitcnt lgkmcnt(0)
	s_barrier
	s_waitcnt lgkmcnt(0)
	v_mfma_f32_16x16x32_bf16 v[156:159], v[112:115], v[172:175], 0
	v_mfma_f32_16x16x32_bf16 v[152:155], v[120:123], v[172:175], 0
	v_mfma_f32_16x16x32_bf16 v[108:111], v[112:115], v[186:189], 0
	v_mfma_f32_16x16x32_bf16 v[100:103], v[120:123], v[186:189], 0
	v_mfma_f32_16x16x32_bf16 v[92:95], v[112:115], v[194:197], 0
	v_mfma_f32_16x16x32_bf16 v[84:87], v[120:123], v[194:197], 0
	v_mfma_f32_16x16x32_bf16 v[76:79], v[112:115], v[208:211], 0
	v_mfma_f32_16x16x32_bf16 v[68:71], v[120:123], v[208:211], 0
	v_mfma_f32_16x16x32_bf16 v[156:159], v[116:119], v[178:181], v[156:159]
	v_mfma_f32_16x16x32_bf16 v[152:155], v[124:127], v[178:181], v[152:155]
	v_mfma_f32_16x16x32_bf16 v[108:111], v[116:119], v[190:193], v[108:111]
	v_mfma_f32_16x16x32_bf16 v[100:103], v[124:127], v[190:193], v[100:103]
	v_mfma_f32_16x16x32_bf16 v[92:95], v[116:119], v[200:203], v[92:95]
	v_mfma_f32_16x16x32_bf16 v[84:87], v[124:127], v[200:203], v[84:87]
	v_mfma_f32_16x16x32_bf16 v[76:79], v[116:119], v[212:215], v[76:79]
	v_mfma_f32_16x16x32_bf16 v[68:71], v[124:127], v[212:215], v[68:71]
	v_mfma_f32_16x16x32_bf16 v[148:151], v[128:131], v[172:175], 0
	v_mfma_f32_16x16x32_bf16 v[144:147], v[136:139], v[172:175], 0
	v_mfma_f32_16x16x32_bf16 v[104:107], v[128:131], v[186:189], 0
	v_mfma_f32_16x16x32_bf16 v[96:99], v[136:139], v[186:189], 0
	v_mfma_f32_16x16x32_bf16 v[88:91], v[128:131], v[194:197], 0
	v_mfma_f32_16x16x32_bf16 v[80:83], v[136:139], v[194:197], 0
	v_mfma_f32_16x16x32_bf16 v[72:75], v[128:131], v[208:211], 0
	v_mfma_f32_16x16x32_bf16 v[64:67], v[136:139], v[208:211], 0
	v_mfma_f32_16x16x32_bf16 v[148:151], v[132:135], v[178:181], v[148:151]
	v_mfma_f32_16x16x32_bf16 v[144:147], v[140:143], v[178:181], v[144:147]
	v_mfma_f32_16x16x32_bf16 v[104:107], v[132:135], v[190:193], v[104:107]
	v_mfma_f32_16x16x32_bf16 v[96:99], v[140:143], v[190:193], v[96:99]
	v_mfma_f32_16x16x32_bf16 v[88:91], v[132:135], v[200:203], v[88:91]
	v_mfma_f32_16x16x32_bf16 v[80:83], v[140:143], v[200:203], v[80:83]
	v_mfma_f32_16x16x32_bf16 v[72:75], v[132:135], v[212:215], v[72:75]
	v_mfma_f32_16x16x32_bf16 v[64:67], v[140:143], v[212:215], v[64:67]
	s_barrier
	s_add_i32 s74, s74, s62
	v_lshl_add_u64 v[182:183], s[0:1], 0, v[164:165]
	s_mov_b32 m0, s74
	ds_read_b128 v[172:175], v207 offset:16384
	ds_read_b128 v[178:181], v207 offset:17408
	ds_read_b128 v[186:189], v207 offset:18432
	ds_read_b128 v[190:193], v207 offset:19456
	ds_read_b128 v[194:197], v207 offset:20480
	ds_read_b128 v[200:203], v207 offset:21504
	ds_read_b128 v[208:211], v207 offset:22528
	ds_read_b128 v[212:215], v207 offset:23552
	global_load_lds_dwordx4 v164, s[0:1]
	s_add_i32 m0, s74, 0x2000
	s_add_u32 s74, s0, 0x40000
	v_lshl_add_u64 v[204:205], s[0:1], 0, v[160:161]
	s_addc_u32 s75, s1, 0
	s_add_i32 s92, s92, s62
	global_load_lds_dwordx4 v160, s[0:1]
	s_mov_b32 m0, s92
	v_lshl_add_u64 v[218:219], s[4:5], 0, v[162:163]
	global_load_lds_dwordx4 v164, s[74:75]
	s_add_i32 m0, s92, 0x2000
	s_nop 0
	global_load_lds_dwordx4 v160, s[74:75]
	v_lshl_add_u64 v[216:217], s[4:5], 0, v[166:167]
	s_mov_b32 m0, s63
	s_nop 0
	global_load_lds_dwordx4 v166, s[4:5]
	s_mov_b32 m0, s64
	s_nop 0
	global_load_lds_dwordx4 v162, s[4:5]
	s_waitcnt vmcnt(8)
	s_waitcnt lgkmcnt(0)
	s_barrier
	s_waitcnt lgkmcnt(0)
	v_mfma_f32_16x16x32_bf16 v[60:63], v[112:115], v[172:175], 0
	v_mfma_f32_16x16x32_bf16 v[56:59], v[120:123], v[172:175], 0
	v_mfma_f32_16x16x32_bf16 v[44:47], v[112:115], v[186:189], 0
	v_mfma_f32_16x16x32_bf16 v[36:39], v[120:123], v[186:189], 0
	v_mfma_f32_16x16x32_bf16 v[28:31], v[112:115], v[194:197], 0
	v_mfma_f32_16x16x32_bf16 v[20:23], v[120:123], v[194:197], 0
	v_mfma_f32_16x16x32_bf16 v[12:15], v[112:115], v[208:211], 0
	v_mfma_f32_16x16x32_bf16 v[4:7], v[120:123], v[208:211], 0
	v_mfma_f32_16x16x32_bf16 v[60:63], v[116:119], v[178:181], v[60:63]
	v_mfma_f32_16x16x32_bf16 v[56:59], v[124:127], v[178:181], v[56:59]
	v_mfma_f32_16x16x32_bf16 v[44:47], v[116:119], v[190:193], v[44:47]
	v_mfma_f32_16x16x32_bf16 v[36:39], v[124:127], v[190:193], v[36:39]
	v_mfma_f32_16x16x32_bf16 v[28:31], v[116:119], v[200:203], v[28:31]
	v_mfma_f32_16x16x32_bf16 v[20:23], v[124:127], v[200:203], v[20:23]
	v_mfma_f32_16x16x32_bf16 v[12:15], v[116:119], v[212:215], v[12:15]
	v_mfma_f32_16x16x32_bf16 v[4:7], v[124:127], v[212:215], v[4:7]
	v_mfma_f32_16x16x32_bf16 v[52:55], v[128:131], v[172:175], 0
	v_mfma_f32_16x16x32_bf16 v[48:51], v[136:139], v[172:175], 0
	v_mfma_f32_16x16x32_bf16 v[40:43], v[128:131], v[186:189], 0
	v_mfma_f32_16x16x32_bf16 v[32:35], v[136:139], v[186:189], 0
	v_mfma_f32_16x16x32_bf16 v[24:27], v[128:131], v[194:197], 0
	v_mfma_f32_16x16x32_bf16 v[16:19], v[136:139], v[194:197], 0
	v_mfma_f32_16x16x32_bf16 v[8:11], v[128:131], v[208:211], 0
	v_mfma_f32_16x16x32_bf16 v[0:3], v[136:139], v[208:211], 0
	v_mfma_f32_16x16x32_bf16 v[52:55], v[132:135], v[178:181], v[52:55]
	v_mfma_f32_16x16x32_bf16 v[48:51], v[140:143], v[178:181], v[48:51]
	v_mfma_f32_16x16x32_bf16 v[40:43], v[132:135], v[190:193], v[40:43]
	v_mfma_f32_16x16x32_bf16 v[32:35], v[140:143], v[190:193], v[32:35]
	v_mfma_f32_16x16x32_bf16 v[24:27], v[132:135], v[200:203], v[24:27]
	v_mfma_f32_16x16x32_bf16 v[16:19], v[140:143], v[200:203], v[16:19]
	v_mfma_f32_16x16x32_bf16 v[8:11], v[132:135], v[212:215], v[8:11]
	v_mfma_f32_16x16x32_bf16 v[0:3], v[140:143], v[212:215], v[0:3]
	s_barrier
	s_add_i32 s74, 0, 0x18000
	s_add_i32 s75, 0, 0x1c000
	v_add_u32_e32 v124, s74, v199
	v_add_u32_e32 v140, s75, v199
	ds_read_b128 v[112:115], v124
	ds_read_b128 v[116:119], v124 offset:1024
	ds_read_b128 v[120:123], v124 offset:2048
	ds_read_b128 v[124:127], v124 offset:3072
	ds_read_b128 v[128:131], v140
	ds_read_b128 v[132:135], v140 offset:1024
	ds_read_b128 v[136:139], v140 offset:2048
	ds_read_b128 v[140:143], v140 offset:3072
	s_add_u32 s4, s4, 0x40000
	s_addc_u32 s5, s5, 0
	s_mov_b32 m0, s65
	ds_read_b128 v[172:175], v207 offset:32768
	ds_read_b128 v[178:181], v207 offset:33792
	ds_read_b128 v[186:189], v207 offset:34816
	ds_read_b128 v[190:193], v207 offset:35840
	ds_read_b128 v[194:197], v207 offset:36864
	ds_read_b128 v[200:203], v207 offset:37888
	ds_read_b128 v[208:211], v207 offset:38912
	ds_read_b128 v[212:215], v207 offset:39936
	global_load_lds_dwordx4 v166, s[4:5]
	s_mov_b32 m0, s66
	s_nop 0
	global_load_lds_dwordx4 v162, s[4:5]
	s_waitcnt vmcnt(8)
	s_waitcnt lgkmcnt(0)
	s_barrier
	s_waitcnt lgkmcnt(0)
	v_mfma_f32_16x16x32_bf16 v[156:159], v[112:115], v[172:175], v[156:159]
	v_mfma_f32_16x16x32_bf16 v[152:155], v[120:123], v[172:175], v[152:155]
	v_mfma_f32_16x16x32_bf16 v[108:111], v[112:115], v[186:189], v[108:111]
	v_mfma_f32_16x16x32_bf16 v[100:103], v[120:123], v[186:189], v[100:103]
	v_mfma_f32_16x16x32_bf16 v[92:95], v[112:115], v[194:197], v[92:95]
	v_mfma_f32_16x16x32_bf16 v[84:87], v[120:123], v[194:197], v[84:87]
	v_mfma_f32_16x16x32_bf16 v[76:79], v[112:115], v[208:211], v[76:79]
	v_mfma_f32_16x16x32_bf16 v[68:71], v[120:123], v[208:211], v[68:71]
	v_mfma_f32_16x16x32_bf16 v[156:159], v[116:119], v[178:181], v[156:159]
	v_mfma_f32_16x16x32_bf16 v[152:155], v[124:127], v[178:181], v[152:155]
	v_mfma_f32_16x16x32_bf16 v[108:111], v[116:119], v[190:193], v[108:111]
	v_mfma_f32_16x16x32_bf16 v[100:103], v[124:127], v[190:193], v[100:103]
	v_mfma_f32_16x16x32_bf16 v[92:95], v[116:119], v[200:203], v[92:95]
	v_mfma_f32_16x16x32_bf16 v[84:87], v[124:127], v[200:203], v[84:87]
	v_mfma_f32_16x16x32_bf16 v[76:79], v[116:119], v[212:215], v[76:79]
	v_mfma_f32_16x16x32_bf16 v[68:71], v[124:127], v[212:215], v[68:71]
	v_mfma_f32_16x16x32_bf16 v[148:151], v[128:131], v[172:175], v[148:151]
	v_mfma_f32_16x16x32_bf16 v[144:147], v[136:139], v[172:175], v[144:147]
	v_mfma_f32_16x16x32_bf16 v[104:107], v[128:131], v[186:189], v[104:107]
	v_mfma_f32_16x16x32_bf16 v[96:99], v[136:139], v[186:189], v[96:99]
	v_mfma_f32_16x16x32_bf16 v[88:91], v[128:131], v[194:197], v[88:91]
	v_mfma_f32_16x16x32_bf16 v[80:83], v[136:139], v[194:197], v[80:83]
	v_mfma_f32_16x16x32_bf16 v[72:75], v[128:131], v[208:211], v[72:75]
	v_mfma_f32_16x16x32_bf16 v[64:67], v[136:139], v[208:211], v[64:67]
	v_mfma_f32_16x16x32_bf16 v[148:151], v[132:135], v[178:181], v[148:151]
	v_mfma_f32_16x16x32_bf16 v[144:147], v[140:143], v[178:181], v[144:147]
	v_mfma_f32_16x16x32_bf16 v[104:107], v[132:135], v[190:193], v[104:107]
	v_mfma_f32_16x16x32_bf16 v[96:99], v[140:143], v[190:193], v[96:99]
	v_mfma_f32_16x16x32_bf16 v[88:91], v[132:135], v[200:203], v[88:91]
	v_mfma_f32_16x16x32_bf16 v[80:83], v[140:143], v[200:203], v[80:83]
	v_mfma_f32_16x16x32_bf16 v[72:75], v[132:135], v[212:215], v[72:75]
	v_mfma_f32_16x16x32_bf16 v[64:67], v[140:143], v[212:215], v[64:67]
	s_barrier
	s_add_i32 s4, s74, s62
	v_lshl_add_u64 v[182:183], v[182:183], 0, s[82:83]
	s_mov_b32 m0, s4
	ds_read_b128 v[172:175], v207 offset:49152
	ds_read_b128 v[178:181], v207 offset:50176
	ds_read_b128 v[186:189], v207 offset:51200
	ds_read_b128 v[190:193], v207 offset:52224
	ds_read_b128 v[194:197], v207 offset:53248
	ds_read_b128 v[200:203], v207 offset:54272
	ds_read_b128 v[208:211], v207 offset:55296
	ds_read_b128 v[212:215], v207 offset:56320
	global_load_lds_dwordx4 v[182:183], off
	s_add_i32 m0, s4, 0x2000
	s_add_u32 s0, s0, 0x40080
	v_lshl_add_u64 v[182:183], v[204:205], 0, s[82:83]
	s_addc_u32 s1, s1, 0
	s_add_i32 s4, s75, s62
	global_load_lds_dwordx4 v[182:183], off
	s_mov_b32 m0, s4
	s_nop 0
	global_load_lds_dwordx4 v164, s[0:1]
	s_add_i32 m0, s4, 0x2000
	s_nop 0
	global_load_lds_dwordx4 v160, s[0:1]
	v_lshl_add_u64 v[182:183], v[216:217], 0, s[82:83]
	s_mov_b32 m0, s69
	s_nop 0
	global_load_lds_dwordx4 v[182:183], off
	v_lshl_add_u64 v[182:183], v[218:219], 0, s[82:83]
	s_mov_b32 m0, s70
	s_nop 0
	global_load_lds_dwordx4 v[182:183], off
	s_waitcnt vmcnt(8)
	s_waitcnt lgkmcnt(0)
	s_barrier
	s_waitcnt lgkmcnt(0)
	v_mfma_f32_16x16x32_bf16 v[60:63], v[112:115], v[172:175], v[60:63]
	v_mfma_f32_16x16x32_bf16 v[56:59], v[120:123], v[172:175], v[56:59]
	v_mfma_f32_16x16x32_bf16 v[44:47], v[112:115], v[186:189], v[44:47]
	v_mfma_f32_16x16x32_bf16 v[36:39], v[120:123], v[186:189], v[36:39]
	v_mfma_f32_16x16x32_bf16 v[28:31], v[112:115], v[194:197], v[28:31]
	v_mfma_f32_16x16x32_bf16 v[20:23], v[120:123], v[194:197], v[20:23]
	v_mfma_f32_16x16x32_bf16 v[12:15], v[112:115], v[208:211], v[12:15]
	v_mfma_f32_16x16x32_bf16 v[4:7], v[120:123], v[208:211], v[4:7]
	v_mfma_f32_16x16x32_bf16 v[60:63], v[116:119], v[178:181], v[60:63]
	v_mfma_f32_16x16x32_bf16 v[56:59], v[124:127], v[178:181], v[56:59]
	v_mfma_f32_16x16x32_bf16 v[44:47], v[116:119], v[190:193], v[44:47]
	v_mfma_f32_16x16x32_bf16 v[36:39], v[124:127], v[190:193], v[36:39]
	v_mfma_f32_16x16x32_bf16 v[28:31], v[116:119], v[200:203], v[28:31]
	v_mfma_f32_16x16x32_bf16 v[20:23], v[124:127], v[200:203], v[20:23]
	v_mfma_f32_16x16x32_bf16 v[12:15], v[116:119], v[212:215], v[12:15]
	v_mfma_f32_16x16x32_bf16 v[4:7], v[124:127], v[212:215], v[4:7]
	v_mfma_f32_16x16x32_bf16 v[52:55], v[128:131], v[172:175], v[52:55]
	v_mfma_f32_16x16x32_bf16 v[48:51], v[136:139], v[172:175], v[48:51]
	v_mfma_f32_16x16x32_bf16 v[40:43], v[128:131], v[186:189], v[40:43]
	v_mfma_f32_16x16x32_bf16 v[32:35], v[136:139], v[186:189], v[32:35]
	v_mfma_f32_16x16x32_bf16 v[24:27], v[128:131], v[194:197], v[24:27]
	v_mfma_f32_16x16x32_bf16 v[16:19], v[136:139], v[194:197], v[16:19]
	v_mfma_f32_16x16x32_bf16 v[8:11], v[128:131], v[208:211], v[8:11]
	v_mfma_f32_16x16x32_bf16 v[0:3], v[136:139], v[208:211], v[0:3]
	v_mfma_f32_16x16x32_bf16 v[52:55], v[132:135], v[178:181], v[52:55]
	v_mfma_f32_16x16x32_bf16 v[48:51], v[140:143], v[178:181], v[48:51]
	v_mfma_f32_16x16x32_bf16 v[40:43], v[132:135], v[190:193], v[40:43]
	v_mfma_f32_16x16x32_bf16 v[32:35], v[140:143], v[190:193], v[32:35]
	v_mfma_f32_16x16x32_bf16 v[24:27], v[132:135], v[200:203], v[24:27]
	v_mfma_f32_16x16x32_bf16 v[16:19], v[140:143], v[200:203], v[16:19]
	v_mfma_f32_16x16x32_bf16 v[8:11], v[132:135], v[212:215], v[8:11]
	v_mfma_f32_16x16x32_bf16 v[0:3], v[140:143], v[212:215], v[0:3]
	s_barrier
	s_add_i32 s73, s73, 2
	s_add_u32 s44, s44, 0x100
	s_addc_u32 s45, s45, 0
	s_add_u32 s49, s49, 0x100
	s_addc_u32 s72, s72, 0
	s_cmp_gt_u32 s73, 13
.LBB0_748:
	s_add_u32 s0, s44, 0xfffc0080
	s_addc_u32 s1, s45, -1
	s_add_i32 s74, 0, 0x10000
	s_cmp_eq_u32 s73, 12
	s_cselect_b32 s5, s6, s1
	s_cselect_b32 s4, s7, s0
	s_cselect_b32 s1, s39, s72
	s_cselect_b32 s0, s41, s49
	s_add_i32 s92, 0, 0x14000
	v_add_u32_e32 v124, s74, v199
	v_add_u32_e32 v140, s92, v199
	ds_read_b128 v[112:115], v124
	ds_read_b128 v[116:119], v124 offset:1024
	ds_read_b128 v[120:123], v124 offset:2048
	ds_read_b128 v[124:127], v124 offset:3072
	ds_read_b128 v[128:131], v140
	ds_read_b128 v[132:135], v140 offset:1024
	ds_read_b128 v[136:139], v140 offset:2048
	ds_read_b128 v[140:143], v140 offset:3072
	s_add_i32 m0, s63, 0xc000
	ds_read_b128 v[172:175], v207
	ds_read_b128 v[178:181], v207 offset:1024
	ds_read_b128 v[186:189], v207 offset:2048
	ds_read_b128 v[190:193], v207 offset:3072
	ds_read_b128 v[194:197], v207 offset:4096
	ds_read_b128 v[200:203], v207 offset:5120
	ds_read_b128 v[208:211], v207 offset:6144
	ds_read_b128 v[212:215], v207 offset:7168
	global_load_lds_dwordx4 v168, s[44:45]
	s_add_i32 m0, s63, 0xe000
	s_nop 0
	global_load_lds_dwordx4 v170, s[44:45]
	s_waitcnt vmcnt(8)
	s_waitcnt lgkmcnt(0)
	s_barrier
	s_waitcnt lgkmcnt(0)
	v_mfma_f32_16x16x32_bf16 v[156:159], v[112:115], v[172:175], v[156:159]
	v_mfma_f32_16x16x32_bf16 v[152:155], v[120:123], v[172:175], v[152:155]
	v_mfma_f32_16x16x32_bf16 v[108:111], v[112:115], v[186:189], v[108:111]
	v_mfma_f32_16x16x32_bf16 v[100:103], v[120:123], v[186:189], v[100:103]
	v_mfma_f32_16x16x32_bf16 v[92:95], v[112:115], v[194:197], v[92:95]
	v_mfma_f32_16x16x32_bf16 v[84:87], v[120:123], v[194:197], v[84:87]
	v_mfma_f32_16x16x32_bf16 v[76:79], v[112:115], v[208:211], v[76:79]
	v_mfma_f32_16x16x32_bf16 v[68:71], v[120:123], v[208:211], v[68:71]
	v_mfma_f32_16x16x32_bf16 v[156:159], v[116:119], v[178:181], v[156:159]
	v_mfma_f32_16x16x32_bf16 v[152:155], v[124:127], v[178:181], v[152:155]
	v_mfma_f32_16x16x32_bf16 v[108:111], v[116:119], v[190:193], v[108:111]
	v_mfma_f32_16x16x32_bf16 v[100:103], v[124:127], v[190:193], v[100:103]
	v_mfma_f32_16x16x32_bf16 v[92:95], v[116:119], v[200:203], v[92:95]
	v_mfma_f32_16x16x32_bf16 v[84:87], v[124:127], v[200:203], v[84:87]
	v_mfma_f32_16x16x32_bf16 v[76:79], v[116:119], v[212:215], v[76:79]
	v_mfma_f32_16x16x32_bf16 v[68:71], v[124:127], v[212:215], v[68:71]
	v_mfma_f32_16x16x32_bf16 v[148:151], v[128:131], v[172:175], v[148:151]
	v_mfma_f32_16x16x32_bf16 v[144:147], v[136:139], v[172:175], v[144:147]
	v_mfma_f32_16x16x32_bf16 v[104:107], v[128:131], v[186:189], v[104:107]
	v_mfma_f32_16x16x32_bf16 v[96:99], v[136:139], v[186:189], v[96:99]
	v_mfma_f32_16x16x32_bf16 v[88:91], v[128:131], v[194:197], v[88:91]
	v_mfma_f32_16x16x32_bf16 v[80:83], v[136:139], v[194:197], v[80:83]
	v_mfma_f32_16x16x32_bf16 v[72:75], v[128:131], v[208:211], v[72:75]
	v_mfma_f32_16x16x32_bf16 v[64:67], v[136:139], v[208:211], v[64:67]
	v_mfma_f32_16x16x32_bf16 v[148:151], v[132:135], v[178:181], v[148:151]
	v_mfma_f32_16x16x32_bf16 v[144:147], v[140:143], v[178:181], v[144:147]
	v_mfma_f32_16x16x32_bf16 v[104:107], v[132:135], v[190:193], v[104:107]
	v_mfma_f32_16x16x32_bf16 v[96:99], v[140:143], v[190:193], v[96:99]
	v_mfma_f32_16x16x32_bf16 v[88:91], v[132:135], v[200:203], v[88:91]
	v_mfma_f32_16x16x32_bf16 v[80:83], v[140:143], v[200:203], v[80:83]
	v_mfma_f32_16x16x32_bf16 v[72:75], v[132:135], v[212:215], v[72:75]
	v_mfma_f32_16x16x32_bf16 v[64:67], v[140:143], v[212:215], v[64:67]
	s_barrier
	s_add_i32 s74, s74, s62
	v_lshl_add_u64 v[182:183], s[0:1], 0, v[164:165]
	s_mov_b32 m0, s74
	ds_read_b128 v[172:175], v207 offset:16384
	ds_read_b128 v[178:181], v207 offset:17408
	ds_read_b128 v[186:189], v207 offset:18432
	ds_read_b128 v[190:193], v207 offset:19456
	ds_read_b128 v[194:197], v207 offset:20480
	ds_read_b128 v[200:203], v207 offset:21504
	ds_read_b128 v[208:211], v207 offset:22528
	ds_read_b128 v[212:215], v207 offset:23552
	global_load_lds_dwordx4 v164, s[0:1]
	s_add_i32 m0, s74, 0x2000
	s_add_u32 s74, s0, 0x40000
	v_lshl_add_u64 v[204:205], s[0:1], 0, v[160:161]
	s_addc_u32 s75, s1, 0
	s_add_i32 s92, s92, s62
	global_load_lds_dwordx4 v160, s[0:1]
	s_mov_b32 m0, s92
	v_lshl_add_u64 v[218:219], s[4:5], 0, v[162:163]
	global_load_lds_dwordx4 v164, s[74:75]
	s_add_i32 m0, s92, 0x2000
	s_nop 0
	global_load_lds_dwordx4 v160, s[74:75]
	v_lshl_add_u64 v[216:217], s[4:5], 0, v[166:167]
	s_mov_b32 m0, s63
	s_nop 0
	global_load_lds_dwordx4 v166, s[4:5]
	s_mov_b32 m0, s64
	s_nop 0
	global_load_lds_dwordx4 v162, s[4:5]
	s_waitcnt vmcnt(8)
	s_waitcnt lgkmcnt(0)
	s_barrier
	s_waitcnt lgkmcnt(0)
	v_mfma_f32_16x16x32_bf16 v[60:63], v[112:115], v[172:175], v[60:63]
	v_mfma_f32_16x16x32_bf16 v[56:59], v[120:123], v[172:175], v[56:59]
	v_mfma_f32_16x16x32_bf16 v[44:47], v[112:115], v[186:189], v[44:47]
	v_mfma_f32_16x16x32_bf16 v[36:39], v[120:123], v[186:189], v[36:39]
	v_mfma_f32_16x16x32_bf16 v[28:31], v[112:115], v[194:197], v[28:31]
	v_mfma_f32_16x16x32_bf16 v[20:23], v[120:123], v[194:197], v[20:23]
	v_mfma_f32_16x16x32_bf16 v[12:15], v[112:115], v[208:211], v[12:15]
	v_mfma_f32_16x16x32_bf16 v[4:7], v[120:123], v[208:211], v[4:7]
	v_mfma_f32_16x16x32_bf16 v[60:63], v[116:119], v[178:181], v[60:63]
	v_mfma_f32_16x16x32_bf16 v[56:59], v[124:127], v[178:181], v[56:59]
	v_mfma_f32_16x16x32_bf16 v[44:47], v[116:119], v[190:193], v[44:47]
	v_mfma_f32_16x16x32_bf16 v[36:39], v[124:127], v[190:193], v[36:39]
	v_mfma_f32_16x16x32_bf16 v[28:31], v[116:119], v[200:203], v[28:31]
	v_mfma_f32_16x16x32_bf16 v[20:23], v[124:127], v[200:203], v[20:23]
	v_mfma_f32_16x16x32_bf16 v[12:15], v[116:119], v[212:215], v[12:15]
	v_mfma_f32_16x16x32_bf16 v[4:7], v[124:127], v[212:215], v[4:7]
	v_mfma_f32_16x16x32_bf16 v[52:55], v[128:131], v[172:175], v[52:55]
	v_mfma_f32_16x16x32_bf16 v[48:51], v[136:139], v[172:175], v[48:51]
	v_mfma_f32_16x16x32_bf16 v[40:43], v[128:131], v[186:189], v[40:43]
	v_mfma_f32_16x16x32_bf16 v[32:35], v[136:139], v[186:189], v[32:35]
	v_mfma_f32_16x16x32_bf16 v[24:27], v[128:131], v[194:197], v[24:27]
	v_mfma_f32_16x16x32_bf16 v[16:19], v[136:139], v[194:197], v[16:19]
	v_mfma_f32_16x16x32_bf16 v[8:11], v[128:131], v[208:211], v[8:11]
	v_mfma_f32_16x16x32_bf16 v[0:3], v[136:139], v[208:211], v[0:3]
	v_mfma_f32_16x16x32_bf16 v[52:55], v[132:135], v[178:181], v[52:55]
	v_mfma_f32_16x16x32_bf16 v[48:51], v[140:143], v[178:181], v[48:51]
	v_mfma_f32_16x16x32_bf16 v[40:43], v[132:135], v[190:193], v[40:43]
	v_mfma_f32_16x16x32_bf16 v[32:35], v[140:143], v[190:193], v[32:35]
	v_mfma_f32_16x16x32_bf16 v[24:27], v[132:135], v[200:203], v[24:27]
	v_mfma_f32_16x16x32_bf16 v[16:19], v[140:143], v[200:203], v[16:19]
	v_mfma_f32_16x16x32_bf16 v[8:11], v[132:135], v[212:215], v[8:11]
	v_mfma_f32_16x16x32_bf16 v[0:3], v[140:143], v[212:215], v[0:3]
	s_barrier
	s_add_i32 s74, 0, 0x18000
	s_add_i32 s75, 0, 0x1c000
	v_add_u32_e32 v124, s74, v199
	v_add_u32_e32 v140, s75, v199
	ds_read_b128 v[112:115], v124
	ds_read_b128 v[116:119], v124 offset:1024
	ds_read_b128 v[120:123], v124 offset:2048
	ds_read_b128 v[124:127], v124 offset:3072
	ds_read_b128 v[128:131], v140
	ds_read_b128 v[132:135], v140 offset:1024
	ds_read_b128 v[136:139], v140 offset:2048
	ds_read_b128 v[140:143], v140 offset:3072
	s_add_u32 s4, s4, 0x40000
	s_addc_u32 s5, s5, 0
	s_mov_b32 m0, s65
	ds_read_b128 v[172:175], v207 offset:32768
	ds_read_b128 v[178:181], v207 offset:33792
	ds_read_b128 v[186:189], v207 offset:34816
	ds_read_b128 v[190:193], v207 offset:35840
	ds_read_b128 v[194:197], v207 offset:36864
	ds_read_b128 v[200:203], v207 offset:37888
	ds_read_b128 v[208:211], v207 offset:38912
	ds_read_b128 v[212:215], v207 offset:39936
	global_load_lds_dwordx4 v166, s[4:5]
	s_mov_b32 m0, s66
	s_nop 0
	global_load_lds_dwordx4 v162, s[4:5]
	s_waitcnt vmcnt(8)
	s_waitcnt lgkmcnt(0)
	s_barrier
	s_waitcnt lgkmcnt(0)
	v_mfma_f32_16x16x32_bf16 v[156:159], v[112:115], v[172:175], v[156:159]
	v_mfma_f32_16x16x32_bf16 v[152:155], v[120:123], v[172:175], v[152:155]
	v_mfma_f32_16x16x32_bf16 v[108:111], v[112:115], v[186:189], v[108:111]
	v_mfma_f32_16x16x32_bf16 v[100:103], v[120:123], v[186:189], v[100:103]
	v_mfma_f32_16x16x32_bf16 v[92:95], v[112:115], v[194:197], v[92:95]
	v_mfma_f32_16x16x32_bf16 v[84:87], v[120:123], v[194:197], v[84:87]
	v_mfma_f32_16x16x32_bf16 v[76:79], v[112:115], v[208:211], v[76:79]
	v_mfma_f32_16x16x32_bf16 v[68:71], v[120:123], v[208:211], v[68:71]
	v_mfma_f32_16x16x32_bf16 v[156:159], v[116:119], v[178:181], v[156:159]
	v_mfma_f32_16x16x32_bf16 v[152:155], v[124:127], v[178:181], v[152:155]
	v_mfma_f32_16x16x32_bf16 v[108:111], v[116:119], v[190:193], v[108:111]
	v_mfma_f32_16x16x32_bf16 v[100:103], v[124:127], v[190:193], v[100:103]
	v_mfma_f32_16x16x32_bf16 v[92:95], v[116:119], v[200:203], v[92:95]
	v_mfma_f32_16x16x32_bf16 v[84:87], v[124:127], v[200:203], v[84:87]
	v_mfma_f32_16x16x32_bf16 v[76:79], v[116:119], v[212:215], v[76:79]
	v_mfma_f32_16x16x32_bf16 v[68:71], v[124:127], v[212:215], v[68:71]
	v_mfma_f32_16x16x32_bf16 v[148:151], v[128:131], v[172:175], v[148:151]
	v_mfma_f32_16x16x32_bf16 v[144:147], v[136:139], v[172:175], v[144:147]
	v_mfma_f32_16x16x32_bf16 v[104:107], v[128:131], v[186:189], v[104:107]
	v_mfma_f32_16x16x32_bf16 v[96:99], v[136:139], v[186:189], v[96:99]
	v_mfma_f32_16x16x32_bf16 v[88:91], v[128:131], v[194:197], v[88:91]
	v_mfma_f32_16x16x32_bf16 v[80:83], v[136:139], v[194:197], v[80:83]
	v_mfma_f32_16x16x32_bf16 v[72:75], v[128:131], v[208:211], v[72:75]
	v_mfma_f32_16x16x32_bf16 v[64:67], v[136:139], v[208:211], v[64:67]
	v_mfma_f32_16x16x32_bf16 v[148:151], v[132:135], v[178:181], v[148:151]
	v_mfma_f32_16x16x32_bf16 v[144:147], v[140:143], v[178:181], v[144:147]
	v_mfma_f32_16x16x32_bf16 v[104:107], v[132:135], v[190:193], v[104:107]
	v_mfma_f32_16x16x32_bf16 v[96:99], v[140:143], v[190:193], v[96:99]
	v_mfma_f32_16x16x32_bf16 v[88:91], v[132:135], v[200:203], v[88:91]
	v_mfma_f32_16x16x32_bf16 v[80:83], v[140:143], v[200:203], v[80:83]
	v_mfma_f32_16x16x32_bf16 v[72:75], v[132:135], v[212:215], v[72:75]
	v_mfma_f32_16x16x32_bf16 v[64:67], v[140:143], v[212:215], v[64:67]
	s_barrier
	s_add_i32 s4, s74, s62
	v_lshl_add_u64 v[182:183], v[182:183], 0, s[82:83]
	s_mov_b32 m0, s4
	ds_read_b128 v[172:175], v207 offset:49152
	ds_read_b128 v[178:181], v207 offset:50176
	ds_read_b128 v[186:189], v207 offset:51200
	ds_read_b128 v[190:193], v207 offset:52224
	ds_read_b128 v[194:197], v207 offset:53248
	ds_read_b128 v[200:203], v207 offset:54272
	ds_read_b128 v[208:211], v207 offset:55296
	ds_read_b128 v[212:215], v207 offset:56320
	global_load_lds_dwordx4 v[182:183], off
	s_add_i32 m0, s4, 0x2000
	s_add_u32 s0, s0, 0x40080
	v_lshl_add_u64 v[182:183], v[204:205], 0, s[82:83]
	s_addc_u32 s1, s1, 0
	s_add_i32 s4, s75, s62
	global_load_lds_dwordx4 v[182:183], off
	s_mov_b32 m0, s4
	s_nop 0
	global_load_lds_dwordx4 v164, s[0:1]
	s_add_i32 m0, s4, 0x2000
	s_nop 0
	global_load_lds_dwordx4 v160, s[0:1]
	v_lshl_add_u64 v[182:183], v[216:217], 0, s[82:83]
	s_mov_b32 m0, s69
	s_nop 0
	global_load_lds_dwordx4 v[182:183], off
	v_lshl_add_u64 v[182:183], v[218:219], 0, s[82:83]
	s_mov_b32 m0, s70
	s_nop 0
	global_load_lds_dwordx4 v[182:183], off
	s_waitcnt vmcnt(8)
	s_waitcnt lgkmcnt(0)
	s_barrier
	s_waitcnt lgkmcnt(0)
	v_mfma_f32_16x16x32_bf16 v[60:63], v[112:115], v[172:175], v[60:63]
	v_mfma_f32_16x16x32_bf16 v[56:59], v[120:123], v[172:175], v[56:59]
	v_mfma_f32_16x16x32_bf16 v[44:47], v[112:115], v[186:189], v[44:47]
	v_mfma_f32_16x16x32_bf16 v[36:39], v[120:123], v[186:189], v[36:39]
	v_mfma_f32_16x16x32_bf16 v[28:31], v[112:115], v[194:197], v[28:31]
	v_mfma_f32_16x16x32_bf16 v[20:23], v[120:123], v[194:197], v[20:23]
	v_mfma_f32_16x16x32_bf16 v[12:15], v[112:115], v[208:211], v[12:15]
	v_mfma_f32_16x16x32_bf16 v[4:7], v[120:123], v[208:211], v[4:7]
	v_mfma_f32_16x16x32_bf16 v[60:63], v[116:119], v[178:181], v[60:63]
	v_mfma_f32_16x16x32_bf16 v[56:59], v[124:127], v[178:181], v[56:59]
	v_mfma_f32_16x16x32_bf16 v[44:47], v[116:119], v[190:193], v[44:47]
	v_mfma_f32_16x16x32_bf16 v[36:39], v[124:127], v[190:193], v[36:39]
	v_mfma_f32_16x16x32_bf16 v[28:31], v[116:119], v[200:203], v[28:31]
	v_mfma_f32_16x16x32_bf16 v[20:23], v[124:127], v[200:203], v[20:23]
	v_mfma_f32_16x16x32_bf16 v[12:15], v[116:119], v[212:215], v[12:15]
	v_mfma_f32_16x16x32_bf16 v[4:7], v[124:127], v[212:215], v[4:7]
	v_mfma_f32_16x16x32_bf16 v[52:55], v[128:131], v[172:175], v[52:55]
	v_mfma_f32_16x16x32_bf16 v[48:51], v[136:139], v[172:175], v[48:51]
	v_mfma_f32_16x16x32_bf16 v[40:43], v[128:131], v[186:189], v[40:43]
	v_mfma_f32_16x16x32_bf16 v[32:35], v[136:139], v[186:189], v[32:35]
	v_mfma_f32_16x16x32_bf16 v[24:27], v[128:131], v[194:197], v[24:27]
	v_mfma_f32_16x16x32_bf16 v[16:19], v[136:139], v[194:197], v[16:19]
	v_mfma_f32_16x16x32_bf16 v[8:11], v[128:131], v[208:211], v[8:11]
	v_mfma_f32_16x16x32_bf16 v[0:3], v[136:139], v[208:211], v[0:3]
	v_mfma_f32_16x16x32_bf16 v[52:55], v[132:135], v[178:181], v[52:55]
	v_mfma_f32_16x16x32_bf16 v[48:51], v[140:143], v[178:181], v[48:51]
	v_mfma_f32_16x16x32_bf16 v[40:43], v[132:135], v[190:193], v[40:43]
	v_mfma_f32_16x16x32_bf16 v[32:35], v[140:143], v[190:193], v[32:35]
	v_mfma_f32_16x16x32_bf16 v[24:27], v[132:135], v[200:203], v[24:27]
	v_mfma_f32_16x16x32_bf16 v[16:19], v[140:143], v[200:203], v[16:19]
	v_mfma_f32_16x16x32_bf16 v[8:11], v[132:135], v[212:215], v[8:11]
	v_mfma_f32_16x16x32_bf16 v[0:3], v[140:143], v[212:215], v[0:3]
	s_barrier
	s_add_i32 s73, s73, 2
	s_add_u32 s44, s44, 0x100
	s_addc_u32 s45, s45, 0
	s_add_u32 s49, s49, 0x100
	s_addc_u32 s72, s72, 0
	s_cmp_gt_u32 s73, 13
	s_cbranch_scc0 .LBB0_748
	s_and_b64 vcc, exec, s[90:91]
	s_cbranch_vccz .LBB0_751
	s_barrier

.LBB0_930:
	s_add_u32 s0, s54, 0x100
	s_addc_u32 s1, s55, 0
	s_add_i32 s72, 0, 0x10000
	s_cmp_eq_u32 s71, 40
	s_cselect_b32 s43, s51, s1
	s_cselect_b32 s42, s50, s0
	s_cselect_b32 s5, s53, s70
	s_cselect_b32 s4, s52, s69
	s_add_i32 s73, 0, 0x14000
	v_add_u32_e32 v140, s72, v164
	v_add_u32_e32 v162, s73, v164
	ds_read_b128 v[128:131], v140
	ds_read_b128 v[132:135], v140 offset:1024
	ds_read_b128 v[136:139], v140 offset:2048
	ds_read_b128 v[140:143], v140 offset:3072
	ds_read_b128 v[154:157], v162
	ds_read_b128 v[158:161], v162 offset:1024
	ds_read_b128 v[166:169], v162 offset:2048
	ds_read_b128 v[170:173], v162 offset:3072
	s_add_i32 m0, s20, 0xc000
	ds_read_b128 v[178:181], v165
	ds_read_b128 v[186:189], v165 offset:1024
	ds_read_b128 v[190:193], v165 offset:2048
	ds_read_b128 v[194:197], v165 offset:3072
	ds_read_b128 v[198:201], v165 offset:4096
	ds_read_b128 v[202:205], v165 offset:5120
	ds_read_b128 v[206:209], v165 offset:6144
	ds_read_b128 v[210:213], v165 offset:7168
	global_load_lds_dwordx4 v150, s[54:55]
	s_add_i32 m0, s20, 0xe000
	s_nop 0
	global_load_lds_dwordx4 v152, s[54:55]
	s_waitcnt vmcnt(8)
	s_waitcnt lgkmcnt(0)
	s_barrier
	s_waitcnt lgkmcnt(0)
	v_mfma_f32_16x16x32_bf16 v[124:127], v[128:131], v[178:181], v[124:127]
	v_mfma_f32_16x16x32_bf16 v[120:123], v[136:139], v[178:181], v[120:123]
	v_mfma_f32_16x16x32_bf16 v[108:111], v[128:131], v[190:193], v[108:111]
	v_mfma_f32_16x16x32_bf16 v[104:107], v[136:139], v[190:193], v[104:107]
	v_mfma_f32_16x16x32_bf16 v[92:95], v[128:131], v[198:201], v[92:95]
	v_mfma_f32_16x16x32_bf16 v[88:91], v[136:139], v[198:201], v[88:91]
	v_mfma_f32_16x16x32_bf16 v[76:79], v[128:131], v[206:209], v[76:79]
	v_mfma_f32_16x16x32_bf16 v[72:75], v[136:139], v[206:209], v[72:75]
	v_mfma_f32_16x16x32_bf16 v[124:127], v[132:135], v[186:189], v[124:127]
	v_mfma_f32_16x16x32_bf16 v[120:123], v[140:143], v[186:189], v[120:123]
	v_mfma_f32_16x16x32_bf16 v[108:111], v[132:135], v[194:197], v[108:111]
	v_mfma_f32_16x16x32_bf16 v[104:107], v[140:143], v[194:197], v[104:107]
	v_mfma_f32_16x16x32_bf16 v[92:95], v[132:135], v[202:205], v[92:95]
	v_mfma_f32_16x16x32_bf16 v[88:91], v[140:143], v[202:205], v[88:91]
	v_mfma_f32_16x16x32_bf16 v[76:79], v[132:135], v[210:213], v[76:79]
	v_mfma_f32_16x16x32_bf16 v[72:75], v[140:143], v[210:213], v[72:75]
	v_mfma_f32_16x16x32_bf16 v[116:119], v[154:157], v[178:181], v[116:119]
	v_mfma_f32_16x16x32_bf16 v[112:115], v[166:169], v[178:181], v[112:115]
	v_mfma_f32_16x16x32_bf16 v[100:103], v[154:157], v[190:193], v[100:103]
	v_mfma_f32_16x16x32_bf16 v[96:99], v[166:169], v[190:193], v[96:99]
	v_mfma_f32_16x16x32_bf16 v[84:87], v[154:157], v[198:201], v[84:87]
	v_mfma_f32_16x16x32_bf16 v[80:83], v[166:169], v[198:201], v[80:83]
	v_mfma_f32_16x16x32_bf16 v[68:71], v[154:157], v[206:209], v[68:71]
	v_mfma_f32_16x16x32_bf16 v[64:67], v[166:169], v[206:209], v[64:67]
	v_mfma_f32_16x16x32_bf16 v[116:119], v[158:161], v[186:189], v[116:119]
	v_mfma_f32_16x16x32_bf16 v[112:115], v[170:173], v[186:189], v[112:115]
	v_mfma_f32_16x16x32_bf16 v[100:103], v[158:161], v[194:197], v[100:103]
	v_mfma_f32_16x16x32_bf16 v[96:99], v[170:173], v[194:197], v[96:99]
	v_mfma_f32_16x16x32_bf16 v[84:87], v[158:161], v[202:205], v[84:87]
	v_mfma_f32_16x16x32_bf16 v[80:83], v[170:173], v[202:205], v[80:83]
	v_mfma_f32_16x16x32_bf16 v[68:71], v[158:161], v[210:213], v[68:71]
	v_mfma_f32_16x16x32_bf16 v[64:67], v[170:173], v[210:213], v[64:67]
	s_barrier
	s_add_i32 s54, s72, s12
	v_lshl_add_u64 v[162:163], s[4:5], 0, v[176:177]
	s_mov_b32 m0, s54
	ds_read_b128 v[178:181], v165 offset:16384
	ds_read_b128 v[186:189], v165 offset:17408
	ds_read_b128 v[190:193], v165 offset:18432
	ds_read_b128 v[194:197], v165 offset:19456
	ds_read_b128 v[198:201], v165 offset:20480
	ds_read_b128 v[202:205], v165 offset:21504
	ds_read_b128 v[206:209], v165 offset:22528
	ds_read_b128 v[210:213], v165 offset:23552
	global_load_lds_dwordx4 v176, s[4:5]
	s_add_i32 m0, s54, 0x2000
	s_add_u32 s54, s4, 0xb0000
	v_lshl_add_u64 v[174:175], s[4:5], 0, v[144:145]
	s_addc_u32 s55, s5, 0
	s_add_i32 s72, s73, s12
	global_load_lds_dwordx4 v144, s[4:5]
	s_mov_b32 m0, s72
	v_lshl_add_u64 v[214:215], s[42:43], 0, v[146:147]
	global_load_lds_dwordx4 v176, s[54:55]
	s_add_i32 m0, s72, 0x2000
	s_nop 0
	global_load_lds_dwordx4 v144, s[54:55]
	v_lshl_add_u64 v[182:183], s[42:43], 0, v[148:149]
	s_mov_b32 m0, s20
	s_nop 0
	global_load_lds_dwordx4 v148, s[42:43]
	s_mov_b32 m0, s27
	s_nop 0
	global_load_lds_dwordx4 v146, s[42:43]
	s_waitcnt vmcnt(8)
	s_waitcnt lgkmcnt(0)
	s_barrier
	s_waitcnt lgkmcnt(0)
	v_mfma_f32_16x16x32_bf16 v[60:63], v[128:131], v[178:181], v[60:63]
	v_mfma_f32_16x16x32_bf16 v[56:59], v[136:139], v[178:181], v[56:59]
	v_mfma_f32_16x16x32_bf16 v[44:47], v[128:131], v[190:193], v[44:47]
	v_mfma_f32_16x16x32_bf16 v[40:43], v[136:139], v[190:193], v[40:43]
	v_mfma_f32_16x16x32_bf16 v[28:31], v[128:131], v[198:201], v[28:31]
	v_mfma_f32_16x16x32_bf16 v[24:27], v[136:139], v[198:201], v[24:27]
	v_mfma_f32_16x16x32_bf16 v[12:15], v[128:131], v[206:209], v[12:15]
	v_mfma_f32_16x16x32_bf16 v[8:11], v[136:139], v[206:209], v[8:11]
	v_mfma_f32_16x16x32_bf16 v[60:63], v[132:135], v[186:189], v[60:63]
	v_mfma_f32_16x16x32_bf16 v[56:59], v[140:143], v[186:189], v[56:59]
	v_mfma_f32_16x16x32_bf16 v[44:47], v[132:135], v[194:197], v[44:47]
	v_mfma_f32_16x16x32_bf16 v[40:43], v[140:143], v[194:197], v[40:43]
	v_mfma_f32_16x16x32_bf16 v[28:31], v[132:135], v[202:205], v[28:31]
	v_mfma_f32_16x16x32_bf16 v[24:27], v[140:143], v[202:205], v[24:27]
	v_mfma_f32_16x16x32_bf16 v[12:15], v[132:135], v[210:213], v[12:15]
	v_mfma_f32_16x16x32_bf16 v[8:11], v[140:143], v[210:213], v[8:11]
	v_mfma_f32_16x16x32_bf16 v[52:55], v[154:157], v[178:181], v[52:55]
	v_mfma_f32_16x16x32_bf16 v[48:51], v[166:169], v[178:181], v[48:51]
	v_mfma_f32_16x16x32_bf16 v[36:39], v[154:157], v[190:193], v[36:39]
	v_mfma_f32_16x16x32_bf16 v[32:35], v[166:169], v[190:193], v[32:35]
	v_mfma_f32_16x16x32_bf16 v[20:23], v[154:157], v[198:201], v[20:23]
	v_mfma_f32_16x16x32_bf16 v[16:19], v[166:169], v[198:201], v[16:19]
	v_mfma_f32_16x16x32_bf16 v[4:7], v[154:157], v[206:209], v[4:7]
	v_mfma_f32_16x16x32_bf16 v[0:3], v[166:169], v[206:209], v[0:3]
	v_mfma_f32_16x16x32_bf16 v[52:55], v[158:161], v[186:189], v[52:55]
	v_mfma_f32_16x16x32_bf16 v[48:51], v[170:173], v[186:189], v[48:51]
	v_mfma_f32_16x16x32_bf16 v[36:39], v[158:161], v[194:197], v[36:39]
	v_mfma_f32_16x16x32_bf16 v[32:35], v[170:173], v[194:197], v[32:35]
	v_mfma_f32_16x16x32_bf16 v[20:23], v[158:161], v[202:205], v[20:23]
	v_mfma_f32_16x16x32_bf16 v[16:19], v[170:173], v[202:205], v[16:19]
	v_mfma_f32_16x16x32_bf16 v[4:7], v[158:161], v[210:213], v[4:7]
	v_mfma_f32_16x16x32_bf16 v[0:3], v[170:173], v[210:213], v[0:3]
	s_barrier
	s_add_i32 s54, 0, 0x18000
	s_add_i32 s55, 0, 0x1c000
	v_add_u32_e32 v140, s54, v164
	v_add_u32_e32 v170, s55, v164
	ds_read_b128 v[128:131], v140
	ds_read_b128 v[132:135], v140 offset:1024
	ds_read_b128 v[136:139], v140 offset:2048
	ds_read_b128 v[140:143], v140 offset:3072
	ds_read_b128 v[154:157], v170
	ds_read_b128 v[158:161], v170 offset:1024
	ds_read_b128 v[166:169], v170 offset:2048
	ds_read_b128 v[170:173], v170 offset:3072
	s_add_u32 s42, s42, 0xb0000
	s_addc_u32 s43, s43, 0
	s_mov_b32 m0, s47
	ds_read_b128 v[178:181], v165 offset:32768
	ds_read_b128 v[186:189], v165 offset:33792
	ds_read_b128 v[190:193], v165 offset:34816
	ds_read_b128 v[194:197], v165 offset:35840
	ds_read_b128 v[198:201], v165 offset:36864
	ds_read_b128 v[202:205], v165 offset:37888
	ds_read_b128 v[206:209], v165 offset:38912
	ds_read_b128 v[210:213], v165 offset:39936
	global_load_lds_dwordx4 v148, s[42:43]
	s_mov_b32 m0, s56
	s_nop 0
	global_load_lds_dwordx4 v146, s[42:43]
	s_waitcnt vmcnt(8)
	s_waitcnt lgkmcnt(0)
	s_barrier
	s_waitcnt lgkmcnt(0)
	v_mfma_f32_16x16x32_bf16 v[124:127], v[128:131], v[178:181], v[124:127]
	v_mfma_f32_16x16x32_bf16 v[120:123], v[136:139], v[178:181], v[120:123]
	v_mfma_f32_16x16x32_bf16 v[108:111], v[128:131], v[190:193], v[108:111]
	v_mfma_f32_16x16x32_bf16 v[104:107], v[136:139], v[190:193], v[104:107]
	v_mfma_f32_16x16x32_bf16 v[92:95], v[128:131], v[198:201], v[92:95]
	v_mfma_f32_16x16x32_bf16 v[88:91], v[136:139], v[198:201], v[88:91]
	v_mfma_f32_16x16x32_bf16 v[76:79], v[128:131], v[206:209], v[76:79]
	v_mfma_f32_16x16x32_bf16 v[72:75], v[136:139], v[206:209], v[72:75]
	v_mfma_f32_16x16x32_bf16 v[124:127], v[132:135], v[186:189], v[124:127]
	v_mfma_f32_16x16x32_bf16 v[120:123], v[140:143], v[186:189], v[120:123]
	v_mfma_f32_16x16x32_bf16 v[108:111], v[132:135], v[194:197], v[108:111]
	v_mfma_f32_16x16x32_bf16 v[104:107], v[140:143], v[194:197], v[104:107]
	v_mfma_f32_16x16x32_bf16 v[92:95], v[132:135], v[202:205], v[92:95]
	v_mfma_f32_16x16x32_bf16 v[88:91], v[140:143], v[202:205], v[88:91]
	v_mfma_f32_16x16x32_bf16 v[76:79], v[132:135], v[210:213], v[76:79]
	v_mfma_f32_16x16x32_bf16 v[72:75], v[140:143], v[210:213], v[72:75]
	v_mfma_f32_16x16x32_bf16 v[116:119], v[154:157], v[178:181], v[116:119]
	v_mfma_f32_16x16x32_bf16 v[112:115], v[166:169], v[178:181], v[112:115]
	v_mfma_f32_16x16x32_bf16 v[100:103], v[154:157], v[190:193], v[100:103]
	v_mfma_f32_16x16x32_bf16 v[96:99], v[166:169], v[190:193], v[96:99]
	v_mfma_f32_16x16x32_bf16 v[84:87], v[154:157], v[198:201], v[84:87]
	v_mfma_f32_16x16x32_bf16 v[80:83], v[166:169], v[198:201], v[80:83]
	v_mfma_f32_16x16x32_bf16 v[68:71], v[154:157], v[206:209], v[68:71]
	v_mfma_f32_16x16x32_bf16 v[64:67], v[166:169], v[206:209], v[64:67]
	v_mfma_f32_16x16x32_bf16 v[116:119], v[158:161], v[186:189], v[116:119]
	v_mfma_f32_16x16x32_bf16 v[112:115], v[170:173], v[186:189], v[112:115]
	v_mfma_f32_16x16x32_bf16 v[100:103], v[158:161], v[194:197], v[100:103]
	v_mfma_f32_16x16x32_bf16 v[96:99], v[170:173], v[194:197], v[96:99]
	v_mfma_f32_16x16x32_bf16 v[84:87], v[158:161], v[202:205], v[84:87]
	v_mfma_f32_16x16x32_bf16 v[80:83], v[170:173], v[202:205], v[80:83]
	v_mfma_f32_16x16x32_bf16 v[68:71], v[158:161], v[210:213], v[68:71]
	v_mfma_f32_16x16x32_bf16 v[64:67], v[170:173], v[210:213], v[64:67]
	s_barrier
	s_add_i32 s42, s54, s12
	v_lshl_add_u64 v[162:163], v[162:163], 0, s[82:83]
	s_mov_b32 m0, s42
	ds_read_b128 v[178:181], v165 offset:49152
	ds_read_b128 v[186:189], v165 offset:50176
	ds_read_b128 v[190:193], v165 offset:51200
	ds_read_b128 v[194:197], v165 offset:52224
	ds_read_b128 v[198:201], v165 offset:53248
	ds_read_b128 v[202:205], v165 offset:54272
	ds_read_b128 v[206:209], v165 offset:55296
	ds_read_b128 v[210:213], v165 offset:56320
	global_load_lds_dwordx4 v[162:163], off
	s_add_i32 m0, s42, 0x2000
	s_add_u32 s4, s4, 0xb0080
	v_lshl_add_u64 v[162:163], v[174:175], 0, s[82:83]
	s_addc_u32 s5, s5, 0
	s_add_i32 s42, s55, s12
	global_load_lds_dwordx4 v[162:163], off
	s_mov_b32 m0, s42
	s_nop 0
	global_load_lds_dwordx4 v176, s[4:5]
	s_add_i32 m0, s42, 0x2000
	s_nop 0
	global_load_lds_dwordx4 v144, s[4:5]
	v_lshl_add_u64 v[162:163], v[182:183], 0, s[82:83]
	s_mov_b32 m0, s62
	s_nop 0
	global_load_lds_dwordx4 v[162:163], off
	v_lshl_add_u64 v[162:163], v[214:215], 0, s[82:83]
	s_mov_b32 m0, s63
	s_nop 0
	global_load_lds_dwordx4 v[162:163], off
	s_waitcnt vmcnt(8)
	s_waitcnt lgkmcnt(0)
	s_barrier
	s_waitcnt lgkmcnt(0)
	v_mfma_f32_16x16x32_bf16 v[60:63], v[128:131], v[178:181], v[60:63]
	v_mfma_f32_16x16x32_bf16 v[56:59], v[136:139], v[178:181], v[56:59]
	v_mfma_f32_16x16x32_bf16 v[44:47], v[128:131], v[190:193], v[44:47]
	v_mfma_f32_16x16x32_bf16 v[40:43], v[136:139], v[190:193], v[40:43]
	v_mfma_f32_16x16x32_bf16 v[28:31], v[128:131], v[198:201], v[28:31]
	v_mfma_f32_16x16x32_bf16 v[24:27], v[136:139], v[198:201], v[24:27]
	v_mfma_f32_16x16x32_bf16 v[12:15], v[128:131], v[206:209], v[12:15]
	v_mfma_f32_16x16x32_bf16 v[8:11], v[136:139], v[206:209], v[8:11]
	v_mfma_f32_16x16x32_bf16 v[60:63], v[132:135], v[186:189], v[60:63]
	v_mfma_f32_16x16x32_bf16 v[56:59], v[140:143], v[186:189], v[56:59]
	v_mfma_f32_16x16x32_bf16 v[44:47], v[132:135], v[194:197], v[44:47]
	v_mfma_f32_16x16x32_bf16 v[40:43], v[140:143], v[194:197], v[40:43]
	v_mfma_f32_16x16x32_bf16 v[28:31], v[132:135], v[202:205], v[28:31]
	v_mfma_f32_16x16x32_bf16 v[24:27], v[140:143], v[202:205], v[24:27]
	v_mfma_f32_16x16x32_bf16 v[12:15], v[132:135], v[210:213], v[12:15]
	v_mfma_f32_16x16x32_bf16 v[8:11], v[140:143], v[210:213], v[8:11]
	v_mfma_f32_16x16x32_bf16 v[52:55], v[154:157], v[178:181], v[52:55]
	v_mfma_f32_16x16x32_bf16 v[48:51], v[166:169], v[178:181], v[48:51]
	v_mfma_f32_16x16x32_bf16 v[36:39], v[154:157], v[190:193], v[36:39]
	v_mfma_f32_16x16x32_bf16 v[32:35], v[166:169], v[190:193], v[32:35]
	v_mfma_f32_16x16x32_bf16 v[20:23], v[154:157], v[198:201], v[20:23]
	v_mfma_f32_16x16x32_bf16 v[16:19], v[166:169], v[198:201], v[16:19]
	v_mfma_f32_16x16x32_bf16 v[4:7], v[154:157], v[206:209], v[4:7]
	v_mfma_f32_16x16x32_bf16 v[0:3], v[166:169], v[206:209], v[0:3]
	v_mfma_f32_16x16x32_bf16 v[52:55], v[158:161], v[186:189], v[52:55]
	v_mfma_f32_16x16x32_bf16 v[48:51], v[170:173], v[186:189], v[48:51]
	v_mfma_f32_16x16x32_bf16 v[36:39], v[158:161], v[194:197], v[36:39]
	v_mfma_f32_16x16x32_bf16 v[32:35], v[170:173], v[194:197], v[32:35]
	v_mfma_f32_16x16x32_bf16 v[20:23], v[158:161], v[202:205], v[20:23]
	v_mfma_f32_16x16x32_bf16 v[16:19], v[170:173], v[202:205], v[16:19]
	v_mfma_f32_16x16x32_bf16 v[4:7], v[158:161], v[210:213], v[4:7]
	v_mfma_f32_16x16x32_bf16 v[0:3], v[170:173], v[210:213], v[0:3]
	s_barrier
	s_add_i32 s71, s71, 2
	s_add_u32 s69, s69, 0x100
	s_addc_u32 s70, s70, 0
	s_cmp_gt_u32 s71, 41
	s_mov_b64 s[54:55], s[0:1]
	s_cbranch_scc0 .LBB0_930
	s_and_b64 vcc, exec, s[48:49]
	s_cbranch_vccz .LBB0_933
	s_barrier
